# v33spat
# speedup vs baseline: 1.0128x; 1.0069x over previous
; __device__ __forceinline__ float bf2f(u16 b) { return __uint_as_float(((unsigned)b) << 16); }
; __device__ __forceinline__ float silu_f(float g) { return g * __builtin_amdgcn_rcpf(1.f + __builtin_amdgcn_exp2f(-g * LOG2E)); }
; template <int EPI>
; __device__ __forceinline__ void epilogue(const Params& p, int pass, int layer, int pm, int pn,
;                                          f32x4 (&acc)[2][2][4][2], const float* xin, float* xout) {
;     ...
;     int t0 = pm * 256;
;     u16* Y = (u16*)(p.ws + OFF_Y);
;     const float* stat = (const float*)(p.ws + OFF_STAT0);
;     int h = pn >> 1;
;     float gn[2][2];
; #pragma unroll
;     for (int bj = 0; bj < 2; ++bj)
; #pragma unroll
;       for (int n = 0; n < 2; ++n) gn[bj][n] = p.ret_gn[pn * 256 + bj * 128 + wc * 32 + n * 16 + fr];
; #pragma unroll
;     for (int ai = 0; ai < 2; ++ai)
; #pragma unroll
;       for (int m = 0; m < 4; ++m) {
;         int tb = t0 + ai * 128 + wr * 64 + m * 16 + fq * 4;
;         asm volatile("" : "+v"(tb));
;         float4 s01[4], s23[4];
;         u16 yv[4][2][2];
; #pragma unroll
;         for (int j = 0; j < 4; ++j) {
;           const float4* sp = (const float4*)(stat + ((long)(tb + j) * 8 + h) * 8);
;           s01[j] = sp[0]; s23[j] = sp[1];
; #pragma unroll
;           for (int bj = 0; bj < 2; ++bj)
; #pragma unroll
;             for (int n = 0; n < 2; ++n)
;               yv[j][bj][n] = Y[(long)(tb + j) * YS + pn * 256 + bj * 128 + wc * 32 + n * 16 + fr];
;         }
; #pragma unroll
;         for (int j = 0; j < 4; ++j) {
;           float s1 = s01[j].x + s01[j].z + s23[j].x + s23[j].z, s2 = s01[j].y + s01[j].w + s23[j].y + s23[j].w;
;           float mu = s1 * (1.f / 512.f);
;           float var = s2 * (1.f / 512.f) - mu * mu;
;           float rstd = rsqrtf(fmaxf(var, 0.f) + 1e-5f);
; #pragma unroll
;           for (int bj = 0; bj < 2; ++bj)
; #pragma unroll
;             for (int n = 0; n < 2; ++n) {
;               float g = acc[ai][bj][m][n][j];
;               float yn = (bf2f(yv[j][bj][n]) - mu) * rstd * gn[bj][n];
;               Y[(long)(tb + j) * YS + pn * 256 + bj * 128 + wc * 32 + n * 16 + fr] = f2bf(silu_f(g) * yn);
;             }
;         }
.LBB0_54:
	v_mbcnt_lo_u32_b32 v0, -1, 0
	v_mbcnt_hi_u32_b32 v0, -1, v0
	s_lshl_b32 s18, s3, 8
	v_or_b32_e32 v132, s33, v0
	v_lshrrev_b32_e32 v130, 1, v132
	v_and_b32_e32 v133, 15, v0
	v_and_b32_e32 v134, 0x60, v130
	s_lshl_b32 s1, s14, 8
	s_ashr_i32 s14, s3, 1
	v_or3_b32 v130, v133, s18, v134
	v_readlane_b32 s40, v252, 16
	v_lshrrev_b32_e32 v0, 2, v0
	s_ashr_i32 s15, s14, 31
	v_ashrrev_i32_e32 v131, 31, v130
	v_readlane_b32 s54, v252, 30
	v_readlane_b32 s55, v252, 31
	v_and_or_b32 v0, v0, 12, s1
	s_lshl_b64 s[14:15], s[14:15], 5
	v_readlane_b32 s1, v252, 59
	v_lshl_add_u64 v[130:131], v[130:131], 2, s[54:55]
	s_add_u32 s16, s1, s14
	v_readlane_b32 s1, v252, 60
	global_load_dword v151, v[130:131], off
	global_load_dword v150, v[130:131], off offset:64
	global_load_dword v149, v[130:131], off offset:512
	global_load_dword v148, v[130:131], off offset:576
	v_ashrrev_i32_e32 v130, 2, v132
	s_addc_u32 s17, s1, s15
	s_ashr_i32 s19, s18, 31
	v_and_b32_e32 v130, 0xffffffc0, v130
	s_lshl_b64 s[14:15], s[18:19], 1
	v_readlane_b32 s18, v252, 61
	v_add_u32_e32 v152, v0, v130
	v_readlane_b32 s19, v252, 62
	s_add_u32 s14, s18, s14
	s_addc_u32 s15, s19, s15
	v_lshlrev_b32_e32 v0, 1, v134
	v_mov_b32_e32 v134, v152
	v_lshl_add_u64 v[130:131], s[14:15], 0, v[0:1]
	v_lshlrev_b32_e32 v0, 1, v133
	v_lshl_add_u64 v[138:139], v[130:131], 0, v[0:1]
	v_ashrrev_i32_e32 v135, 31, v134
	v_lshlrev_b64 v[130:131], 8, v[134:135]
	v_lshl_add_u64 v[136:137], s[16:17], 0, v[130:131]
	global_load_dwordx4 v[154:157], v[136:137], off offset:16
	global_load_dwordx4 v[158:161], v[136:137], off
	s_mov_b32 s18, 0x3b000000
	v_mad_i64_i32 v[142:143], s[14:15], v134, s24, v[138:139]
	global_load_ushort v162, v[142:143], off
	global_load_ushort v163, v[142:143], off offset:32
	global_load_ushort v164, v[142:143], off offset:256
	global_load_ushort v165, v[142:143], off offset:288
	v_mul_f32_e32 v153, 0xbfb8aa3b, v126
	v_exp_f32_e32 v153, v153
	v_add_u32_e32 v130, 1, v134
	v_ashrrev_i32_e32 v131, 31, v130
	v_lshlrev_b64 v[132:133], 8, v[130:131]
	v_add_f32_e32 v153, 1.0, v153
	v_rcp_f32_e32 v153, v153
	v_lshl_add_u64 v[132:133], s[16:17], 0, v[132:133]
	global_load_dwordx4 v[194:197], v[132:133], off offset:16
	global_load_dwordx4 v[198:201], v[132:133], off
	v_mad_i64_i32 v[144:145], s[14:15], v130, s24, v[138:139]
	global_load_ushort v166, v[144:145], off
	global_load_ushort v167, v[144:145], off offset:32
	global_load_ushort v168, v[144:145], off offset:256
	global_load_ushort v169, v[144:145], off offset:288
	v_mul_f32_e32 v126, v126, v153
	v_mul_f32_e32 v153, 0xbfb8aa3b, v122
	v_exp_f32_e32 v153, v153
	v_add_u32_e32 v140, 2, v134
	v_ashrrev_i32_e32 v141, 31, v140
	v_lshlrev_b64 v[130:131], 8, v[140:141]
	v_add_f32_e32 v153, 1.0, v153
	v_rcp_f32_e32 v153, v153
	v_lshl_add_u64 v[130:131], s[16:17], 0, v[130:131]
	global_load_dwordx4 v[202:205], v[130:131], off offset:16
	global_load_dwordx4 v[206:209], v[130:131], off
	v_mad_i64_i32 v[146:147], s[14:15], v140, s24, v[138:139]
	global_load_ushort v170, v[146:147], off
	global_load_ushort v171, v[146:147], off offset:32
	global_load_ushort v172, v[146:147], off offset:256
	global_load_ushort v173, v[146:147], off offset:288
	v_mul_f32_e32 v122, v122, v153
	v_mul_f32_e32 v153, 0xbfb8aa3b, v118
	v_exp_f32_e32 v153, v153
	v_add_u32_e32 v140, 3, v134
	v_ashrrev_i32_e32 v141, 31, v140
	v_lshlrev_b64 v[134:135], 8, v[140:141]
	v_add_f32_e32 v153, 1.0, v153
	v_rcp_f32_e32 v153, v153
	v_lshl_add_u64 v[134:135], s[16:17], 0, v[134:135]
	global_load_dwordx4 v[210:213], v[134:135], off offset:16
	global_load_dwordx4 v[214:217], v[134:135], off
	v_mad_i64_i32 v[140:141], s[14:15], v140, s24, v[138:139]
	global_load_ushort v174, v[140:141], off
	global_load_ushort v175, v[140:141], off offset:32
	global_load_ushort v176, v[140:141], off offset:256
	global_load_ushort v177, v[140:141], off offset:288
	v_mul_f32_e32 v118, v118, v153
	s_mov_b32 s3, s0
	v_readlane_b32 s41, v252, 17
	v_readlane_b32 s42, v252, 18
	v_readlane_b32 s43, v252, 19
	v_readlane_b32 s44, v252, 20
	v_readlane_b32 s45, v252, 21
	v_readlane_b32 s46, v252, 22
	v_readlane_b32 s47, v252, 23
	v_readlane_b32 s48, v252, 24
	v_readlane_b32 s49, v252, 25
	v_readlane_b32 s50, v252, 26
	v_readlane_b32 s51, v252, 27
	v_readlane_b32 s52, v252, 28
	v_readlane_b32 s53, v252, 29
	s_waitcnt vmcnt(0)
; __device__ __forceinline__ float bf2f(u16 b) { return __uint_as_float(((unsigned)b) << 16); }
; __device__ __forceinline__ float silu_f(float g) { return g * __builtin_amdgcn_rcpf(1.f + __builtin_amdgcn_exp2f(-g * LOG2E)); }
; template <int EPI>
; __device__ __forceinline__ void epilogue(const Params& p, int pass, int layer, int pm, int pn,
;                                          f32x4 (&acc)[2][2][4][2], const float* xin, float* xout) {
;     ...
;       for (int m = 0; m < 4; ++m) {
;         int tb = t0 + ai * 128 + wr * 64 + m * 16 + fq * 4;
;         asm volatile("" : "+v"(tb));
;         float4 s01[4], s23[4];
;         u16 yv[4][2][2];
; #pragma unroll
;         for (int j = 0; j < 4; ++j) {
;           const float4* sp = (const float4*)(stat + ((long)(tb + j) * 8 + h) * 8);
;           s01[j] = sp[0]; s23[j] = sp[1];
; #pragma unroll
;           for (int bj = 0; bj < 2; ++bj)
; #pragma unroll
;             for (int n = 0; n < 2; ++n)
;               yv[j][bj][n] = Y[(long)(tb + j) * YS + pn * 256 + bj * 128 + wc * 32 + n * 16 + fr];
;         }
; #pragma unroll
;         for (int j = 0; j < 4; ++j) {
;           float s1 = s01[j].x + s01[j].z + s23[j].x + s23[j].z, s2 = s01[j].y + s01[j].w + s23[j].y + s23[j].w;
;           float mu = s1 * (1.f / 512.f);
;           float var = s2 * (1.f / 512.f) - mu * mu;
;           float rstd = rsqrtf(fmaxf(var, 0.f) + 1e-5f);
; #pragma unroll
;           for (int bj = 0; bj < 2; ++bj)
; #pragma unroll
;             for (int n = 0; n < 2; ++n) {
;               float g = acc[ai][bj][m][n][j];
;               float yn = (bf2f(yv[j][bj][n]) - mu) * rstd * gn[bj][n];
;               Y[(long)(tb + j) * YS + pn * 256 + bj * 128 + wc * 32 + n * 16 + fr] = f2bf(silu_f(g) * yn);
;             }
;         }
	v_pk_add_f32 v[136:137], v[158:159], v[160:161]
	s_nop 0
	v_pk_add_f32 v[136:137], v[136:137], v[154:155]
	s_nop 0
	v_pk_add_f32 v[136:137], v[136:137], v[156:157]
	s_nop 0
	v_pk_mul_f32 v[136:137], v[136:137], s[18:19] op_sel_hi:[1,0]
	s_nop 0
	v_fma_f32 v0, -v136, v136, v137
	v_max_f32_e32 v0, 0, v0
	v_add_f32_e32 v0, 0x3727c5ac, v0
	v_cmp_gt_f32_e32 vcc, s25, v0
	v_mul_f32_e32 v137, 0x4b800000, v0
	s_nop 0
	v_cndmask_b32_e32 v0, v0, v137, vcc
	v_rsq_f32_e32 v0, v0
	s_nop 0
	v_mul_f32_e32 v137, 0x45800000, v0
	v_cndmask_b32_e32 v137, v0, v137, vcc
	v_lshlrev_b32_e32 v0, 16, v162
	v_sub_f32_e32 v0, v0, v136
	v_mul_f32_e32 v0, v0, v137
	v_mul_f32_e32 v0, v151, v0
	v_mul_f32_e32 v0, v126, v0
	v_cvt_pk_bf16_f32 v0, v0, s0
	v_lshlrev_b32_e32 v126, 16, v163
	v_sub_f32_e32 v126, v126, v136
	v_mul_f32_e32 v126, v126, v137
	v_mul_f32_e32 v126, v150, v126
	v_mul_f32_e32 v122, v122, v126
	v_cvt_pk_bf16_f32 v122, v122, s0
	v_lshlrev_b32_e32 v126, 16, v164
	v_sub_f32_e32 v126, v126, v136
	v_mul_f32_e32 v126, v126, v137
	v_mul_f32_e32 v126, v149, v126
	v_mul_f32_e32 v118, v118, v126
	v_cvt_pk_bf16_f32 v118, v118, s0
	v_lshlrev_b32_e32 v126, 16, v165
	v_sub_f32_e32 v126, v126, v136
	v_mul_f32_e32 v136, 0xbfb8aa3b, v114
	v_exp_f32_e32 v136, v136
	v_pk_add_f32 v[132:133], v[198:199], v[200:201]
	v_mul_f32_e32 v126, v126, v137
	v_pk_add_f32 v[132:133], v[132:133], v[194:195]
	v_add_f32_e32 v136, 1.0, v136
	v_rcp_f32_e32 v136, v136
	v_mul_f32_e32 v126, v148, v126
	v_pk_add_f32 v[132:133], v[132:133], v[196:197]
	v_mul_f32_e32 v114, v114, v136
	v_mul_f32_e32 v114, v114, v126
	v_pk_mul_f32 v[132:133], v[132:133], s[18:19] op_sel_hi:[1,0]
	v_cvt_pk_bf16_f32 v126, v114, s0
	v_fma_f32 v114, -v132, v132, v133
	v_max_f32_e32 v114, 0, v114
	v_add_f32_e32 v114, 0x3727c5ac, v114
	v_cmp_gt_f32_e32 vcc, s25, v114
	v_mul_f32_e32 v133, 0x4b800000, v114
	v_mul_f32_e32 v136, 0xbfb8aa3b, v127
	v_cndmask_b32_e32 v114, v114, v133, vcc
	v_rsq_f32_e32 v114, v114
	v_exp_f32_e32 v136, v136
	v_mul_f32_e32 v133, 0x45800000, v114
	v_cndmask_b32_e32 v114, v114, v133, vcc
	v_add_f32_e32 v136, 1.0, v136
	v_rcp_f32_e32 v136, v136
	v_lshlrev_b32_e32 v133, 16, v166
	v_sub_f32_e32 v133, v133, v132
	v_mul_f32_e32 v133, v133, v114
	v_mul_f32_e32 v133, v151, v133
	v_mul_f32_e32 v127, v127, v136
	v_mul_f32_e32 v127, v127, v133
	v_mul_f32_e32 v136, 0xbfb8aa3b, v123
	v_exp_f32_e32 v136, v136
	v_cvt_pk_bf16_f32 v127, v127, s0
	v_add_f32_e32 v136, 1.0, v136
	v_rcp_f32_e32 v136, v136
	v_lshlrev_b32_e32 v133, 16, v167
	v_sub_f32_e32 v133, v133, v132
	v_mul_f32_e32 v133, v133, v114
	v_mul_f32_e32 v133, v150, v133
	v_mul_f32_e32 v123, v123, v136
	v_mul_f32_e32 v123, v123, v133
	v_mul_f32_e32 v136, 0xbfb8aa3b, v119
	v_exp_f32_e32 v136, v136
	v_cvt_pk_bf16_f32 v123, v123, s0
	v_add_f32_e32 v136, 1.0, v136
	v_rcp_f32_e32 v136, v136
	v_lshlrev_b32_e32 v133, 16, v168
	v_sub_f32_e32 v133, v133, v132
	v_mul_f32_e32 v133, v133, v114
	v_mul_f32_e32 v133, v149, v133
	v_mul_f32_e32 v119, v119, v136
	v_mul_f32_e32 v119, v119, v133
	v_cvt_pk_bf16_f32 v119, v119, s0
	v_lshlrev_b32_e32 v133, 16, v169
	v_sub_f32_e32 v132, v133, v132
	v_mul_f32_e32 v114, v132, v114
	v_mul_f32_e32 v132, 0xbfb8aa3b, v115
	v_exp_f32_e32 v132, v132
	v_mul_f32_e32 v114, v148, v114
	v_add_f32_e32 v132, 1.0, v132
	v_rcp_f32_e32 v132, v132
	s_nop 0
	v_mul_f32_e32 v115, v115, v132
	s_nop 0
	v_mul_f32_e32 v114, v115, v114
	v_cvt_pk_bf16_f32 v153, v114, s0
	v_pk_add_f32 v[114:115], v[206:207], v[208:209]
	s_nop 0
	v_pk_add_f32 v[114:115], v[114:115], v[202:203]
	v_mul_f32_e32 v131, 0xbfb8aa3b, v128
	v_pk_add_f32 v[114:115], v[114:115], v[204:205]
	v_exp_f32_e32 v131, v131
	v_pk_mul_f32 v[114:115], v[114:115], s[18:19] op_sel_hi:[1,0]
	v_add_f32_e32 v131, 1.0, v131
	v_fma_f32 v115, -v114, v114, v115
	v_max_f32_e32 v115, 0, v115
	v_add_f32_e32 v115, 0x3727c5ac, v115
	v_cmp_gt_f32_e32 vcc, s25, v115
	v_mul_f32_e32 v130, 0x4b800000, v115
	v_rcp_f32_e32 v131, v131
	v_cndmask_b32_e32 v115, v115, v130, vcc
	v_rsq_f32_e32 v115, v115
	v_mul_f32_e32 v128, v128, v131
	v_mul_f32_e32 v131, 0xbfb8aa3b, v124
	v_mul_f32_e32 v130, 0x45800000, v115
	v_cndmask_b32_e32 v130, v115, v130, vcc
	v_exp_f32_e32 v131, v131
	v_lshlrev_b32_e32 v115, 16, v170
	v_sub_f32_e32 v115, v115, v114
	v_mul_f32_e32 v115, v115, v130
	v_mul_f32_e32 v115, v151, v115
	v_mul_f32_e32 v115, v128, v115
	v_add_f32_e32 v131, 1.0, v131
	v_rcp_f32_e32 v131, v131
	v_cvt_pk_bf16_f32 v115, v115, s0
	v_mul_f32_e32 v124, v124, v131
	v_mul_f32_e32 v131, 0xbfb8aa3b, v120
	v_exp_f32_e32 v131, v131
	v_lshlrev_b32_e32 v128, 16, v171
	v_sub_f32_e32 v128, v128, v114
	v_mul_f32_e32 v128, v128, v130
	v_mul_f32_e32 v128, v150, v128
	v_mul_f32_e32 v124, v124, v128
	v_add_f32_e32 v131, 1.0, v131
	v_rcp_f32_e32 v131, v131
	v_cvt_pk_bf16_f32 v124, v124, s0
	v_mul_f32_e32 v120, v120, v131
	v_lshlrev_b32_e32 v128, 16, v172
	v_sub_f32_e32 v128, v128, v114
	v_mul_f32_e32 v128, v128, v130
	v_mul_f32_e32 v128, v149, v128
	v_mul_f32_e32 v120, v120, v128
	v_cvt_pk_bf16_f32 v120, v120, s0
	v_lshlrev_b32_e32 v128, 16, v173
	v_sub_f32_e32 v114, v128, v114
	v_mul_f32_e32 v128, 0xbfb8aa3b, v116
	v_exp_f32_e32 v128, v128
	v_mul_f32_e32 v114, v114, v130
	v_mul_f32_e32 v114, v148, v114
	v_add_f32_e32 v128, 1.0, v128
	v_rcp_f32_e32 v128, v128
	s_nop 0
	v_mul_f32_e32 v116, v116, v128
	v_mul_f32_e32 v114, v116, v114
	s_nop 0
	s_nop 0
	v_cvt_pk_bf16_f32 v114, v114, s0
	global_store_short v[142:143], v0, off
	global_store_short v[142:143], v122, off offset:32
	global_store_short v[142:143], v118, off offset:256
	global_store_short v[142:143], v126, off offset:288
	global_store_short v[144:145], v127, off
; __device__ __forceinline__ float bf2f(u16 b) { return __uint_as_float(((unsigned)b) << 16); }
; __device__ __forceinline__ float silu_f(float g) { return g * __builtin_amdgcn_rcpf(1.f + __builtin_amdgcn_exp2f(-g * LOG2E)); }
; template <int EPI>
; __device__ __forceinline__ void epilogue(const Params& p, int pass, int layer, int pm, int pn,
;                                          f32x4 (&acc)[2][2][4][2], const float* xin, float* xout) {
;     ...
;       for (int m = 0; m < 4; ++m) {
;         int tb = t0 + ai * 128 + wr * 64 + m * 16 + fq * 4;
;         asm volatile("" : "+v"(tb));
;         float4 s01[4], s23[4];
;         u16 yv[4][2][2];
; #pragma unroll
;         for (int j = 0; j < 4; ++j) {
;           const float4* sp = (const float4*)(stat + ((long)(tb + j) * 8 + h) * 8);
;           s01[j] = sp[0]; s23[j] = sp[1];
; #pragma unroll
;           for (int bj = 0; bj < 2; ++bj)
; #pragma unroll
;             for (int n = 0; n < 2; ++n)
;               yv[j][bj][n] = Y[(long)(tb + j) * YS + pn * 256 + bj * 128 + wc * 32 + n * 16 + fr];
;         }
; #pragma unroll
;         for (int j = 0; j < 4; ++j) {
;           float s1 = s01[j].x + s01[j].z + s23[j].x + s23[j].z, s2 = s01[j].y + s01[j].w + s23[j].y + s23[j].w;
;           float mu = s1 * (1.f / 512.f);
;           float var = s2 * (1.f / 512.f) - mu * mu;
;           float rstd = rsqrtf(fmaxf(var, 0.f) + 1e-5f);
; #pragma unroll
;           for (int bj = 0; bj < 2; ++bj)
; #pragma unroll
;             for (int n = 0; n < 2; ++n) {
;               float g = acc[ai][bj][m][n][j];
;               float yn = (bf2f(yv[j][bj][n]) - mu) * rstd * gn[bj][n];
;               Y[(long)(tb + j) * YS + pn * 256 + bj * 128 + wc * 32 + n * 16 + fr] = f2bf(silu_f(g) * yn);
;             }
;         }
	global_store_short v[144:145], v123, off offset:32
	global_store_short v[144:145], v119, off offset:256
	global_store_short v[144:145], v153, off offset:288
	global_store_short v[146:147], v115, off
	global_store_short v[146:147], v124, off offset:32
	global_store_short v[146:147], v120, off offset:256
	global_store_short v[146:147], v114, off offset:288
	v_or_b32_e32 v118, 16, v152
	v_pk_add_f32 v[114:115], v[214:215], v[216:217]
	s_nop 0
	v_pk_add_f32 v[114:115], v[114:115], v[210:211]
	s_nop 0
	v_pk_add_f32 v[114:115], v[114:115], v[212:213]
	s_nop 0
	v_pk_mul_f32 v[114:115], v[114:115], s[18:19] op_sel_hi:[1,0]
	s_nop 0
	v_fma_f32 v0, -v114, v114, v115
	v_max_f32_e32 v0, 0, v0
	v_add_f32_e32 v0, 0x3727c5ac, v0
	v_cmp_gt_f32_e32 vcc, s25, v0
	v_mul_f32_e32 v115, 0x4b800000, v0
	s_nop 0
	v_cndmask_b32_e32 v0, v0, v115, vcc
	v_rsq_f32_e32 v0, v0
	s_nop 0
	v_mul_f32_e32 v115, 0x45800000, v0
	v_cndmask_b32_e32 v0, v0, v115, vcc
	v_lshlrev_b32_e32 v115, 16, v174
	v_mul_f32_e32 v116, 0xbfb8aa3b, v129
	v_exp_f32_e32 v116, v116
	v_sub_f32_e32 v115, v115, v114
	v_mul_f32_e32 v115, v115, v0
	v_mul_f32_e32 v115, v151, v115
	v_add_f32_e32 v116, 1.0, v116
	v_rcp_f32_e32 v116, v116
	s_nop 0
	v_mul_f32_e32 v116, v129, v116
	v_mul_f32_e32 v115, v116, v115
	v_mul_f32_e32 v116, 0xbfb8aa3b, v125
	v_exp_f32_e32 v116, v116
	v_cvt_pk_bf16_f32 v115, v115, s0
	global_store_short v[140:141], v115, off
	v_lshlrev_b32_e32 v115, 16, v175
	v_add_f32_e32 v116, 1.0, v116
	v_rcp_f32_e32 v116, v116
	v_sub_f32_e32 v115, v115, v114
	v_mul_f32_e32 v115, v115, v0
	v_mul_f32_e32 v115, v150, v115
	v_mul_f32_e32 v116, v125, v116
	v_mul_f32_e32 v115, v116, v115
	v_mul_f32_e32 v116, 0xbfb8aa3b, v121
	v_exp_f32_e32 v116, v116
	v_cvt_pk_bf16_f32 v115, v115, s0
	global_store_short v[140:141], v115, off offset:32
	v_lshlrev_b32_e32 v115, 16, v176
	v_add_f32_e32 v116, 1.0, v116
	v_rcp_f32_e32 v116, v116
	v_sub_f32_e32 v115, v115, v114
	v_mul_f32_e32 v115, v115, v0
	v_mul_f32_e32 v115, v149, v115
	v_mul_f32_e32 v116, v121, v116
	v_mul_f32_e32 v115, v116, v115
	v_cvt_pk_bf16_f32 v115, v115, s0
	global_store_short v[140:141], v115, off offset:256
	v_lshlrev_b32_e32 v115, 16, v177
	v_sub_f32_e32 v114, v115, v114
	v_mul_f32_e32 v0, v114, v0
	v_mul_f32_e32 v114, 0xbfb8aa3b, v117
	v_exp_f32_e32 v114, v114
	v_mul_f32_e32 v0, v148, v0
	v_add_f32_e32 v114, 1.0, v114
	v_rcp_f32_e32 v114, v114
	s_nop 0
	v_mul_f32_e32 v114, v117, v114
	v_mul_f32_e32 v0, v114, v0
	v_cvt_pk_bf16_f32 v0, v0, s0
	global_store_short v[140:141], v0, off offset:288
	s_nop 0
	v_ashrrev_i32_e32 v119, 31, v118
	v_lshlrev_b64 v[114:115], 8, v[118:119]
	v_lshl_add_u64 v[120:121], s[16:17], 0, v[114:115]
	global_load_dwordx4 v[130:133], v[120:121], off offset:16
	global_load_dwordx4 v[134:137], v[120:121], off
	v_mad_i64_i32 v[124:125], s[14:15], v118, s24, v[138:139]
	global_load_ushort v178, v[124:125], off
	global_load_ushort v179, v[124:125], off offset:32
	global_load_ushort v180, v[124:125], off offset:256
	global_load_ushort v181, v[124:125], off offset:288
	v_add_u32_e32 v114, 1, v118
	v_ashrrev_i32_e32 v115, 31, v114
	v_lshlrev_b64 v[116:117], 8, v[114:115]
	v_lshl_add_u64 v[116:117], s[16:17], 0, v[116:117]
	global_load_dwordx4 v[194:197], v[116:117], off offset:16
	global_load_dwordx4 v[198:201], v[116:117], off
	v_mad_i64_i32 v[126:127], s[14:15], v114, s24, v[138:139]
	global_load_ushort v182, v[126:127], off
	global_load_ushort v183, v[126:127], off offset:32
	global_load_ushort v184, v[126:127], off offset:256
	global_load_ushort v185, v[126:127], off offset:288
	v_add_u32_e32 v122, 2, v118
	v_ashrrev_i32_e32 v123, 31, v122
	v_lshlrev_b64 v[114:115], 8, v[122:123]
	v_lshl_add_u64 v[114:115], s[16:17], 0, v[114:115]
	global_load_dwordx4 v[202:205], v[114:115], off offset:16
	global_load_dwordx4 v[206:209], v[114:115], off
	v_mad_i64_i32 v[128:129], s[14:15], v122, s24, v[138:139]
	global_load_ushort v186, v[128:129], off
	global_load_ushort v187, v[128:129], off offset:32
	global_load_ushort v188, v[128:129], off offset:256
	global_load_ushort v189, v[128:129], off offset:288
	v_add_u32_e32 v122, 3, v118
	v_ashrrev_i32_e32 v123, 31, v122
	v_lshlrev_b64 v[118:119], 8, v[122:123]
	v_lshl_add_u64 v[118:119], s[16:17], 0, v[118:119]
	global_load_dwordx4 v[210:213], v[118:119], off offset:16
	global_load_dwordx4 v[214:217], v[118:119], off
	v_mad_i64_i32 v[122:123], s[14:15], v122, s24, v[138:139]
	global_load_ushort v190, v[122:123], off
	global_load_ushort v191, v[122:123], off offset:32
	global_load_ushort v192, v[122:123], off offset:256
	global_load_ushort v193, v[122:123], off offset:288
	s_waitcnt vmcnt(0)
; __device__ __forceinline__ float bf2f(u16 b) { return __uint_as_float(((unsigned)b) << 16); }
; __device__ __forceinline__ float silu_f(float g) { return g * __builtin_amdgcn_rcpf(1.f + __builtin_amdgcn_exp2f(-g * LOG2E)); }
; template <int EPI>
; __device__ __forceinline__ void epilogue(const Params& p, int pass, int layer, int pm, int pn,
;                                          f32x4 (&acc)[2][2][4][2], const float* xin, float* xout) {
;     ...
;       for (int m = 0; m < 4; ++m) {
;         int tb = t0 + ai * 128 + wr * 64 + m * 16 + fq * 4;
;         asm volatile("" : "+v"(tb));
;         float4 s01[4], s23[4];
;         u16 yv[4][2][2];
; #pragma unroll
;         for (int j = 0; j < 4; ++j) {
;           const float4* sp = (const float4*)(stat + ((long)(tb + j) * 8 + h) * 8);
;           s01[j] = sp[0]; s23[j] = sp[1];
; #pragma unroll
;           for (int bj = 0; bj < 2; ++bj)
; #pragma unroll
;             for (int n = 0; n < 2; ++n)
;               yv[j][bj][n] = Y[(long)(tb + j) * YS + pn * 256 + bj * 128 + wc * 32 + n * 16 + fr];
;         }
; #pragma unroll
;         for (int j = 0; j < 4; ++j) {
;           float s1 = s01[j].x + s01[j].z + s23[j].x + s23[j].z, s2 = s01[j].y + s01[j].w + s23[j].y + s23[j].w;
;           float mu = s1 * (1.f / 512.f);
;           float var = s2 * (1.f / 512.f) - mu * mu;
;           float rstd = rsqrtf(fmaxf(var, 0.f) + 1e-5f);
; #pragma unroll
;           for (int bj = 0; bj < 2; ++bj)
; #pragma unroll
;             for (int n = 0; n < 2; ++n) {
;               float g = acc[ai][bj][m][n][j];
;               float yn = (bf2f(yv[j][bj][n]) - mu) * rstd * gn[bj][n];
;               Y[(long)(tb + j) * YS + pn * 256 + bj * 128 + wc * 32 + n * 16 + fr] = f2bf(silu_f(g) * yn);
;             }
;         }
	v_pk_add_f32 v[120:121], v[134:135], v[136:137]
	s_nop 0
	v_pk_add_f32 v[120:121], v[120:121], v[130:131]
	v_mul_f32_e32 v130, 0xbfb8aa3b, v110
	v_pk_add_f32 v[120:121], v[120:121], v[132:133]
	v_exp_f32_e32 v130, v130
	v_pk_mul_f32 v[120:121], v[120:121], s[18:19] op_sel_hi:[1,0]
	v_add_f32_e32 v130, 1.0, v130
	v_fma_f32 v0, -v120, v120, v121
	v_max_f32_e32 v0, 0, v0
	v_add_f32_e32 v0, 0x3727c5ac, v0
	v_cmp_gt_f32_e32 vcc, s25, v0
	v_mul_f32_e32 v121, 0x4b800000, v0
	v_rcp_f32_e32 v130, v130
	v_cndmask_b32_e32 v0, v0, v121, vcc
	v_rsq_f32_e32 v0, v0
	v_mul_f32_e32 v110, v110, v130
	v_mul_f32_e32 v130, 0xbfb8aa3b, v106
	v_mul_f32_e32 v121, 0x45800000, v0
	v_cndmask_b32_e32 v121, v0, v121, vcc
	v_exp_f32_e32 v130, v130
	v_lshlrev_b32_e32 v0, 16, v178
	v_sub_f32_e32 v0, v0, v120
	v_mul_f32_e32 v0, v0, v121
	v_mul_f32_e32 v0, v151, v0
	v_mul_f32_e32 v0, v110, v0
	v_add_f32_e32 v130, 1.0, v130
	v_rcp_f32_e32 v130, v130
	v_cvt_pk_bf16_f32 v0, v0, s0
	v_mul_f32_e32 v106, v106, v130
	v_mul_f32_e32 v130, 0xbfb8aa3b, v102
	v_exp_f32_e32 v130, v130
	v_lshlrev_b32_e32 v110, 16, v179
	v_sub_f32_e32 v110, v110, v120
	v_mul_f32_e32 v110, v110, v121
	v_mul_f32_e32 v110, v150, v110
	v_mul_f32_e32 v106, v106, v110
	v_add_f32_e32 v130, 1.0, v130
	v_rcp_f32_e32 v130, v130
	v_cvt_pk_bf16_f32 v106, v106, s0
	v_mul_f32_e32 v102, v102, v130
	v_lshlrev_b32_e32 v110, 16, v180
	v_sub_f32_e32 v110, v110, v120
	v_mul_f32_e32 v110, v110, v121
	v_mul_f32_e32 v110, v149, v110
	v_mul_f32_e32 v102, v102, v110
	v_cvt_pk_bf16_f32 v102, v102, s0
	v_lshlrev_b32_e32 v110, 16, v181
	v_sub_f32_e32 v110, v110, v120
	v_mul_f32_e32 v120, 0xbfb8aa3b, v98
	v_exp_f32_e32 v120, v120
	v_pk_add_f32 v[116:117], v[198:199], v[200:201]
	v_mul_f32_e32 v110, v110, v121
	v_pk_add_f32 v[116:117], v[116:117], v[194:195]
	v_add_f32_e32 v120, 1.0, v120
	v_rcp_f32_e32 v120, v120
	v_mul_f32_e32 v110, v148, v110
	v_pk_add_f32 v[116:117], v[116:117], v[196:197]
	v_mul_f32_e32 v98, v98, v120
	v_mul_f32_e32 v98, v98, v110
	v_pk_mul_f32 v[116:117], v[116:117], s[18:19] op_sel_hi:[1,0]
	v_cvt_pk_bf16_f32 v110, v98, s0
	v_fma_f32 v98, -v116, v116, v117
	v_max_f32_e32 v98, 0, v98
	v_add_f32_e32 v98, 0x3727c5ac, v98
	v_cmp_gt_f32_e32 vcc, s25, v98
	v_mul_f32_e32 v117, 0x4b800000, v98
	v_mul_f32_e32 v120, 0xbfb8aa3b, v111
	v_cndmask_b32_e32 v98, v98, v117, vcc
	v_rsq_f32_e32 v98, v98
	v_exp_f32_e32 v120, v120
	v_mul_f32_e32 v117, 0x45800000, v98
	v_cndmask_b32_e32 v98, v98, v117, vcc
	v_add_f32_e32 v120, 1.0, v120
	v_rcp_f32_e32 v120, v120
	v_lshlrev_b32_e32 v117, 16, v182
	v_sub_f32_e32 v117, v117, v116
	v_mul_f32_e32 v117, v117, v98
	v_mul_f32_e32 v117, v151, v117
	v_mul_f32_e32 v111, v111, v120
	v_mul_f32_e32 v111, v111, v117
	v_mul_f32_e32 v120, 0xbfb8aa3b, v107
	v_exp_f32_e32 v120, v120
	v_cvt_pk_bf16_f32 v111, v111, s0
	v_add_f32_e32 v120, 1.0, v120
	v_rcp_f32_e32 v120, v120
	v_lshlrev_b32_e32 v117, 16, v183
	v_sub_f32_e32 v117, v117, v116
	v_mul_f32_e32 v117, v117, v98
	v_mul_f32_e32 v117, v150, v117
	v_mul_f32_e32 v107, v107, v120
	v_mul_f32_e32 v107, v107, v117
	v_mul_f32_e32 v120, 0xbfb8aa3b, v103
	v_exp_f32_e32 v120, v120
	v_cvt_pk_bf16_f32 v107, v107, s0
	v_add_f32_e32 v120, 1.0, v120
	v_rcp_f32_e32 v120, v120
	v_lshlrev_b32_e32 v117, 16, v184
	v_sub_f32_e32 v117, v117, v116
	v_mul_f32_e32 v117, v117, v98
	v_mul_f32_e32 v117, v149, v117
	v_mul_f32_e32 v103, v103, v120
	v_mul_f32_e32 v103, v103, v117
	v_cvt_pk_bf16_f32 v103, v103, s0
	v_lshlrev_b32_e32 v117, 16, v185
	v_sub_f32_e32 v116, v117, v116
	v_mul_f32_e32 v98, v116, v98
	v_mul_f32_e32 v116, 0xbfb8aa3b, v99
	v_exp_f32_e32 v116, v116
	v_mul_f32_e32 v98, v148, v98
	v_add_f32_e32 v116, 1.0, v116
	v_rcp_f32_e32 v116, v116
	s_nop 0
	v_mul_f32_e32 v99, v99, v116
	s_nop 0
	v_mul_f32_e32 v98, v99, v98
	v_cvt_pk_bf16_f32 v130, v98, s0
	v_pk_add_f32 v[98:99], v[206:207], v[208:209]
	s_nop 0
	v_pk_add_f32 v[98:99], v[98:99], v[202:203]
	v_mul_f32_e32 v115, 0xbfb8aa3b, v112
	v_pk_add_f32 v[98:99], v[98:99], v[204:205]
	v_exp_f32_e32 v115, v115
	v_pk_mul_f32 v[98:99], v[98:99], s[18:19] op_sel_hi:[1,0]
	v_add_f32_e32 v115, 1.0, v115
	v_fma_f32 v99, -v98, v98, v99
	v_max_f32_e32 v99, 0, v99
	v_add_f32_e32 v99, 0x3727c5ac, v99
	v_cmp_gt_f32_e32 vcc, s25, v99
	v_mul_f32_e32 v114, 0x4b800000, v99
	v_rcp_f32_e32 v115, v115
	v_cndmask_b32_e32 v99, v99, v114, vcc
	v_rsq_f32_e32 v99, v99
	v_mul_f32_e32 v112, v112, v115
	v_mul_f32_e32 v115, 0xbfb8aa3b, v108
	v_mul_f32_e32 v114, 0x45800000, v99
	v_cndmask_b32_e32 v114, v99, v114, vcc
	v_exp_f32_e32 v115, v115
	v_lshlrev_b32_e32 v99, 16, v186
	v_sub_f32_e32 v99, v99, v98
	v_mul_f32_e32 v99, v99, v114
	v_mul_f32_e32 v99, v151, v99
	v_mul_f32_e32 v99, v112, v99
	v_add_f32_e32 v115, 1.0, v115
	v_rcp_f32_e32 v115, v115
	v_cvt_pk_bf16_f32 v99, v99, s0
	v_mul_f32_e32 v108, v108, v115
	v_mul_f32_e32 v115, 0xbfb8aa3b, v104
	v_exp_f32_e32 v115, v115
	v_lshlrev_b32_e32 v112, 16, v187
	v_sub_f32_e32 v112, v112, v98
	v_mul_f32_e32 v112, v112, v114
	v_mul_f32_e32 v112, v150, v112
	v_mul_f32_e32 v108, v108, v112
	v_add_f32_e32 v115, 1.0, v115
	v_rcp_f32_e32 v115, v115
	v_cvt_pk_bf16_f32 v108, v108, s0
	v_mul_f32_e32 v104, v104, v115
	v_lshlrev_b32_e32 v112, 16, v188
	v_sub_f32_e32 v112, v112, v98
	v_mul_f32_e32 v112, v112, v114
	v_mul_f32_e32 v112, v149, v112
	v_mul_f32_e32 v104, v104, v112
	v_cvt_pk_bf16_f32 v104, v104, s0
	v_lshlrev_b32_e32 v112, 16, v189
	v_sub_f32_e32 v98, v112, v98
	v_mul_f32_e32 v112, 0xbfb8aa3b, v100
	v_exp_f32_e32 v112, v112
	v_mul_f32_e32 v98, v98, v114
	v_mul_f32_e32 v98, v148, v98
	v_add_f32_e32 v112, 1.0, v112
	v_rcp_f32_e32 v112, v112
	s_nop 0
	v_mul_f32_e32 v100, v100, v112
	v_mul_f32_e32 v98, v100, v98
; __device__ __forceinline__ float bf2f(u16 b) { return __uint_as_float(((unsigned)b) << 16); }
; __device__ __forceinline__ float silu_f(float g) { return g * __builtin_amdgcn_rcpf(1.f + __builtin_amdgcn_exp2f(-g * LOG2E)); }
; template <int EPI>
; __device__ __forceinline__ void epilogue(const Params& p, int pass, int layer, int pm, int pn,
;                                          f32x4 (&acc)[2][2][4][2], const float* xin, float* xout) {
;     ...
;         int tb = t0 + ai * 128 + wr * 64 + m * 16 + fq * 4;
;         asm volatile("" : "+v"(tb));
;         float4 s01[4], s23[4];
;         u16 yv[4][2][2];
; #pragma unroll
;         for (int j = 0; j < 4; ++j) {
;           const float4* sp = (const float4*)(stat + ((long)(tb + j) * 8 + h) * 8);
;           s01[j] = sp[0]; s23[j] = sp[1];
; #pragma unroll
;           for (int bj = 0; bj < 2; ++bj)
; #pragma unroll
;             for (int n = 0; n < 2; ++n)
;               yv[j][bj][n] = Y[(long)(tb + j) * YS + pn * 256 + bj * 128 + wc * 32 + n * 16 + fr];
;         }
; #pragma unroll
;         for (int j = 0; j < 4; ++j) {
;           float s1 = s01[j].x + s01[j].z + s23[j].x + s23[j].z, s2 = s01[j].y + s01[j].w + s23[j].y + s23[j].w;
;           float mu = s1 * (1.f / 512.f);
;           float var = s2 * (1.f / 512.f) - mu * mu;
;           float rstd = rsqrtf(fmaxf(var, 0.f) + 1e-5f);
; #pragma unroll
;           for (int bj = 0; bj < 2; ++bj)
; #pragma unroll
;             for (int n = 0; n < 2; ++n) {
;               float g = acc[ai][bj][m][n][j];
;               float yn = (bf2f(yv[j][bj][n]) - mu) * rstd * gn[bj][n];
;               Y[(long)(tb + j) * YS + pn * 256 + bj * 128 + wc * 32 + n * 16 + fr] = f2bf(silu_f(g) * yn);
	s_nop 0
	s_nop 0
	v_cvt_pk_bf16_f32 v98, v98, s0
	global_store_short v[124:125], v0, off
	global_store_short v[124:125], v106, off offset:32
	global_store_short v[124:125], v102, off offset:256
	global_store_short v[124:125], v110, off offset:288
	global_store_short v[126:127], v111, off
	global_store_short v[126:127], v107, off offset:32
	global_store_short v[126:127], v103, off offset:256
	global_store_short v[126:127], v130, off offset:288
	global_store_short v[128:129], v99, off
	global_store_short v[128:129], v108, off offset:32
	global_store_short v[128:129], v104, off offset:256
	global_store_short v[128:129], v98, off offset:288
	v_or_b32_e32 v102, 32, v152
	v_pk_add_f32 v[98:99], v[214:215], v[216:217]
	s_nop 0
	v_pk_add_f32 v[98:99], v[98:99], v[210:211]
	s_nop 0
	v_pk_add_f32 v[98:99], v[98:99], v[212:213]
	s_nop 0
	v_pk_mul_f32 v[98:99], v[98:99], s[18:19] op_sel_hi:[1,0]
	s_nop 0
	v_fma_f32 v0, -v98, v98, v99
	v_max_f32_e32 v0, 0, v0
	v_add_f32_e32 v0, 0x3727c5ac, v0
	v_cmp_gt_f32_e32 vcc, s25, v0
	v_mul_f32_e32 v99, 0x4b800000, v0
	s_nop 0
	v_cndmask_b32_e32 v0, v0, v99, vcc
	v_rsq_f32_e32 v0, v0
	s_nop 0
	v_mul_f32_e32 v99, 0x45800000, v0
	v_cndmask_b32_e32 v0, v0, v99, vcc
	v_lshlrev_b32_e32 v99, 16, v190
	v_mul_f32_e32 v100, 0xbfb8aa3b, v113
	v_exp_f32_e32 v100, v100
	v_sub_f32_e32 v99, v99, v98
	v_mul_f32_e32 v99, v99, v0
	v_mul_f32_e32 v99, v151, v99
	v_add_f32_e32 v100, 1.0, v100
	v_rcp_f32_e32 v100, v100
	s_nop 0
	v_mul_f32_e32 v100, v113, v100
	v_mul_f32_e32 v99, v100, v99
	v_mul_f32_e32 v100, 0xbfb8aa3b, v109
	v_exp_f32_e32 v100, v100
	v_cvt_pk_bf16_f32 v99, v99, s0
	global_store_short v[122:123], v99, off
	v_lshlrev_b32_e32 v99, 16, v191
	v_add_f32_e32 v100, 1.0, v100
	v_rcp_f32_e32 v100, v100
	v_sub_f32_e32 v99, v99, v98
	v_mul_f32_e32 v99, v99, v0
	v_mul_f32_e32 v99, v150, v99
	v_mul_f32_e32 v100, v109, v100
	v_mul_f32_e32 v99, v100, v99
	v_mul_f32_e32 v100, 0xbfb8aa3b, v105
	v_exp_f32_e32 v100, v100
	v_cvt_pk_bf16_f32 v99, v99, s0
	global_store_short v[122:123], v99, off offset:32
	v_lshlrev_b32_e32 v99, 16, v192
	v_add_f32_e32 v100, 1.0, v100
	v_rcp_f32_e32 v100, v100
	v_sub_f32_e32 v99, v99, v98
	v_mul_f32_e32 v99, v99, v0
	v_mul_f32_e32 v99, v149, v99
	v_mul_f32_e32 v100, v105, v100
	v_mul_f32_e32 v99, v100, v99
	v_cvt_pk_bf16_f32 v99, v99, s0
	global_store_short v[122:123], v99, off offset:256
	v_lshlrev_b32_e32 v99, 16, v193
	v_sub_f32_e32 v98, v99, v98
	v_mul_f32_e32 v0, v98, v0
	v_mul_f32_e32 v98, 0xbfb8aa3b, v101
	v_exp_f32_e32 v98, v98
	v_mul_f32_e32 v0, v148, v0
	v_add_f32_e32 v98, 1.0, v98
	v_rcp_f32_e32 v98, v98
	s_nop 0
	v_mul_f32_e32 v98, v101, v98
	v_mul_f32_e32 v0, v98, v0
	v_cvt_pk_bf16_f32 v0, v0, s0
	global_store_short v[122:123], v0, off offset:288
	s_nop 0
	v_ashrrev_i32_e32 v103, 31, v102
	v_lshlrev_b64 v[98:99], 8, v[102:103]
	v_lshl_add_u64 v[104:105], s[16:17], 0, v[98:99]
	global_load_dwordx4 v[114:117], v[104:105], off offset:16
	global_load_dwordx4 v[118:121], v[104:105], off
	v_mad_i64_i32 v[108:109], s[14:15], v102, s24, v[138:139]
	global_load_ushort v162, v[108:109], off
	global_load_ushort v163, v[108:109], off offset:32
	global_load_ushort v164, v[108:109], off offset:256
	global_load_ushort v165, v[108:109], off offset:288
	v_add_u32_e32 v98, 1, v102
	v_ashrrev_i32_e32 v99, 31, v98
	v_lshlrev_b64 v[100:101], 8, v[98:99]
	v_lshl_add_u64 v[100:101], s[16:17], 0, v[100:101]
	global_load_dwordx4 v[194:197], v[100:101], off offset:16
	global_load_dwordx4 v[198:201], v[100:101], off
	v_mad_i64_i32 v[110:111], s[14:15], v98, s24, v[138:139]
	global_load_ushort v166, v[110:111], off
	global_load_ushort v167, v[110:111], off offset:32
	global_load_ushort v168, v[110:111], off offset:256
	global_load_ushort v169, v[110:111], off offset:288
	v_add_u32_e32 v106, 2, v102
	v_ashrrev_i32_e32 v107, 31, v106
	v_lshlrev_b64 v[98:99], 8, v[106:107]
	v_lshl_add_u64 v[98:99], s[16:17], 0, v[98:99]
	global_load_dwordx4 v[202:205], v[98:99], off offset:16
	global_load_dwordx4 v[206:209], v[98:99], off
	v_mad_i64_i32 v[112:113], s[14:15], v106, s24, v[138:139]
	global_load_ushort v170, v[112:113], off
	global_load_ushort v171, v[112:113], off offset:32
	global_load_ushort v172, v[112:113], off offset:256
	global_load_ushort v173, v[112:113], off offset:288
	v_add_u32_e32 v106, 3, v102
	v_ashrrev_i32_e32 v107, 31, v106
	v_lshlrev_b64 v[102:103], 8, v[106:107]
	v_lshl_add_u64 v[102:103], s[16:17], 0, v[102:103]
	global_load_dwordx4 v[210:213], v[102:103], off offset:16
	global_load_dwordx4 v[214:217], v[102:103], off
	v_mad_i64_i32 v[106:107], s[14:15], v106, s24, v[138:139]
	global_load_ushort v174, v[106:107], off
	global_load_ushort v175, v[106:107], off offset:32
	global_load_ushort v176, v[106:107], off offset:256
	global_load_ushort v177, v[106:107], off offset:288
	s_waitcnt vmcnt(0)
; __device__ __forceinline__ float bf2f(u16 b) { return __uint_as_float(((unsigned)b) << 16); }
; __device__ __forceinline__ float silu_f(float g) { return g * __builtin_amdgcn_rcpf(1.f + __builtin_amdgcn_exp2f(-g * LOG2E)); }
; template <int EPI>
; __device__ __forceinline__ void epilogue(const Params& p, int pass, int layer, int pm, int pn,
;                                          f32x4 (&acc)[2][2][4][2], const float* xin, float* xout) {
;     ...
; #pragma unroll
;         for (int j = 0; j < 4; ++j) {
;           const float4* sp = (const float4*)(stat + ((long)(tb + j) * 8 + h) * 8);
;           s01[j] = sp[0]; s23[j] = sp[1];
; #pragma unroll
;           for (int bj = 0; bj < 2; ++bj)
; #pragma unroll
;             for (int n = 0; n < 2; ++n)
;               yv[j][bj][n] = Y[(long)(tb + j) * YS + pn * 256 + bj * 128 + wc * 32 + n * 16 + fr];
;         }
; #pragma unroll
;         for (int j = 0; j < 4; ++j) {
;           float s1 = s01[j].x + s01[j].z + s23[j].x + s23[j].z, s2 = s01[j].y + s01[j].w + s23[j].y + s23[j].w;
;           float mu = s1 * (1.f / 512.f);
;           float var = s2 * (1.f / 512.f) - mu * mu;
;           float rstd = rsqrtf(fmaxf(var, 0.f) + 1e-5f);
; #pragma unroll
;           for (int bj = 0; bj < 2; ++bj)
; #pragma unroll
;             for (int n = 0; n < 2; ++n) {
;               float g = acc[ai][bj][m][n][j];
;               float yn = (bf2f(yv[j][bj][n]) - mu) * rstd * gn[bj][n];
;               Y[(long)(tb + j) * YS + pn * 256 + bj * 128 + wc * 32 + n * 16 + fr] = f2bf(silu_f(g) * yn);
	v_pk_add_f32 v[104:105], v[118:119], v[120:121]
	s_nop 0
	v_pk_add_f32 v[104:105], v[104:105], v[114:115]
	v_mul_f32_e32 v114, 0xbfb8aa3b, v94
	v_pk_add_f32 v[104:105], v[104:105], v[116:117]
	v_exp_f32_e32 v114, v114
	v_pk_mul_f32 v[104:105], v[104:105], s[18:19] op_sel_hi:[1,0]
	v_add_f32_e32 v114, 1.0, v114
	v_fma_f32 v0, -v104, v104, v105
	v_max_f32_e32 v0, 0, v0
	v_add_f32_e32 v0, 0x3727c5ac, v0
	v_cmp_gt_f32_e32 vcc, s25, v0
	v_mul_f32_e32 v105, 0x4b800000, v0
	v_rcp_f32_e32 v114, v114
	v_cndmask_b32_e32 v0, v0, v105, vcc
	v_rsq_f32_e32 v0, v0
	v_mul_f32_e32 v94, v94, v114
	v_mul_f32_e32 v114, 0xbfb8aa3b, v90
	v_mul_f32_e32 v105, 0x45800000, v0
	v_cndmask_b32_e32 v105, v0, v105, vcc
	v_exp_f32_e32 v114, v114
	v_lshlrev_b32_e32 v0, 16, v162
	v_sub_f32_e32 v0, v0, v104
	v_mul_f32_e32 v0, v0, v105
	v_mul_f32_e32 v0, v151, v0
	v_mul_f32_e32 v0, v94, v0
	v_add_f32_e32 v114, 1.0, v114
	v_rcp_f32_e32 v114, v114
	v_cvt_pk_bf16_f32 v0, v0, s0
	v_mul_f32_e32 v90, v90, v114
	v_mul_f32_e32 v114, 0xbfb8aa3b, v86
	v_exp_f32_e32 v114, v114
	v_lshlrev_b32_e32 v94, 16, v163
	v_sub_f32_e32 v94, v94, v104
	v_mul_f32_e32 v94, v94, v105
	v_mul_f32_e32 v94, v150, v94
	v_mul_f32_e32 v90, v90, v94
	v_add_f32_e32 v114, 1.0, v114
	v_rcp_f32_e32 v114, v114
	v_cvt_pk_bf16_f32 v90, v90, s0
	v_mul_f32_e32 v86, v86, v114
	v_lshlrev_b32_e32 v94, 16, v164
	v_sub_f32_e32 v94, v94, v104
	v_mul_f32_e32 v94, v94, v105
	v_mul_f32_e32 v94, v149, v94
	v_mul_f32_e32 v86, v86, v94
	v_cvt_pk_bf16_f32 v86, v86, s0
	v_lshlrev_b32_e32 v94, 16, v165
	v_sub_f32_e32 v94, v94, v104
	v_mul_f32_e32 v104, 0xbfb8aa3b, v82
	v_exp_f32_e32 v104, v104
	v_pk_add_f32 v[100:101], v[198:199], v[200:201]
	v_mul_f32_e32 v94, v94, v105
	v_pk_add_f32 v[100:101], v[100:101], v[194:195]
	v_add_f32_e32 v104, 1.0, v104
	v_rcp_f32_e32 v104, v104
	v_mul_f32_e32 v94, v148, v94
	v_pk_add_f32 v[100:101], v[100:101], v[196:197]
	v_mul_f32_e32 v82, v82, v104
	v_mul_f32_e32 v82, v82, v94
	v_pk_mul_f32 v[100:101], v[100:101], s[18:19] op_sel_hi:[1,0]
	v_cvt_pk_bf16_f32 v94, v82, s0
	v_fma_f32 v82, -v100, v100, v101
	v_max_f32_e32 v82, 0, v82
	v_add_f32_e32 v82, 0x3727c5ac, v82
	v_cmp_gt_f32_e32 vcc, s25, v82
	v_mul_f32_e32 v101, 0x4b800000, v82
	v_mul_f32_e32 v104, 0xbfb8aa3b, v95
	v_cndmask_b32_e32 v82, v82, v101, vcc
	v_rsq_f32_e32 v82, v82
	v_exp_f32_e32 v104, v104
	v_mul_f32_e32 v101, 0x45800000, v82
	v_cndmask_b32_e32 v82, v82, v101, vcc
	v_add_f32_e32 v104, 1.0, v104
	v_rcp_f32_e32 v104, v104
	v_lshlrev_b32_e32 v101, 16, v166
	v_sub_f32_e32 v101, v101, v100
	v_mul_f32_e32 v101, v101, v82
	v_mul_f32_e32 v101, v151, v101
	v_mul_f32_e32 v95, v95, v104
	v_mul_f32_e32 v95, v95, v101
	v_mul_f32_e32 v104, 0xbfb8aa3b, v91
	v_exp_f32_e32 v104, v104
	v_cvt_pk_bf16_f32 v95, v95, s0
	v_add_f32_e32 v104, 1.0, v104
	v_rcp_f32_e32 v104, v104
	v_lshlrev_b32_e32 v101, 16, v167
	v_sub_f32_e32 v101, v101, v100
	v_mul_f32_e32 v101, v101, v82
	v_mul_f32_e32 v101, v150, v101
	v_mul_f32_e32 v91, v91, v104
	v_mul_f32_e32 v91, v91, v101
	v_mul_f32_e32 v104, 0xbfb8aa3b, v87
	v_exp_f32_e32 v104, v104
	v_cvt_pk_bf16_f32 v91, v91, s0
	v_add_f32_e32 v104, 1.0, v104
	v_rcp_f32_e32 v104, v104
	v_lshlrev_b32_e32 v101, 16, v168
	v_sub_f32_e32 v101, v101, v100
	v_mul_f32_e32 v101, v101, v82
	v_mul_f32_e32 v101, v149, v101
	v_mul_f32_e32 v87, v87, v104
	v_mul_f32_e32 v87, v87, v101
	v_cvt_pk_bf16_f32 v87, v87, s0
	v_lshlrev_b32_e32 v101, 16, v169
	v_sub_f32_e32 v100, v101, v100
	v_mul_f32_e32 v82, v100, v82
	v_mul_f32_e32 v100, 0xbfb8aa3b, v83
	v_exp_f32_e32 v100, v100
	v_mul_f32_e32 v82, v148, v82
	v_add_f32_e32 v100, 1.0, v100
	v_rcp_f32_e32 v100, v100
	s_nop 0
	v_mul_f32_e32 v83, v83, v100
	s_nop 0
	v_mul_f32_e32 v82, v83, v82
	v_cvt_pk_bf16_f32 v114, v82, s0
	v_pk_add_f32 v[82:83], v[206:207], v[208:209]
	s_nop 0
	v_pk_add_f32 v[82:83], v[82:83], v[202:203]
	v_mul_f32_e32 v99, 0xbfb8aa3b, v96
	v_pk_add_f32 v[82:83], v[82:83], v[204:205]
	v_exp_f32_e32 v99, v99
	v_pk_mul_f32 v[82:83], v[82:83], s[18:19] op_sel_hi:[1,0]
	v_add_f32_e32 v99, 1.0, v99
	v_fma_f32 v83, -v82, v82, v83
	v_max_f32_e32 v83, 0, v83
	v_add_f32_e32 v83, 0x3727c5ac, v83
	v_cmp_gt_f32_e32 vcc, s25, v83
	v_mul_f32_e32 v98, 0x4b800000, v83
	v_rcp_f32_e32 v99, v99
	v_cndmask_b32_e32 v83, v83, v98, vcc
	v_rsq_f32_e32 v83, v83
	v_mul_f32_e32 v96, v96, v99
	v_mul_f32_e32 v99, 0xbfb8aa3b, v92
	v_mul_f32_e32 v98, 0x45800000, v83
	v_cndmask_b32_e32 v98, v83, v98, vcc
	v_exp_f32_e32 v99, v99
	v_lshlrev_b32_e32 v83, 16, v170
	v_sub_f32_e32 v83, v83, v82
	v_mul_f32_e32 v83, v83, v98
	v_mul_f32_e32 v83, v151, v83
	v_mul_f32_e32 v83, v96, v83
	v_add_f32_e32 v99, 1.0, v99
	v_rcp_f32_e32 v99, v99
	v_cvt_pk_bf16_f32 v83, v83, s0
	v_mul_f32_e32 v92, v92, v99
	v_mul_f32_e32 v99, 0xbfb8aa3b, v88
	v_exp_f32_e32 v99, v99
	v_lshlrev_b32_e32 v96, 16, v171
	v_sub_f32_e32 v96, v96, v82
	v_mul_f32_e32 v96, v96, v98
	v_mul_f32_e32 v96, v150, v96
	v_mul_f32_e32 v92, v92, v96
	v_add_f32_e32 v99, 1.0, v99
	v_rcp_f32_e32 v99, v99
	v_cvt_pk_bf16_f32 v92, v92, s0
	v_mul_f32_e32 v88, v88, v99
	v_lshlrev_b32_e32 v96, 16, v172
	v_sub_f32_e32 v96, v96, v82
	v_mul_f32_e32 v96, v96, v98
	v_mul_f32_e32 v96, v149, v96
	v_mul_f32_e32 v88, v88, v96
	v_cvt_pk_bf16_f32 v88, v88, s0
	v_lshlrev_b32_e32 v96, 16, v173
	v_sub_f32_e32 v82, v96, v82
	v_mul_f32_e32 v96, 0xbfb8aa3b, v84
	v_exp_f32_e32 v96, v96
	v_mul_f32_e32 v82, v82, v98
	v_mul_f32_e32 v82, v148, v82
	v_add_f32_e32 v96, 1.0, v96
	v_rcp_f32_e32 v96, v96
	s_nop 0
	v_mul_f32_e32 v84, v84, v96
	v_mul_f32_e32 v82, v84, v82
	s_nop 0
	s_nop 0
	v_cvt_pk_bf16_f32 v82, v82, s0
	global_store_short v[108:109], v0, off
	global_store_short v[108:109], v90, off offset:32
; __device__ __forceinline__ float bf2f(u16 b) { return __uint_as_float(((unsigned)b) << 16); }
; __device__ __forceinline__ float silu_f(float g) { return g * __builtin_amdgcn_rcpf(1.f + __builtin_amdgcn_exp2f(-g * LOG2E)); }
; template <int EPI>
; __device__ __forceinline__ void epilogue(const Params& p, int pass, int layer, int pm, int pn,
;                                          f32x4 (&acc)[2][2][4][2], const float* xin, float* xout) {
;     ...
;         int tb = t0 + ai * 128 + wr * 64 + m * 16 + fq * 4;
;         asm volatile("" : "+v"(tb));
;         float4 s01[4], s23[4];
;         u16 yv[4][2][2];
; #pragma unroll
;         for (int j = 0; j < 4; ++j) {
;           const float4* sp = (const float4*)(stat + ((long)(tb + j) * 8 + h) * 8);
;           s01[j] = sp[0]; s23[j] = sp[1];
; #pragma unroll
;           for (int bj = 0; bj < 2; ++bj)
; #pragma unroll
;             for (int n = 0; n < 2; ++n)
;               yv[j][bj][n] = Y[(long)(tb + j) * YS + pn * 256 + bj * 128 + wc * 32 + n * 16 + fr];
;         }
; #pragma unroll
;         for (int j = 0; j < 4; ++j) {
;           float s1 = s01[j].x + s01[j].z + s23[j].x + s23[j].z, s2 = s01[j].y + s01[j].w + s23[j].y + s23[j].w;
;           float mu = s1 * (1.f / 512.f);
;           float var = s2 * (1.f / 512.f) - mu * mu;
;           float rstd = rsqrtf(fmaxf(var, 0.f) + 1e-5f);
; #pragma unroll
;           for (int bj = 0; bj < 2; ++bj)
; #pragma unroll
;             for (int n = 0; n < 2; ++n) {
;               float g = acc[ai][bj][m][n][j];
;               float yn = (bf2f(yv[j][bj][n]) - mu) * rstd * gn[bj][n];
;               Y[(long)(tb + j) * YS + pn * 256 + bj * 128 + wc * 32 + n * 16 + fr] = f2bf(silu_f(g) * yn);
	global_store_short v[108:109], v86, off offset:256
	global_store_short v[108:109], v94, off offset:288
	global_store_short v[110:111], v95, off
	global_store_short v[110:111], v91, off offset:32
	global_store_short v[110:111], v87, off offset:256
	global_store_short v[110:111], v114, off offset:288
	global_store_short v[112:113], v83, off
	global_store_short v[112:113], v92, off offset:32
	global_store_short v[112:113], v88, off offset:256
	global_store_short v[112:113], v82, off offset:288
	v_or_b32_e32 v86, 48, v152
	v_pk_add_f32 v[82:83], v[214:215], v[216:217]
	s_nop 0
	v_pk_add_f32 v[82:83], v[82:83], v[210:211]
	s_nop 0
	v_pk_add_f32 v[82:83], v[82:83], v[212:213]
	s_nop 0
	v_pk_mul_f32 v[82:83], v[82:83], s[18:19] op_sel_hi:[1,0]
	s_nop 0
	v_fma_f32 v0, -v82, v82, v83
	v_max_f32_e32 v0, 0, v0
	v_add_f32_e32 v0, 0x3727c5ac, v0
	v_cmp_gt_f32_e32 vcc, s25, v0
	v_mul_f32_e32 v83, 0x4b800000, v0
	s_nop 0
	v_cndmask_b32_e32 v0, v0, v83, vcc
	v_rsq_f32_e32 v0, v0
	s_nop 0
	v_mul_f32_e32 v83, 0x45800000, v0
	v_cndmask_b32_e32 v0, v0, v83, vcc
	v_lshlrev_b32_e32 v83, 16, v174
	v_mul_f32_e32 v84, 0xbfb8aa3b, v97
	v_exp_f32_e32 v84, v84
	v_sub_f32_e32 v83, v83, v82
	v_mul_f32_e32 v83, v83, v0
	v_mul_f32_e32 v83, v151, v83
	v_add_f32_e32 v84, 1.0, v84
	v_rcp_f32_e32 v84, v84
	s_nop 0
	v_mul_f32_e32 v84, v97, v84
	v_mul_f32_e32 v83, v84, v83
	v_mul_f32_e32 v84, 0xbfb8aa3b, v93
	v_exp_f32_e32 v84, v84
	v_cvt_pk_bf16_f32 v83, v83, s0
	global_store_short v[106:107], v83, off
	v_lshlrev_b32_e32 v83, 16, v175
	v_add_f32_e32 v84, 1.0, v84
	v_rcp_f32_e32 v84, v84
	v_sub_f32_e32 v83, v83, v82
	v_mul_f32_e32 v83, v83, v0
	v_mul_f32_e32 v83, v150, v83
	v_mul_f32_e32 v84, v93, v84
	v_mul_f32_e32 v83, v84, v83
	v_mul_f32_e32 v84, 0xbfb8aa3b, v89
	v_exp_f32_e32 v84, v84
	v_cvt_pk_bf16_f32 v83, v83, s0
	global_store_short v[106:107], v83, off offset:32
	v_lshlrev_b32_e32 v83, 16, v176
	v_add_f32_e32 v84, 1.0, v84
	v_rcp_f32_e32 v84, v84
	v_sub_f32_e32 v83, v83, v82
	v_mul_f32_e32 v83, v83, v0
	v_mul_f32_e32 v83, v149, v83
	v_mul_f32_e32 v84, v89, v84
	v_mul_f32_e32 v83, v84, v83
	v_cvt_pk_bf16_f32 v83, v83, s0
	global_store_short v[106:107], v83, off offset:256
	v_lshlrev_b32_e32 v83, 16, v177
	v_sub_f32_e32 v82, v83, v82
	v_mul_f32_e32 v0, v82, v0
	v_mul_f32_e32 v82, 0xbfb8aa3b, v85
	v_exp_f32_e32 v82, v82
	v_mul_f32_e32 v0, v148, v0
	v_add_f32_e32 v82, 1.0, v82
	v_rcp_f32_e32 v82, v82
	s_nop 0
	v_mul_f32_e32 v82, v85, v82
	v_mul_f32_e32 v0, v82, v0
	v_cvt_pk_bf16_f32 v0, v0, s0
	global_store_short v[106:107], v0, off offset:288
	s_nop 0
	v_ashrrev_i32_e32 v87, 31, v86
	v_lshlrev_b64 v[82:83], 8, v[86:87]
	v_lshl_add_u64 v[88:89], s[16:17], 0, v[82:83]
	global_load_dwordx4 v[98:101], v[88:89], off offset:16
	global_load_dwordx4 v[102:105], v[88:89], off
	v_mad_i64_i32 v[92:93], s[14:15], v86, s24, v[138:139]
	global_load_ushort v178, v[92:93], off
	global_load_ushort v179, v[92:93], off offset:32
	global_load_ushort v180, v[92:93], off offset:256
	global_load_ushort v181, v[92:93], off offset:288
	v_add_u32_e32 v82, 1, v86
	v_ashrrev_i32_e32 v83, 31, v82
	v_lshlrev_b64 v[84:85], 8, v[82:83]
	v_lshl_add_u64 v[84:85], s[16:17], 0, v[84:85]
	global_load_dwordx4 v[194:197], v[84:85], off offset:16
	global_load_dwordx4 v[198:201], v[84:85], off
	v_mad_i64_i32 v[94:95], s[14:15], v82, s24, v[138:139]
	global_load_ushort v182, v[94:95], off
	global_load_ushort v183, v[94:95], off offset:32
	global_load_ushort v184, v[94:95], off offset:256
	global_load_ushort v185, v[94:95], off offset:288
	v_add_u32_e32 v90, 2, v86
	v_ashrrev_i32_e32 v91, 31, v90
	v_lshlrev_b64 v[82:83], 8, v[90:91]
	v_lshl_add_u64 v[82:83], s[16:17], 0, v[82:83]
	global_load_dwordx4 v[202:205], v[82:83], off offset:16
	global_load_dwordx4 v[206:209], v[82:83], off
	v_mad_i64_i32 v[96:97], s[14:15], v90, s24, v[138:139]
	global_load_ushort v186, v[96:97], off
	global_load_ushort v187, v[96:97], off offset:32
	global_load_ushort v188, v[96:97], off offset:256
	global_load_ushort v189, v[96:97], off offset:288
	v_add_u32_e32 v90, 3, v86
	v_ashrrev_i32_e32 v91, 31, v90
	v_lshlrev_b64 v[86:87], 8, v[90:91]
	v_lshl_add_u64 v[86:87], s[16:17], 0, v[86:87]
	global_load_dwordx4 v[210:213], v[86:87], off offset:16
	global_load_dwordx4 v[214:217], v[86:87], off
	v_mad_i64_i32 v[90:91], s[14:15], v90, s24, v[138:139]
	global_load_ushort v190, v[90:91], off
	global_load_ushort v191, v[90:91], off offset:32
	global_load_ushort v192, v[90:91], off offset:256
	global_load_ushort v193, v[90:91], off offset:288
	s_waitcnt vmcnt(0)
; __device__ __forceinline__ float bf2f(u16 b) { return __uint_as_float(((unsigned)b) << 16); }
; __device__ __forceinline__ float silu_f(float g) { return g * __builtin_amdgcn_rcpf(1.f + __builtin_amdgcn_exp2f(-g * LOG2E)); }
; template <int EPI>
; __device__ __forceinline__ void epilogue(const Params& p, int pass, int layer, int pm, int pn,
;                                          f32x4 (&acc)[2][2][4][2], const float* xin, float* xout) {
;     ...
; #pragma unroll
;         for (int j = 0; j < 4; ++j) {
;           const float4* sp = (const float4*)(stat + ((long)(tb + j) * 8 + h) * 8);
;           s01[j] = sp[0]; s23[j] = sp[1];
; #pragma unroll
;           for (int bj = 0; bj < 2; ++bj)
; #pragma unroll
;             for (int n = 0; n < 2; ++n)
;               yv[j][bj][n] = Y[(long)(tb + j) * YS + pn * 256 + bj * 128 + wc * 32 + n * 16 + fr];
;         }
; #pragma unroll
;         for (int j = 0; j < 4; ++j) {
;           float s1 = s01[j].x + s01[j].z + s23[j].x + s23[j].z, s2 = s01[j].y + s01[j].w + s23[j].y + s23[j].w;
;           float mu = s1 * (1.f / 512.f);
;           float var = s2 * (1.f / 512.f) - mu * mu;
;           float rstd = rsqrtf(fmaxf(var, 0.f) + 1e-5f);
; #pragma unroll
;           for (int bj = 0; bj < 2; ++bj)
; #pragma unroll
;             for (int n = 0; n < 2; ++n) {
;               float g = acc[ai][bj][m][n][j];
;               float yn = (bf2f(yv[j][bj][n]) - mu) * rstd * gn[bj][n];
;               Y[(long)(tb + j) * YS + pn * 256 + bj * 128 + wc * 32 + n * 16 + fr] = f2bf(silu_f(g) * yn);
	v_pk_add_f32 v[88:89], v[102:103], v[104:105]
	s_nop 0
	v_pk_add_f32 v[88:89], v[88:89], v[98:99]
	v_mul_f32_e32 v98, 0xbfb8aa3b, v78
	v_pk_add_f32 v[88:89], v[88:89], v[100:101]
	v_exp_f32_e32 v98, v98
	v_pk_mul_f32 v[88:89], v[88:89], s[18:19] op_sel_hi:[1,0]
	v_add_f32_e32 v98, 1.0, v98
	v_fma_f32 v0, -v88, v88, v89
	v_max_f32_e32 v0, 0, v0
	v_add_f32_e32 v0, 0x3727c5ac, v0
	v_cmp_gt_f32_e32 vcc, s25, v0
	v_mul_f32_e32 v89, 0x4b800000, v0
	v_rcp_f32_e32 v98, v98
	v_cndmask_b32_e32 v0, v0, v89, vcc
	v_rsq_f32_e32 v0, v0
	v_mul_f32_e32 v78, v78, v98
	v_mul_f32_e32 v98, 0xbfb8aa3b, v74
	v_mul_f32_e32 v89, 0x45800000, v0
	v_cndmask_b32_e32 v89, v0, v89, vcc
	v_exp_f32_e32 v98, v98
	v_lshlrev_b32_e32 v0, 16, v178
	v_sub_f32_e32 v0, v0, v88
	v_mul_f32_e32 v0, v0, v89
	v_mul_f32_e32 v0, v151, v0
	v_mul_f32_e32 v0, v78, v0
	v_add_f32_e32 v98, 1.0, v98
	v_rcp_f32_e32 v98, v98
	v_cvt_pk_bf16_f32 v0, v0, s0
	v_mul_f32_e32 v74, v74, v98
	v_mul_f32_e32 v98, 0xbfb8aa3b, v70
	v_exp_f32_e32 v98, v98
	v_lshlrev_b32_e32 v78, 16, v179
	v_sub_f32_e32 v78, v78, v88
	v_mul_f32_e32 v78, v78, v89
	v_mul_f32_e32 v78, v150, v78
	v_mul_f32_e32 v74, v74, v78
	v_add_f32_e32 v98, 1.0, v98
	v_rcp_f32_e32 v98, v98
	v_cvt_pk_bf16_f32 v74, v74, s0
	v_mul_f32_e32 v70, v70, v98
	v_lshlrev_b32_e32 v78, 16, v180
	v_sub_f32_e32 v78, v78, v88
	v_mul_f32_e32 v78, v78, v89
	v_mul_f32_e32 v78, v149, v78
	v_mul_f32_e32 v70, v70, v78
	v_cvt_pk_bf16_f32 v70, v70, s0
	v_lshlrev_b32_e32 v78, 16, v181
	v_sub_f32_e32 v78, v78, v88
	v_mul_f32_e32 v88, 0xbfb8aa3b, v66
	v_exp_f32_e32 v88, v88
	v_pk_add_f32 v[84:85], v[198:199], v[200:201]
	v_mul_f32_e32 v78, v78, v89
	v_pk_add_f32 v[84:85], v[84:85], v[194:195]
	v_add_f32_e32 v88, 1.0, v88
	v_rcp_f32_e32 v88, v88
	v_mul_f32_e32 v78, v148, v78
	v_pk_add_f32 v[84:85], v[84:85], v[196:197]
	v_mul_f32_e32 v66, v66, v88
	v_mul_f32_e32 v66, v66, v78
	v_pk_mul_f32 v[84:85], v[84:85], s[18:19] op_sel_hi:[1,0]
	v_cvt_pk_bf16_f32 v78, v66, s0
	v_fma_f32 v66, -v84, v84, v85
	v_max_f32_e32 v66, 0, v66
	v_add_f32_e32 v66, 0x3727c5ac, v66
	v_cmp_gt_f32_e32 vcc, s25, v66
	v_mul_f32_e32 v85, 0x4b800000, v66
	v_mul_f32_e32 v88, 0xbfb8aa3b, v79
	v_cndmask_b32_e32 v66, v66, v85, vcc
	v_rsq_f32_e32 v66, v66
	v_exp_f32_e32 v88, v88
	v_mul_f32_e32 v85, 0x45800000, v66
	v_cndmask_b32_e32 v66, v66, v85, vcc
	v_add_f32_e32 v88, 1.0, v88
	v_rcp_f32_e32 v88, v88
	v_lshlrev_b32_e32 v85, 16, v182
	v_sub_f32_e32 v85, v85, v84
	v_mul_f32_e32 v85, v85, v66
	v_mul_f32_e32 v85, v151, v85
	v_mul_f32_e32 v79, v79, v88
	v_mul_f32_e32 v79, v79, v85
	v_mul_f32_e32 v88, 0xbfb8aa3b, v75
	v_exp_f32_e32 v88, v88
	v_cvt_pk_bf16_f32 v79, v79, s0
	v_add_f32_e32 v88, 1.0, v88
	v_rcp_f32_e32 v88, v88
	v_lshlrev_b32_e32 v85, 16, v183
	v_sub_f32_e32 v85, v85, v84
	v_mul_f32_e32 v85, v85, v66
	v_mul_f32_e32 v85, v150, v85
	v_mul_f32_e32 v75, v75, v88
	v_mul_f32_e32 v75, v75, v85
	v_mul_f32_e32 v88, 0xbfb8aa3b, v71
	v_exp_f32_e32 v88, v88
	v_cvt_pk_bf16_f32 v75, v75, s0
	v_add_f32_e32 v88, 1.0, v88
	v_rcp_f32_e32 v88, v88
	v_lshlrev_b32_e32 v85, 16, v184
	v_sub_f32_e32 v85, v85, v84
	v_mul_f32_e32 v85, v85, v66
	v_mul_f32_e32 v85, v149, v85
	v_mul_f32_e32 v71, v71, v88
	v_mul_f32_e32 v71, v71, v85
	v_cvt_pk_bf16_f32 v71, v71, s0
	v_lshlrev_b32_e32 v85, 16, v185
	v_sub_f32_e32 v84, v85, v84
	v_mul_f32_e32 v66, v84, v66
	v_mul_f32_e32 v84, 0xbfb8aa3b, v67
	v_exp_f32_e32 v84, v84
	v_mul_f32_e32 v66, v148, v66
	v_add_f32_e32 v84, 1.0, v84
	v_rcp_f32_e32 v84, v84
	s_nop 0
	v_mul_f32_e32 v67, v67, v84
	s_nop 0
	v_mul_f32_e32 v66, v67, v66
	v_cvt_pk_bf16_f32 v98, v66, s0
	v_pk_add_f32 v[66:67], v[206:207], v[208:209]
	s_nop 0
	v_pk_add_f32 v[66:67], v[66:67], v[202:203]
	v_mul_f32_e32 v83, 0xbfb8aa3b, v80
	v_pk_add_f32 v[66:67], v[66:67], v[204:205]
	v_exp_f32_e32 v83, v83
	v_pk_mul_f32 v[66:67], v[66:67], s[18:19] op_sel_hi:[1,0]
	v_add_f32_e32 v83, 1.0, v83
	v_fma_f32 v67, -v66, v66, v67
	v_max_f32_e32 v67, 0, v67
	v_add_f32_e32 v67, 0x3727c5ac, v67
	v_cmp_gt_f32_e32 vcc, s25, v67
	v_mul_f32_e32 v82, 0x4b800000, v67
	v_rcp_f32_e32 v83, v83
	v_cndmask_b32_e32 v67, v67, v82, vcc
	v_rsq_f32_e32 v67, v67
	v_mul_f32_e32 v80, v80, v83
	v_mul_f32_e32 v83, 0xbfb8aa3b, v76
	v_mul_f32_e32 v82, 0x45800000, v67
	v_cndmask_b32_e32 v82, v67, v82, vcc
	v_exp_f32_e32 v83, v83
	v_lshlrev_b32_e32 v67, 16, v186
	v_sub_f32_e32 v67, v67, v66
	v_mul_f32_e32 v67, v67, v82
	v_mul_f32_e32 v67, v151, v67
	v_mul_f32_e32 v67, v80, v67
	v_add_f32_e32 v83, 1.0, v83
	v_rcp_f32_e32 v83, v83
	v_cvt_pk_bf16_f32 v67, v67, s0
	v_mul_f32_e32 v76, v76, v83
	v_mul_f32_e32 v83, 0xbfb8aa3b, v72
	v_exp_f32_e32 v83, v83
	v_lshlrev_b32_e32 v80, 16, v187
	v_sub_f32_e32 v80, v80, v66
	v_mul_f32_e32 v80, v80, v82
	v_mul_f32_e32 v80, v150, v80
	v_mul_f32_e32 v76, v76, v80
	v_add_f32_e32 v83, 1.0, v83
	v_rcp_f32_e32 v83, v83
	v_cvt_pk_bf16_f32 v76, v76, s0
	v_mul_f32_e32 v72, v72, v83
	v_lshlrev_b32_e32 v80, 16, v188
	v_sub_f32_e32 v80, v80, v66
	v_mul_f32_e32 v80, v80, v82
	v_mul_f32_e32 v80, v149, v80
	v_mul_f32_e32 v72, v72, v80
	v_cvt_pk_bf16_f32 v72, v72, s0
	v_lshlrev_b32_e32 v80, 16, v189
	v_sub_f32_e32 v66, v80, v66
	v_mul_f32_e32 v80, 0xbfb8aa3b, v68
	v_exp_f32_e32 v80, v80
	v_mul_f32_e32 v66, v66, v82
	v_mul_f32_e32 v66, v148, v66
	v_add_f32_e32 v80, 1.0, v80
	v_rcp_f32_e32 v80, v80
	s_nop 0
	v_mul_f32_e32 v68, v68, v80
	v_mul_f32_e32 v66, v68, v66
	s_nop 0
	s_nop 0
	v_cvt_pk_bf16_f32 v66, v66, s0
	global_store_short v[92:93], v0, off
	global_store_short v[92:93], v74, off offset:32
	global_store_short v[92:93], v70, off offset:256
	global_store_short v[92:93], v78, off offset:288
	global_store_short v[94:95], v79, off
; __device__ __forceinline__ float bf2f(u16 b) { return __uint_as_float(((unsigned)b) << 16); }
; __device__ __forceinline__ float silu_f(float g) { return g * __builtin_amdgcn_rcpf(1.f + __builtin_amdgcn_exp2f(-g * LOG2E)); }
; template <int EPI>
; __device__ __forceinline__ void epilogue(const Params& p, int pass, int layer, int pm, int pn,
;                                          f32x4 (&acc)[2][2][4][2], const float* xin, float* xout) {
;     ...
;         int tb = t0 + ai * 128 + wr * 64 + m * 16 + fq * 4;
;         asm volatile("" : "+v"(tb));
;         float4 s01[4], s23[4];
;         u16 yv[4][2][2];
; #pragma unroll
;         for (int j = 0; j < 4; ++j) {
;           const float4* sp = (const float4*)(stat + ((long)(tb + j) * 8 + h) * 8);
;           s01[j] = sp[0]; s23[j] = sp[1];
; #pragma unroll
;           for (int bj = 0; bj < 2; ++bj)
; #pragma unroll
;             for (int n = 0; n < 2; ++n)
;               yv[j][bj][n] = Y[(long)(tb + j) * YS + pn * 256 + bj * 128 + wc * 32 + n * 16 + fr];
;         }
; #pragma unroll
;         for (int j = 0; j < 4; ++j) {
;           float s1 = s01[j].x + s01[j].z + s23[j].x + s23[j].z, s2 = s01[j].y + s01[j].w + s23[j].y + s23[j].w;
;           float mu = s1 * (1.f / 512.f);
;           float var = s2 * (1.f / 512.f) - mu * mu;
;           float rstd = rsqrtf(fmaxf(var, 0.f) + 1e-5f);
; #pragma unroll
;           for (int bj = 0; bj < 2; ++bj)
; #pragma unroll
;             for (int n = 0; n < 2; ++n) {
;               float g = acc[ai][bj][m][n][j];
;               float yn = (bf2f(yv[j][bj][n]) - mu) * rstd * gn[bj][n];
;               Y[(long)(tb + j) * YS + pn * 256 + bj * 128 + wc * 32 + n * 16 + fr] = f2bf(silu_f(g) * yn);
	global_store_short v[94:95], v75, off offset:32
	global_store_short v[94:95], v71, off offset:256
	global_store_short v[94:95], v98, off offset:288
	global_store_short v[96:97], v67, off
	global_store_short v[96:97], v76, off offset:32
	global_store_short v[96:97], v72, off offset:256
	global_store_short v[96:97], v66, off offset:288
	v_add_u32_e32 v70, 0x80, v152
	v_pk_add_f32 v[66:67], v[214:215], v[216:217]
	s_nop 0
	v_pk_add_f32 v[66:67], v[66:67], v[210:211]
	s_nop 0
	v_pk_add_f32 v[66:67], v[66:67], v[212:213]
	s_nop 0
	v_pk_mul_f32 v[66:67], v[66:67], s[18:19] op_sel_hi:[1,0]
	s_nop 0
	v_fma_f32 v0, -v66, v66, v67
	v_max_f32_e32 v0, 0, v0
	v_add_f32_e32 v0, 0x3727c5ac, v0
	v_cmp_gt_f32_e32 vcc, s25, v0
	v_mul_f32_e32 v67, 0x4b800000, v0
	s_nop 0
	v_cndmask_b32_e32 v0, v0, v67, vcc
	v_rsq_f32_e32 v0, v0
	s_nop 0
	v_mul_f32_e32 v67, 0x45800000, v0
	v_cndmask_b32_e32 v0, v0, v67, vcc
	v_lshlrev_b32_e32 v67, 16, v190
	v_mul_f32_e32 v68, 0xbfb8aa3b, v81
	v_exp_f32_e32 v68, v68
	v_sub_f32_e32 v67, v67, v66
	v_mul_f32_e32 v67, v67, v0
	v_mul_f32_e32 v67, v151, v67
	v_add_f32_e32 v68, 1.0, v68
	v_rcp_f32_e32 v68, v68
	s_nop 0
	v_mul_f32_e32 v68, v81, v68
	v_mul_f32_e32 v67, v68, v67
	v_mul_f32_e32 v68, 0xbfb8aa3b, v77
	v_exp_f32_e32 v68, v68
	v_cvt_pk_bf16_f32 v67, v67, s0
	global_store_short v[90:91], v67, off
	v_lshlrev_b32_e32 v67, 16, v191
	v_add_f32_e32 v68, 1.0, v68
	v_rcp_f32_e32 v68, v68
	v_sub_f32_e32 v67, v67, v66
	v_mul_f32_e32 v67, v67, v0
	v_mul_f32_e32 v67, v150, v67
	v_mul_f32_e32 v68, v77, v68
	v_mul_f32_e32 v67, v68, v67
	v_mul_f32_e32 v68, 0xbfb8aa3b, v73
	v_exp_f32_e32 v68, v68
	v_cvt_pk_bf16_f32 v67, v67, s0
	global_store_short v[90:91], v67, off offset:32
	v_lshlrev_b32_e32 v67, 16, v192
	v_add_f32_e32 v68, 1.0, v68
	v_rcp_f32_e32 v68, v68
	v_sub_f32_e32 v67, v67, v66
	v_mul_f32_e32 v67, v67, v0
	v_mul_f32_e32 v67, v149, v67
	v_mul_f32_e32 v68, v73, v68
	v_mul_f32_e32 v67, v68, v67
	v_cvt_pk_bf16_f32 v67, v67, s0
	global_store_short v[90:91], v67, off offset:256
	v_lshlrev_b32_e32 v67, 16, v193
	v_sub_f32_e32 v66, v67, v66
	v_mul_f32_e32 v0, v66, v0
	v_mul_f32_e32 v66, 0xbfb8aa3b, v69
	v_exp_f32_e32 v66, v66
	v_mul_f32_e32 v0, v148, v0
	v_add_f32_e32 v66, 1.0, v66
	v_rcp_f32_e32 v66, v66
	s_nop 0
	v_mul_f32_e32 v66, v69, v66
	v_mul_f32_e32 v0, v66, v0
	v_cvt_pk_bf16_f32 v0, v0, s0
	global_store_short v[90:91], v0, off offset:288
	s_nop 0
	v_ashrrev_i32_e32 v71, 31, v70
	v_lshlrev_b64 v[66:67], 8, v[70:71]
	v_lshl_add_u64 v[72:73], s[16:17], 0, v[66:67]
	global_load_dwordx4 v[82:85], v[72:73], off offset:16
	global_load_dwordx4 v[86:89], v[72:73], off
	v_mad_i64_i32 v[76:77], s[14:15], v70, s24, v[138:139]
	global_load_ushort v162, v[76:77], off
	global_load_ushort v163, v[76:77], off offset:32
	global_load_ushort v164, v[76:77], off offset:256
	global_load_ushort v165, v[76:77], off offset:288
	v_add_u32_e32 v66, 1, v70
	v_ashrrev_i32_e32 v67, 31, v66
	v_lshlrev_b64 v[68:69], 8, v[66:67]
	v_lshl_add_u64 v[68:69], s[16:17], 0, v[68:69]
	global_load_dwordx4 v[194:197], v[68:69], off offset:16
	global_load_dwordx4 v[198:201], v[68:69], off
	v_mad_i64_i32 v[78:79], s[14:15], v66, s24, v[138:139]
	global_load_ushort v166, v[78:79], off
	global_load_ushort v167, v[78:79], off offset:32
	global_load_ushort v168, v[78:79], off offset:256
	global_load_ushort v169, v[78:79], off offset:288
	v_add_u32_e32 v74, 2, v70
	v_ashrrev_i32_e32 v75, 31, v74
	v_lshlrev_b64 v[66:67], 8, v[74:75]
	v_lshl_add_u64 v[66:67], s[16:17], 0, v[66:67]
	global_load_dwordx4 v[202:205], v[66:67], off offset:16
	global_load_dwordx4 v[206:209], v[66:67], off
	v_mad_i64_i32 v[80:81], s[14:15], v74, s24, v[138:139]
	global_load_ushort v170, v[80:81], off
	global_load_ushort v171, v[80:81], off offset:32
	global_load_ushort v172, v[80:81], off offset:256
	global_load_ushort v173, v[80:81], off offset:288
	v_add_u32_e32 v74, 3, v70
	v_ashrrev_i32_e32 v75, 31, v74
	v_lshlrev_b64 v[70:71], 8, v[74:75]
	v_lshl_add_u64 v[70:71], s[16:17], 0, v[70:71]
	global_load_dwordx4 v[210:213], v[70:71], off offset:16
	global_load_dwordx4 v[214:217], v[70:71], off
	v_mad_i64_i32 v[74:75], s[14:15], v74, s24, v[138:139]
	global_load_ushort v174, v[74:75], off
	global_load_ushort v175, v[74:75], off offset:32
	global_load_ushort v176, v[74:75], off offset:256
	global_load_ushort v177, v[74:75], off offset:288
	s_waitcnt vmcnt(0)
; __device__ __forceinline__ float bf2f(u16 b) { return __uint_as_float(((unsigned)b) << 16); }
; __device__ __forceinline__ float silu_f(float g) { return g * __builtin_amdgcn_rcpf(1.f + __builtin_amdgcn_exp2f(-g * LOG2E)); }
; template <int EPI>
; __device__ __forceinline__ void epilogue(const Params& p, int pass, int layer, int pm, int pn,
;                                          f32x4 (&acc)[2][2][4][2], const float* xin, float* xout) {
;     ...
; #pragma unroll
;         for (int j = 0; j < 4; ++j) {
;           const float4* sp = (const float4*)(stat + ((long)(tb + j) * 8 + h) * 8);
;           s01[j] = sp[0]; s23[j] = sp[1];
; #pragma unroll
;           for (int bj = 0; bj < 2; ++bj)
; #pragma unroll
;             for (int n = 0; n < 2; ++n)
;               yv[j][bj][n] = Y[(long)(tb + j) * YS + pn * 256 + bj * 128 + wc * 32 + n * 16 + fr];
;         }
; #pragma unroll
;         for (int j = 0; j < 4; ++j) {
;           float s1 = s01[j].x + s01[j].z + s23[j].x + s23[j].z, s2 = s01[j].y + s01[j].w + s23[j].y + s23[j].w;
;           float mu = s1 * (1.f / 512.f);
;           float var = s2 * (1.f / 512.f) - mu * mu;
;           float rstd = rsqrtf(fmaxf(var, 0.f) + 1e-5f);
; #pragma unroll
;           for (int bj = 0; bj < 2; ++bj)
; #pragma unroll
;             for (int n = 0; n < 2; ++n) {
;               float g = acc[ai][bj][m][n][j];
;               float yn = (bf2f(yv[j][bj][n]) - mu) * rstd * gn[bj][n];
;               Y[(long)(tb + j) * YS + pn * 256 + bj * 128 + wc * 32 + n * 16 + fr] = f2bf(silu_f(g) * yn);
	v_pk_add_f32 v[72:73], v[86:87], v[88:89]
	s_nop 0
	v_pk_add_f32 v[72:73], v[72:73], v[82:83]
	v_mul_f32_e32 v82, 0xbfb8aa3b, v62
	v_pk_add_f32 v[72:73], v[72:73], v[84:85]
	v_exp_f32_e32 v82, v82
	v_pk_mul_f32 v[72:73], v[72:73], s[18:19] op_sel_hi:[1,0]
	v_add_f32_e32 v82, 1.0, v82
	v_fma_f32 v0, -v72, v72, v73
	v_max_f32_e32 v0, 0, v0
	v_add_f32_e32 v0, 0x3727c5ac, v0
	v_cmp_gt_f32_e32 vcc, s25, v0
	v_mul_f32_e32 v73, 0x4b800000, v0
	v_rcp_f32_e32 v82, v82
	v_cndmask_b32_e32 v0, v0, v73, vcc
	v_rsq_f32_e32 v0, v0
	v_mul_f32_e32 v62, v62, v82
	v_mul_f32_e32 v82, 0xbfb8aa3b, v58
	v_mul_f32_e32 v73, 0x45800000, v0
	v_cndmask_b32_e32 v73, v0, v73, vcc
	v_exp_f32_e32 v82, v82
	v_lshlrev_b32_e32 v0, 16, v162
	v_sub_f32_e32 v0, v0, v72
	v_mul_f32_e32 v0, v0, v73
	v_mul_f32_e32 v0, v151, v0
	v_mul_f32_e32 v0, v62, v0
	v_add_f32_e32 v82, 1.0, v82
	v_rcp_f32_e32 v82, v82
	v_cvt_pk_bf16_f32 v0, v0, s0
	v_mul_f32_e32 v58, v58, v82
	v_mul_f32_e32 v82, 0xbfb8aa3b, v54
	v_exp_f32_e32 v82, v82
	v_lshlrev_b32_e32 v62, 16, v163
	v_sub_f32_e32 v62, v62, v72
	v_mul_f32_e32 v62, v62, v73
	v_mul_f32_e32 v62, v150, v62
	v_mul_f32_e32 v58, v58, v62
	v_add_f32_e32 v82, 1.0, v82
	v_rcp_f32_e32 v82, v82
	v_cvt_pk_bf16_f32 v58, v58, s0
	v_mul_f32_e32 v54, v54, v82
	v_lshlrev_b32_e32 v62, 16, v164
	v_sub_f32_e32 v62, v62, v72
	v_mul_f32_e32 v62, v62, v73
	v_mul_f32_e32 v62, v149, v62
	v_mul_f32_e32 v54, v54, v62
	v_cvt_pk_bf16_f32 v54, v54, s0
	v_lshlrev_b32_e32 v62, 16, v165
	v_sub_f32_e32 v62, v62, v72
	v_mul_f32_e32 v72, 0xbfb8aa3b, v50
	v_exp_f32_e32 v72, v72
	v_pk_add_f32 v[68:69], v[198:199], v[200:201]
	v_mul_f32_e32 v62, v62, v73
	v_pk_add_f32 v[68:69], v[68:69], v[194:195]
	v_add_f32_e32 v72, 1.0, v72
	v_rcp_f32_e32 v72, v72
	v_mul_f32_e32 v62, v148, v62
	v_pk_add_f32 v[68:69], v[68:69], v[196:197]
	v_mul_f32_e32 v50, v50, v72
	v_mul_f32_e32 v50, v50, v62
	v_pk_mul_f32 v[68:69], v[68:69], s[18:19] op_sel_hi:[1,0]
	v_cvt_pk_bf16_f32 v62, v50, s0
	v_fma_f32 v50, -v68, v68, v69
	v_max_f32_e32 v50, 0, v50
	v_add_f32_e32 v50, 0x3727c5ac, v50
	v_cmp_gt_f32_e32 vcc, s25, v50
	v_mul_f32_e32 v69, 0x4b800000, v50
	v_mul_f32_e32 v72, 0xbfb8aa3b, v63
	v_cndmask_b32_e32 v50, v50, v69, vcc
	v_rsq_f32_e32 v50, v50
	v_exp_f32_e32 v72, v72
	v_mul_f32_e32 v69, 0x45800000, v50
	v_cndmask_b32_e32 v50, v50, v69, vcc
	v_add_f32_e32 v72, 1.0, v72
	v_rcp_f32_e32 v72, v72
	v_lshlrev_b32_e32 v69, 16, v166
	v_sub_f32_e32 v69, v69, v68
	v_mul_f32_e32 v69, v69, v50
	v_mul_f32_e32 v69, v151, v69
	v_mul_f32_e32 v63, v63, v72
	v_mul_f32_e32 v63, v63, v69
	v_mul_f32_e32 v72, 0xbfb8aa3b, v59
	v_exp_f32_e32 v72, v72
	v_cvt_pk_bf16_f32 v63, v63, s0
	v_add_f32_e32 v72, 1.0, v72
	v_rcp_f32_e32 v72, v72
	v_lshlrev_b32_e32 v69, 16, v167
	v_sub_f32_e32 v69, v69, v68
	v_mul_f32_e32 v69, v69, v50
	v_mul_f32_e32 v69, v150, v69
	v_mul_f32_e32 v59, v59, v72
	v_mul_f32_e32 v59, v59, v69
	v_mul_f32_e32 v72, 0xbfb8aa3b, v55
	v_exp_f32_e32 v72, v72
	v_cvt_pk_bf16_f32 v59, v59, s0
	v_add_f32_e32 v72, 1.0, v72
	v_rcp_f32_e32 v72, v72
	v_lshlrev_b32_e32 v69, 16, v168
	v_sub_f32_e32 v69, v69, v68
	v_mul_f32_e32 v69, v69, v50
	v_mul_f32_e32 v69, v149, v69
	v_mul_f32_e32 v55, v55, v72
	v_mul_f32_e32 v55, v55, v69
	v_cvt_pk_bf16_f32 v55, v55, s0
	v_lshlrev_b32_e32 v69, 16, v169
	v_sub_f32_e32 v68, v69, v68
	v_mul_f32_e32 v50, v68, v50
	v_mul_f32_e32 v68, 0xbfb8aa3b, v51
	v_exp_f32_e32 v68, v68
	v_mul_f32_e32 v50, v148, v50
	v_add_f32_e32 v68, 1.0, v68
	v_rcp_f32_e32 v68, v68
	s_nop 0
	v_mul_f32_e32 v51, v51, v68
	s_nop 0
	v_mul_f32_e32 v50, v51, v50
	v_cvt_pk_bf16_f32 v82, v50, s0
	v_pk_add_f32 v[50:51], v[206:207], v[208:209]
	s_nop 0
	v_pk_add_f32 v[50:51], v[50:51], v[202:203]
	v_mul_f32_e32 v67, 0xbfb8aa3b, v64
	v_pk_add_f32 v[50:51], v[50:51], v[204:205]
	v_exp_f32_e32 v67, v67
	v_pk_mul_f32 v[50:51], v[50:51], s[18:19] op_sel_hi:[1,0]
	v_add_f32_e32 v67, 1.0, v67
	v_fma_f32 v51, -v50, v50, v51
	v_max_f32_e32 v51, 0, v51
	v_add_f32_e32 v51, 0x3727c5ac, v51
	v_cmp_gt_f32_e32 vcc, s25, v51
	v_mul_f32_e32 v66, 0x4b800000, v51
	v_rcp_f32_e32 v67, v67
	v_cndmask_b32_e32 v51, v51, v66, vcc
	v_rsq_f32_e32 v51, v51
	v_mul_f32_e32 v64, v64, v67
	v_mul_f32_e32 v67, 0xbfb8aa3b, v60
	v_mul_f32_e32 v66, 0x45800000, v51
	v_cndmask_b32_e32 v66, v51, v66, vcc
	v_exp_f32_e32 v67, v67
	v_lshlrev_b32_e32 v51, 16, v170
	v_sub_f32_e32 v51, v51, v50
	v_mul_f32_e32 v51, v51, v66
	v_mul_f32_e32 v51, v151, v51
	v_mul_f32_e32 v51, v64, v51
	v_add_f32_e32 v67, 1.0, v67
	v_rcp_f32_e32 v67, v67
	v_cvt_pk_bf16_f32 v51, v51, s0
	v_mul_f32_e32 v60, v60, v67
	v_mul_f32_e32 v67, 0xbfb8aa3b, v56
	v_exp_f32_e32 v67, v67
	v_lshlrev_b32_e32 v64, 16, v171
	v_sub_f32_e32 v64, v64, v50
	v_mul_f32_e32 v64, v64, v66
	v_mul_f32_e32 v64, v150, v64
	v_mul_f32_e32 v60, v60, v64
	v_add_f32_e32 v67, 1.0, v67
	v_rcp_f32_e32 v67, v67
	v_cvt_pk_bf16_f32 v60, v60, s0
	v_mul_f32_e32 v56, v56, v67
	v_lshlrev_b32_e32 v64, 16, v172
	v_sub_f32_e32 v64, v64, v50
	v_mul_f32_e32 v64, v64, v66
	v_mul_f32_e32 v64, v149, v64
	v_mul_f32_e32 v56, v56, v64
	v_cvt_pk_bf16_f32 v56, v56, s0
	v_lshlrev_b32_e32 v64, 16, v173
	v_sub_f32_e32 v50, v64, v50
	v_mul_f32_e32 v64, 0xbfb8aa3b, v52
	v_exp_f32_e32 v64, v64
	v_mul_f32_e32 v50, v50, v66
	v_mul_f32_e32 v50, v148, v50
	v_add_f32_e32 v64, 1.0, v64
	v_rcp_f32_e32 v64, v64
	s_nop 0
	v_mul_f32_e32 v52, v52, v64
	v_mul_f32_e32 v50, v52, v50
	s_nop 0
	s_nop 0
	v_cvt_pk_bf16_f32 v50, v50, s0
	global_store_short v[76:77], v0, off
	global_store_short v[76:77], v58, off offset:32
	global_store_short v[76:77], v54, off offset:256
	global_store_short v[76:77], v62, off offset:288
	global_store_short v[78:79], v63, off
; __device__ __forceinline__ float bf2f(u16 b) { return __uint_as_float(((unsigned)b) << 16); }
; __device__ __forceinline__ float silu_f(float g) { return g * __builtin_amdgcn_rcpf(1.f + __builtin_amdgcn_exp2f(-g * LOG2E)); }
; template <int EPI>
; __device__ __forceinline__ void epilogue(const Params& p, int pass, int layer, int pm, int pn,
;                                          f32x4 (&acc)[2][2][4][2], const float* xin, float* xout) {
;     ...
;         int tb = t0 + ai * 128 + wr * 64 + m * 16 + fq * 4;
;         asm volatile("" : "+v"(tb));
;         float4 s01[4], s23[4];
;         u16 yv[4][2][2];
; #pragma unroll
;         for (int j = 0; j < 4; ++j) {
;           const float4* sp = (const float4*)(stat + ((long)(tb + j) * 8 + h) * 8);
;           s01[j] = sp[0]; s23[j] = sp[1];
; #pragma unroll
;           for (int bj = 0; bj < 2; ++bj)
; #pragma unroll
;             for (int n = 0; n < 2; ++n)
;               yv[j][bj][n] = Y[(long)(tb + j) * YS + pn * 256 + bj * 128 + wc * 32 + n * 16 + fr];
;         }
; #pragma unroll
;         for (int j = 0; j < 4; ++j) {
;           float s1 = s01[j].x + s01[j].z + s23[j].x + s23[j].z, s2 = s01[j].y + s01[j].w + s23[j].y + s23[j].w;
;           float mu = s1 * (1.f / 512.f);
;           float var = s2 * (1.f / 512.f) - mu * mu;
;           float rstd = rsqrtf(fmaxf(var, 0.f) + 1e-5f);
; #pragma unroll
;           for (int bj = 0; bj < 2; ++bj)
; #pragma unroll
;             for (int n = 0; n < 2; ++n) {
;               float g = acc[ai][bj][m][n][j];
;               float yn = (bf2f(yv[j][bj][n]) - mu) * rstd * gn[bj][n];
;               Y[(long)(tb + j) * YS + pn * 256 + bj * 128 + wc * 32 + n * 16 + fr] = f2bf(silu_f(g) * yn);
	global_store_short v[78:79], v59, off offset:32
	global_store_short v[78:79], v55, off offset:256
	global_store_short v[78:79], v82, off offset:288
	global_store_short v[80:81], v51, off
	global_store_short v[80:81], v60, off offset:32
	global_store_short v[80:81], v56, off offset:256
	global_store_short v[80:81], v50, off offset:288
	v_add_u32_e32 v54, 0x90, v152
	v_pk_add_f32 v[50:51], v[214:215], v[216:217]
	s_nop 0
	v_pk_add_f32 v[50:51], v[50:51], v[210:211]
	s_nop 0
	v_pk_add_f32 v[50:51], v[50:51], v[212:213]
	s_nop 0
	v_pk_mul_f32 v[50:51], v[50:51], s[18:19] op_sel_hi:[1,0]
	s_nop 0
	v_fma_f32 v0, -v50, v50, v51
	v_max_f32_e32 v0, 0, v0
	v_add_f32_e32 v0, 0x3727c5ac, v0
	v_cmp_gt_f32_e32 vcc, s25, v0
	v_mul_f32_e32 v51, 0x4b800000, v0
	s_nop 0
	v_cndmask_b32_e32 v0, v0, v51, vcc
	v_rsq_f32_e32 v0, v0
	s_nop 0
	v_mul_f32_e32 v51, 0x45800000, v0
	v_cndmask_b32_e32 v0, v0, v51, vcc
	v_lshlrev_b32_e32 v51, 16, v174
	v_mul_f32_e32 v52, 0xbfb8aa3b, v65
	v_exp_f32_e32 v52, v52
	v_sub_f32_e32 v51, v51, v50
	v_mul_f32_e32 v51, v51, v0
	v_mul_f32_e32 v51, v151, v51
	v_add_f32_e32 v52, 1.0, v52
	v_rcp_f32_e32 v52, v52
	s_nop 0
	v_mul_f32_e32 v52, v65, v52
	v_mul_f32_e32 v51, v52, v51
	v_mul_f32_e32 v52, 0xbfb8aa3b, v61
	v_exp_f32_e32 v52, v52
	v_cvt_pk_bf16_f32 v51, v51, s0
	global_store_short v[74:75], v51, off
	v_lshlrev_b32_e32 v51, 16, v175
	v_add_f32_e32 v52, 1.0, v52
	v_rcp_f32_e32 v52, v52
	v_sub_f32_e32 v51, v51, v50
	v_mul_f32_e32 v51, v51, v0
	v_mul_f32_e32 v51, v150, v51
	v_mul_f32_e32 v52, v61, v52
	v_mul_f32_e32 v51, v52, v51
	v_mul_f32_e32 v52, 0xbfb8aa3b, v57
	v_exp_f32_e32 v52, v52
	v_cvt_pk_bf16_f32 v51, v51, s0
	global_store_short v[74:75], v51, off offset:32
	v_lshlrev_b32_e32 v51, 16, v176
	v_add_f32_e32 v52, 1.0, v52
	v_rcp_f32_e32 v52, v52
	v_sub_f32_e32 v51, v51, v50
	v_mul_f32_e32 v51, v51, v0
	v_mul_f32_e32 v51, v149, v51
	v_mul_f32_e32 v52, v57, v52
	v_mul_f32_e32 v51, v52, v51
	v_cvt_pk_bf16_f32 v51, v51, s0
	global_store_short v[74:75], v51, off offset:256
	v_lshlrev_b32_e32 v51, 16, v177
	v_sub_f32_e32 v50, v51, v50
	v_mul_f32_e32 v0, v50, v0
	v_mul_f32_e32 v50, 0xbfb8aa3b, v53
	v_exp_f32_e32 v50, v50
	v_mul_f32_e32 v0, v148, v0
	v_add_f32_e32 v50, 1.0, v50
	v_rcp_f32_e32 v50, v50
	s_nop 0
	v_mul_f32_e32 v50, v53, v50
	v_mul_f32_e32 v0, v50, v0
	v_cvt_pk_bf16_f32 v0, v0, s0
	global_store_short v[74:75], v0, off offset:288
	s_nop 0
	v_ashrrev_i32_e32 v55, 31, v54
	v_lshlrev_b64 v[50:51], 8, v[54:55]
	v_lshl_add_u64 v[56:57], s[16:17], 0, v[50:51]
	global_load_dwordx4 v[66:69], v[56:57], off offset:16
	global_load_dwordx4 v[70:73], v[56:57], off
	v_mad_i64_i32 v[60:61], s[14:15], v54, s24, v[138:139]
	global_load_ushort v178, v[60:61], off
	global_load_ushort v179, v[60:61], off offset:32
	global_load_ushort v180, v[60:61], off offset:256
	global_load_ushort v181, v[60:61], off offset:288
	v_add_u32_e32 v50, 1, v54
	v_ashrrev_i32_e32 v51, 31, v50
	v_lshlrev_b64 v[52:53], 8, v[50:51]
	v_lshl_add_u64 v[52:53], s[16:17], 0, v[52:53]
	global_load_dwordx4 v[194:197], v[52:53], off offset:16
	global_load_dwordx4 v[198:201], v[52:53], off
	v_mad_i64_i32 v[62:63], s[14:15], v50, s24, v[138:139]
	global_load_ushort v182, v[62:63], off
	global_load_ushort v183, v[62:63], off offset:32
	global_load_ushort v184, v[62:63], off offset:256
	global_load_ushort v185, v[62:63], off offset:288
	v_add_u32_e32 v58, 2, v54
	v_ashrrev_i32_e32 v59, 31, v58
	v_lshlrev_b64 v[50:51], 8, v[58:59]
	v_lshl_add_u64 v[50:51], s[16:17], 0, v[50:51]
	global_load_dwordx4 v[202:205], v[50:51], off offset:16
	global_load_dwordx4 v[206:209], v[50:51], off
	v_mad_i64_i32 v[64:65], s[14:15], v58, s24, v[138:139]
	global_load_ushort v186, v[64:65], off
	global_load_ushort v187, v[64:65], off offset:32
	global_load_ushort v188, v[64:65], off offset:256
	global_load_ushort v189, v[64:65], off offset:288
	v_add_u32_e32 v58, 3, v54
	v_ashrrev_i32_e32 v59, 31, v58
	v_lshlrev_b64 v[54:55], 8, v[58:59]
	v_lshl_add_u64 v[54:55], s[16:17], 0, v[54:55]
	global_load_dwordx4 v[210:213], v[54:55], off offset:16
	global_load_dwordx4 v[214:217], v[54:55], off
	v_mad_i64_i32 v[58:59], s[14:15], v58, s24, v[138:139]
	global_load_ushort v190, v[58:59], off
	global_load_ushort v191, v[58:59], off offset:32
	global_load_ushort v192, v[58:59], off offset:256
	global_load_ushort v193, v[58:59], off offset:288
	s_waitcnt vmcnt(0)
; __device__ __forceinline__ float bf2f(u16 b) { return __uint_as_float(((unsigned)b) << 16); }
; __device__ __forceinline__ float silu_f(float g) { return g * __builtin_amdgcn_rcpf(1.f + __builtin_amdgcn_exp2f(-g * LOG2E)); }
; template <int EPI>
; __device__ __forceinline__ void epilogue(const Params& p, int pass, int layer, int pm, int pn,
;                                          f32x4 (&acc)[2][2][4][2], const float* xin, float* xout) {
;     ...
; #pragma unroll
;         for (int j = 0; j < 4; ++j) {
;           const float4* sp = (const float4*)(stat + ((long)(tb + j) * 8 + h) * 8);
;           s01[j] = sp[0]; s23[j] = sp[1];
; #pragma unroll
;           for (int bj = 0; bj < 2; ++bj)
; #pragma unroll
;             for (int n = 0; n < 2; ++n)
;               yv[j][bj][n] = Y[(long)(tb + j) * YS + pn * 256 + bj * 128 + wc * 32 + n * 16 + fr];
;         }
; #pragma unroll
;         for (int j = 0; j < 4; ++j) {
;           float s1 = s01[j].x + s01[j].z + s23[j].x + s23[j].z, s2 = s01[j].y + s01[j].w + s23[j].y + s23[j].w;
;           float mu = s1 * (1.f / 512.f);
;           float var = s2 * (1.f / 512.f) - mu * mu;
;           float rstd = rsqrtf(fmaxf(var, 0.f) + 1e-5f);
; #pragma unroll
;           for (int bj = 0; bj < 2; ++bj)
; #pragma unroll
;             for (int n = 0; n < 2; ++n) {
;               float g = acc[ai][bj][m][n][j];
;               float yn = (bf2f(yv[j][bj][n]) - mu) * rstd * gn[bj][n];
;               Y[(long)(tb + j) * YS + pn * 256 + bj * 128 + wc * 32 + n * 16 + fr] = f2bf(silu_f(g) * yn);
	v_pk_add_f32 v[56:57], v[70:71], v[72:73]
	s_nop 0
	v_pk_add_f32 v[56:57], v[56:57], v[66:67]
	v_mul_f32_e32 v66, 0xbfb8aa3b, v46
	v_pk_add_f32 v[56:57], v[56:57], v[68:69]
	v_exp_f32_e32 v66, v66
	v_pk_mul_f32 v[56:57], v[56:57], s[18:19] op_sel_hi:[1,0]
	v_add_f32_e32 v66, 1.0, v66
	v_fma_f32 v0, -v56, v56, v57
	v_max_f32_e32 v0, 0, v0
	v_add_f32_e32 v0, 0x3727c5ac, v0
	v_cmp_gt_f32_e32 vcc, s25, v0
	v_mul_f32_e32 v57, 0x4b800000, v0
	v_rcp_f32_e32 v66, v66
	v_cndmask_b32_e32 v0, v0, v57, vcc
	v_rsq_f32_e32 v0, v0
	v_mul_f32_e32 v46, v46, v66
	v_mul_f32_e32 v66, 0xbfb8aa3b, v42
	v_mul_f32_e32 v57, 0x45800000, v0
	v_cndmask_b32_e32 v57, v0, v57, vcc
	v_exp_f32_e32 v66, v66
	v_lshlrev_b32_e32 v0, 16, v178
	v_sub_f32_e32 v0, v0, v56
	v_mul_f32_e32 v0, v0, v57
	v_mul_f32_e32 v0, v151, v0
	v_mul_f32_e32 v0, v46, v0
	v_add_f32_e32 v66, 1.0, v66
	v_rcp_f32_e32 v66, v66
	v_cvt_pk_bf16_f32 v0, v0, s0
	v_mul_f32_e32 v42, v42, v66
	v_mul_f32_e32 v66, 0xbfb8aa3b, v38
	v_exp_f32_e32 v66, v66
	v_lshlrev_b32_e32 v46, 16, v179
	v_sub_f32_e32 v46, v46, v56
	v_mul_f32_e32 v46, v46, v57
	v_mul_f32_e32 v46, v150, v46
	v_mul_f32_e32 v42, v42, v46
	v_add_f32_e32 v66, 1.0, v66
	v_rcp_f32_e32 v66, v66
	v_cvt_pk_bf16_f32 v42, v42, s0
	v_mul_f32_e32 v38, v38, v66
	v_lshlrev_b32_e32 v46, 16, v180
	v_sub_f32_e32 v46, v46, v56
	v_mul_f32_e32 v46, v46, v57
	v_mul_f32_e32 v46, v149, v46
	v_mul_f32_e32 v38, v38, v46
	v_cvt_pk_bf16_f32 v38, v38, s0
	v_lshlrev_b32_e32 v46, 16, v181
	v_sub_f32_e32 v46, v46, v56
	v_mul_f32_e32 v56, 0xbfb8aa3b, v34
	v_exp_f32_e32 v56, v56
	v_pk_add_f32 v[52:53], v[198:199], v[200:201]
	v_mul_f32_e32 v46, v46, v57
	v_pk_add_f32 v[52:53], v[52:53], v[194:195]
	v_add_f32_e32 v56, 1.0, v56
	v_rcp_f32_e32 v56, v56
	v_mul_f32_e32 v46, v148, v46
	v_pk_add_f32 v[52:53], v[52:53], v[196:197]
	v_mul_f32_e32 v34, v34, v56
	v_mul_f32_e32 v34, v34, v46
	v_pk_mul_f32 v[52:53], v[52:53], s[18:19] op_sel_hi:[1,0]
	v_cvt_pk_bf16_f32 v46, v34, s0
	v_fma_f32 v34, -v52, v52, v53
	v_max_f32_e32 v34, 0, v34
	v_add_f32_e32 v34, 0x3727c5ac, v34
	v_cmp_gt_f32_e32 vcc, s25, v34
	v_mul_f32_e32 v53, 0x4b800000, v34
	v_mul_f32_e32 v56, 0xbfb8aa3b, v47
	v_cndmask_b32_e32 v34, v34, v53, vcc
	v_rsq_f32_e32 v34, v34
	v_exp_f32_e32 v56, v56
	v_mul_f32_e32 v53, 0x45800000, v34
	v_cndmask_b32_e32 v34, v34, v53, vcc
	v_add_f32_e32 v56, 1.0, v56
	v_rcp_f32_e32 v56, v56
	v_lshlrev_b32_e32 v53, 16, v182
	v_sub_f32_e32 v53, v53, v52
	v_mul_f32_e32 v53, v53, v34
	v_mul_f32_e32 v53, v151, v53
	v_mul_f32_e32 v47, v47, v56
	v_mul_f32_e32 v47, v47, v53
	v_mul_f32_e32 v56, 0xbfb8aa3b, v43
	v_exp_f32_e32 v56, v56
	v_cvt_pk_bf16_f32 v47, v47, s0
	v_add_f32_e32 v56, 1.0, v56
	v_rcp_f32_e32 v56, v56
	v_lshlrev_b32_e32 v53, 16, v183
	v_sub_f32_e32 v53, v53, v52
	v_mul_f32_e32 v53, v53, v34
	v_mul_f32_e32 v53, v150, v53
	v_mul_f32_e32 v43, v43, v56
	v_mul_f32_e32 v43, v43, v53
	v_mul_f32_e32 v56, 0xbfb8aa3b, v39
	v_exp_f32_e32 v56, v56
	v_cvt_pk_bf16_f32 v43, v43, s0
	v_add_f32_e32 v56, 1.0, v56
	v_rcp_f32_e32 v56, v56
	v_lshlrev_b32_e32 v53, 16, v184
	v_sub_f32_e32 v53, v53, v52
	v_mul_f32_e32 v53, v53, v34
	v_mul_f32_e32 v53, v149, v53
	v_mul_f32_e32 v39, v39, v56
	v_mul_f32_e32 v39, v39, v53
	v_cvt_pk_bf16_f32 v39, v39, s0
	v_lshlrev_b32_e32 v53, 16, v185
	v_sub_f32_e32 v52, v53, v52
	v_mul_f32_e32 v34, v52, v34
	v_mul_f32_e32 v52, 0xbfb8aa3b, v35
	v_exp_f32_e32 v52, v52
	v_mul_f32_e32 v34, v148, v34
	v_add_f32_e32 v52, 1.0, v52
	v_rcp_f32_e32 v52, v52
	s_nop 0
	v_mul_f32_e32 v35, v35, v52
	s_nop 0
	v_mul_f32_e32 v34, v35, v34
	v_cvt_pk_bf16_f32 v66, v34, s0
	v_pk_add_f32 v[34:35], v[206:207], v[208:209]
	s_nop 0
	v_pk_add_f32 v[34:35], v[34:35], v[202:203]
	v_mul_f32_e32 v51, 0xbfb8aa3b, v48
	v_pk_add_f32 v[34:35], v[34:35], v[204:205]
	v_exp_f32_e32 v51, v51
	v_pk_mul_f32 v[34:35], v[34:35], s[18:19] op_sel_hi:[1,0]
	v_add_f32_e32 v51, 1.0, v51
	v_fma_f32 v35, -v34, v34, v35
	v_max_f32_e32 v35, 0, v35
	v_add_f32_e32 v35, 0x3727c5ac, v35
	v_cmp_gt_f32_e32 vcc, s25, v35
	v_mul_f32_e32 v50, 0x4b800000, v35
	v_rcp_f32_e32 v51, v51
	v_cndmask_b32_e32 v35, v35, v50, vcc
	v_rsq_f32_e32 v35, v35
	v_mul_f32_e32 v48, v48, v51
	v_mul_f32_e32 v51, 0xbfb8aa3b, v44
	v_mul_f32_e32 v50, 0x45800000, v35
	v_cndmask_b32_e32 v50, v35, v50, vcc
	v_exp_f32_e32 v51, v51
	v_lshlrev_b32_e32 v35, 16, v186
	v_sub_f32_e32 v35, v35, v34
	v_mul_f32_e32 v35, v35, v50
	v_mul_f32_e32 v35, v151, v35
	v_mul_f32_e32 v35, v48, v35
	v_add_f32_e32 v51, 1.0, v51
	v_rcp_f32_e32 v51, v51
	v_cvt_pk_bf16_f32 v35, v35, s0
	v_mul_f32_e32 v44, v44, v51
	v_mul_f32_e32 v51, 0xbfb8aa3b, v40
	v_exp_f32_e32 v51, v51
	v_lshlrev_b32_e32 v48, 16, v187
	v_sub_f32_e32 v48, v48, v34
	v_mul_f32_e32 v48, v48, v50
	v_mul_f32_e32 v48, v150, v48
	v_mul_f32_e32 v44, v44, v48
	v_add_f32_e32 v51, 1.0, v51
	v_rcp_f32_e32 v51, v51
	v_cvt_pk_bf16_f32 v44, v44, s0
	v_mul_f32_e32 v40, v40, v51
	v_lshlrev_b32_e32 v48, 16, v188
	v_sub_f32_e32 v48, v48, v34
	v_mul_f32_e32 v48, v48, v50
	v_mul_f32_e32 v48, v149, v48
	v_mul_f32_e32 v40, v40, v48
	v_cvt_pk_bf16_f32 v40, v40, s0
	v_lshlrev_b32_e32 v48, 16, v189
	v_sub_f32_e32 v34, v48, v34
	v_mul_f32_e32 v48, 0xbfb8aa3b, v36
	v_exp_f32_e32 v48, v48
	v_mul_f32_e32 v34, v34, v50
	v_mul_f32_e32 v34, v148, v34
	v_add_f32_e32 v48, 1.0, v48
	v_rcp_f32_e32 v48, v48
	s_nop 0
	v_mul_f32_e32 v36, v36, v48
	v_mul_f32_e32 v34, v36, v34
	s_nop 0
	s_nop 0
	v_cvt_pk_bf16_f32 v34, v34, s0
	global_store_short v[60:61], v0, off
	global_store_short v[60:61], v42, off offset:32
	global_store_short v[60:61], v38, off offset:256
	global_store_short v[60:61], v46, off offset:288
	global_store_short v[62:63], v47, off
; __device__ __forceinline__ float bf2f(u16 b) { return __uint_as_float(((unsigned)b) << 16); }
; __device__ __forceinline__ float silu_f(float g) { return g * __builtin_amdgcn_rcpf(1.f + __builtin_amdgcn_exp2f(-g * LOG2E)); }
; template <int EPI>
; __device__ __forceinline__ void epilogue(const Params& p, int pass, int layer, int pm, int pn,
;                                          f32x4 (&acc)[2][2][4][2], const float* xin, float* xout) {
;     ...
;         int tb = t0 + ai * 128 + wr * 64 + m * 16 + fq * 4;
;         asm volatile("" : "+v"(tb));
;         float4 s01[4], s23[4];
;         u16 yv[4][2][2];
; #pragma unroll
;         for (int j = 0; j < 4; ++j) {
;           const float4* sp = (const float4*)(stat + ((long)(tb + j) * 8 + h) * 8);
;           s01[j] = sp[0]; s23[j] = sp[1];
; #pragma unroll
;           for (int bj = 0; bj < 2; ++bj)
; #pragma unroll
;             for (int n = 0; n < 2; ++n)
;               yv[j][bj][n] = Y[(long)(tb + j) * YS + pn * 256 + bj * 128 + wc * 32 + n * 16 + fr];
;         }
; #pragma unroll
;         for (int j = 0; j < 4; ++j) {
;           float s1 = s01[j].x + s01[j].z + s23[j].x + s23[j].z, s2 = s01[j].y + s01[j].w + s23[j].y + s23[j].w;
;           float mu = s1 * (1.f / 512.f);
;           float var = s2 * (1.f / 512.f) - mu * mu;
;           float rstd = rsqrtf(fmaxf(var, 0.f) + 1e-5f);
; #pragma unroll
;           for (int bj = 0; bj < 2; ++bj)
; #pragma unroll
;             for (int n = 0; n < 2; ++n) {
;               float g = acc[ai][bj][m][n][j];
;               float yn = (bf2f(yv[j][bj][n]) - mu) * rstd * gn[bj][n];
;               Y[(long)(tb + j) * YS + pn * 256 + bj * 128 + wc * 32 + n * 16 + fr] = f2bf(silu_f(g) * yn);
	global_store_short v[62:63], v43, off offset:32
	global_store_short v[62:63], v39, off offset:256
	global_store_short v[62:63], v66, off offset:288
	global_store_short v[64:65], v35, off
	global_store_short v[64:65], v44, off offset:32
	global_store_short v[64:65], v40, off offset:256
	global_store_short v[64:65], v34, off offset:288
	v_add_u32_e32 v38, 0xa0, v152
	v_pk_add_f32 v[34:35], v[214:215], v[216:217]
	s_nop 0
	v_pk_add_f32 v[34:35], v[34:35], v[210:211]
	s_nop 0
	v_pk_add_f32 v[34:35], v[34:35], v[212:213]
	s_nop 0
	v_pk_mul_f32 v[34:35], v[34:35], s[18:19] op_sel_hi:[1,0]
	s_nop 0
	v_fma_f32 v0, -v34, v34, v35
	v_max_f32_e32 v0, 0, v0
	v_add_f32_e32 v0, 0x3727c5ac, v0
	v_cmp_gt_f32_e32 vcc, s25, v0
	v_mul_f32_e32 v35, 0x4b800000, v0
	s_nop 0
	v_cndmask_b32_e32 v0, v0, v35, vcc
	v_rsq_f32_e32 v0, v0
	s_nop 0
	v_mul_f32_e32 v35, 0x45800000, v0
	v_cndmask_b32_e32 v0, v0, v35, vcc
	v_lshlrev_b32_e32 v35, 16, v190
	v_mul_f32_e32 v36, 0xbfb8aa3b, v49
	v_exp_f32_e32 v36, v36
	v_sub_f32_e32 v35, v35, v34
	v_mul_f32_e32 v35, v35, v0
	v_mul_f32_e32 v35, v151, v35
	v_add_f32_e32 v36, 1.0, v36
	v_rcp_f32_e32 v36, v36
	s_nop 0
	v_mul_f32_e32 v36, v49, v36
	v_mul_f32_e32 v35, v36, v35
	v_mul_f32_e32 v36, 0xbfb8aa3b, v45
	v_exp_f32_e32 v36, v36
	v_cvt_pk_bf16_f32 v35, v35, s0
	global_store_short v[58:59], v35, off
	v_lshlrev_b32_e32 v35, 16, v191
	v_add_f32_e32 v36, 1.0, v36
	v_rcp_f32_e32 v36, v36
	v_sub_f32_e32 v35, v35, v34
	v_mul_f32_e32 v35, v35, v0
	v_mul_f32_e32 v35, v150, v35
	v_mul_f32_e32 v36, v45, v36
	v_mul_f32_e32 v35, v36, v35
	v_mul_f32_e32 v36, 0xbfb8aa3b, v41
	v_exp_f32_e32 v36, v36
	v_cvt_pk_bf16_f32 v35, v35, s0
	global_store_short v[58:59], v35, off offset:32
	v_lshlrev_b32_e32 v35, 16, v192
	v_add_f32_e32 v36, 1.0, v36
	v_rcp_f32_e32 v36, v36
	v_sub_f32_e32 v35, v35, v34
	v_mul_f32_e32 v35, v35, v0
	v_mul_f32_e32 v35, v149, v35
	v_mul_f32_e32 v36, v41, v36
	v_mul_f32_e32 v35, v36, v35
	v_cvt_pk_bf16_f32 v35, v35, s0
	global_store_short v[58:59], v35, off offset:256
	v_lshlrev_b32_e32 v35, 16, v193
	v_sub_f32_e32 v34, v35, v34
	v_mul_f32_e32 v0, v34, v0
	v_mul_f32_e32 v34, 0xbfb8aa3b, v37
	v_exp_f32_e32 v34, v34
	v_mul_f32_e32 v0, v148, v0
	v_add_f32_e32 v34, 1.0, v34
	v_rcp_f32_e32 v34, v34
	s_nop 0
	v_mul_f32_e32 v34, v37, v34
	v_mul_f32_e32 v0, v34, v0
	v_cvt_pk_bf16_f32 v0, v0, s0
	global_store_short v[58:59], v0, off offset:288
	s_nop 0
	v_ashrrev_i32_e32 v39, 31, v38
	v_lshlrev_b64 v[34:35], 8, v[38:39]
	v_lshl_add_u64 v[40:41], s[16:17], 0, v[34:35]
	global_load_dwordx4 v[50:53], v[40:41], off offset:16
	global_load_dwordx4 v[54:57], v[40:41], off
	v_mad_i64_i32 v[44:45], s[14:15], v38, s24, v[138:139]
	global_load_ushort v162, v[44:45], off
	global_load_ushort v163, v[44:45], off offset:32
	global_load_ushort v164, v[44:45], off offset:256
	global_load_ushort v165, v[44:45], off offset:288
	v_add_u32_e32 v34, 1, v38
	v_ashrrev_i32_e32 v35, 31, v34
	v_lshlrev_b64 v[36:37], 8, v[34:35]
	v_lshl_add_u64 v[36:37], s[16:17], 0, v[36:37]
	global_load_dwordx4 v[194:197], v[36:37], off offset:16
	global_load_dwordx4 v[198:201], v[36:37], off
	v_mad_i64_i32 v[46:47], s[14:15], v34, s24, v[138:139]
	global_load_ushort v166, v[46:47], off
	global_load_ushort v167, v[46:47], off offset:32
	global_load_ushort v168, v[46:47], off offset:256
	global_load_ushort v169, v[46:47], off offset:288
	v_add_u32_e32 v42, 2, v38
	v_ashrrev_i32_e32 v43, 31, v42
	v_lshlrev_b64 v[34:35], 8, v[42:43]
	v_lshl_add_u64 v[34:35], s[16:17], 0, v[34:35]
	global_load_dwordx4 v[202:205], v[34:35], off offset:16
	global_load_dwordx4 v[206:209], v[34:35], off
	v_mad_i64_i32 v[48:49], s[14:15], v42, s24, v[138:139]
	global_load_ushort v170, v[48:49], off
	global_load_ushort v171, v[48:49], off offset:32
	global_load_ushort v172, v[48:49], off offset:256
	global_load_ushort v173, v[48:49], off offset:288
	v_add_u32_e32 v42, 3, v38
	v_ashrrev_i32_e32 v43, 31, v42
	v_lshlrev_b64 v[38:39], 8, v[42:43]
	v_lshl_add_u64 v[38:39], s[16:17], 0, v[38:39]
	global_load_dwordx4 v[210:213], v[38:39], off offset:16
	global_load_dwordx4 v[214:217], v[38:39], off
	v_mad_i64_i32 v[42:43], s[14:15], v42, s24, v[138:139]
	global_load_ushort v174, v[42:43], off
	global_load_ushort v175, v[42:43], off offset:32
	global_load_ushort v176, v[42:43], off offset:256
	global_load_ushort v177, v[42:43], off offset:288
	s_waitcnt vmcnt(0)
; __device__ __forceinline__ float bf2f(u16 b) { return __uint_as_float(((unsigned)b) << 16); }
; __device__ __forceinline__ float silu_f(float g) { return g * __builtin_amdgcn_rcpf(1.f + __builtin_amdgcn_exp2f(-g * LOG2E)); }
; template <int EPI>
; __device__ __forceinline__ void epilogue(const Params& p, int pass, int layer, int pm, int pn,
;                                          f32x4 (&acc)[2][2][4][2], const float* xin, float* xout) {
;     ...
; #pragma unroll
;         for (int j = 0; j < 4; ++j) {
;           const float4* sp = (const float4*)(stat + ((long)(tb + j) * 8 + h) * 8);
;           s01[j] = sp[0]; s23[j] = sp[1];
; #pragma unroll
;           for (int bj = 0; bj < 2; ++bj)
; #pragma unroll
;             for (int n = 0; n < 2; ++n)
;               yv[j][bj][n] = Y[(long)(tb + j) * YS + pn * 256 + bj * 128 + wc * 32 + n * 16 + fr];
;         }
; #pragma unroll
;         for (int j = 0; j < 4; ++j) {
;           float s1 = s01[j].x + s01[j].z + s23[j].x + s23[j].z, s2 = s01[j].y + s01[j].w + s23[j].y + s23[j].w;
;           float mu = s1 * (1.f / 512.f);
;           float var = s2 * (1.f / 512.f) - mu * mu;
;           float rstd = rsqrtf(fmaxf(var, 0.f) + 1e-5f);
; #pragma unroll
;           for (int bj = 0; bj < 2; ++bj)
; #pragma unroll
;             for (int n = 0; n < 2; ++n) {
;               float g = acc[ai][bj][m][n][j];
;               float yn = (bf2f(yv[j][bj][n]) - mu) * rstd * gn[bj][n];
;               Y[(long)(tb + j) * YS + pn * 256 + bj * 128 + wc * 32 + n * 16 + fr] = f2bf(silu_f(g) * yn);
	v_pk_add_f32 v[40:41], v[54:55], v[56:57]
	s_nop 0
	v_pk_add_f32 v[40:41], v[40:41], v[50:51]
	v_mul_f32_e32 v50, 0xbfb8aa3b, v30
	v_pk_add_f32 v[40:41], v[40:41], v[52:53]
	v_exp_f32_e32 v50, v50
	v_pk_mul_f32 v[40:41], v[40:41], s[18:19] op_sel_hi:[1,0]
	v_add_f32_e32 v50, 1.0, v50
	v_fma_f32 v0, -v40, v40, v41
	v_max_f32_e32 v0, 0, v0
	v_add_f32_e32 v0, 0x3727c5ac, v0
	v_cmp_gt_f32_e32 vcc, s25, v0
	v_mul_f32_e32 v41, 0x4b800000, v0
	v_rcp_f32_e32 v50, v50
	v_cndmask_b32_e32 v0, v0, v41, vcc
	v_rsq_f32_e32 v0, v0
	v_mul_f32_e32 v30, v30, v50
	v_mul_f32_e32 v50, 0xbfb8aa3b, v26
	v_mul_f32_e32 v41, 0x45800000, v0
	v_cndmask_b32_e32 v41, v0, v41, vcc
	v_exp_f32_e32 v50, v50
	v_lshlrev_b32_e32 v0, 16, v162
	v_sub_f32_e32 v0, v0, v40
	v_mul_f32_e32 v0, v0, v41
	v_mul_f32_e32 v0, v151, v0
	v_mul_f32_e32 v0, v30, v0
	v_add_f32_e32 v50, 1.0, v50
	v_rcp_f32_e32 v50, v50
	v_cvt_pk_bf16_f32 v0, v0, s0
	v_mul_f32_e32 v26, v26, v50
	v_mul_f32_e32 v50, 0xbfb8aa3b, v22
	v_exp_f32_e32 v50, v50
	v_lshlrev_b32_e32 v30, 16, v163
	v_sub_f32_e32 v30, v30, v40
	v_mul_f32_e32 v30, v30, v41
	v_mul_f32_e32 v30, v150, v30
	v_mul_f32_e32 v26, v26, v30
	v_add_f32_e32 v50, 1.0, v50
	v_rcp_f32_e32 v50, v50
	v_cvt_pk_bf16_f32 v26, v26, s0
	v_mul_f32_e32 v22, v22, v50
	v_lshlrev_b32_e32 v30, 16, v164
	v_sub_f32_e32 v30, v30, v40
	v_mul_f32_e32 v30, v30, v41
	v_mul_f32_e32 v30, v149, v30
	v_mul_f32_e32 v22, v22, v30
	v_cvt_pk_bf16_f32 v22, v22, s0
	v_lshlrev_b32_e32 v30, 16, v165
	v_sub_f32_e32 v30, v30, v40
	v_mul_f32_e32 v40, 0xbfb8aa3b, v18
	v_exp_f32_e32 v40, v40
	v_pk_add_f32 v[36:37], v[198:199], v[200:201]
	v_mul_f32_e32 v30, v30, v41
	v_pk_add_f32 v[36:37], v[36:37], v[194:195]
	v_add_f32_e32 v40, 1.0, v40
	v_rcp_f32_e32 v40, v40
	v_mul_f32_e32 v30, v148, v30
	v_pk_add_f32 v[36:37], v[36:37], v[196:197]
	v_mul_f32_e32 v18, v18, v40
	v_mul_f32_e32 v18, v18, v30
	v_pk_mul_f32 v[36:37], v[36:37], s[18:19] op_sel_hi:[1,0]
	v_cvt_pk_bf16_f32 v30, v18, s0
	v_fma_f32 v18, -v36, v36, v37
	v_max_f32_e32 v18, 0, v18
	v_add_f32_e32 v18, 0x3727c5ac, v18
	v_cmp_gt_f32_e32 vcc, s25, v18
	v_mul_f32_e32 v37, 0x4b800000, v18
	v_mul_f32_e32 v40, 0xbfb8aa3b, v31
	v_cndmask_b32_e32 v18, v18, v37, vcc
	v_rsq_f32_e32 v18, v18
	v_exp_f32_e32 v40, v40
	v_mul_f32_e32 v37, 0x45800000, v18
	v_cndmask_b32_e32 v18, v18, v37, vcc
	v_add_f32_e32 v40, 1.0, v40
	v_rcp_f32_e32 v40, v40
	v_lshlrev_b32_e32 v37, 16, v166
	v_sub_f32_e32 v37, v37, v36
	v_mul_f32_e32 v37, v37, v18
	v_mul_f32_e32 v37, v151, v37
	v_mul_f32_e32 v31, v31, v40
	v_mul_f32_e32 v31, v31, v37
	v_mul_f32_e32 v40, 0xbfb8aa3b, v27
	v_exp_f32_e32 v40, v40
	v_cvt_pk_bf16_f32 v31, v31, s0
	v_add_f32_e32 v40, 1.0, v40
	v_rcp_f32_e32 v40, v40
	v_lshlrev_b32_e32 v37, 16, v167
	v_sub_f32_e32 v37, v37, v36
	v_mul_f32_e32 v37, v37, v18
	v_mul_f32_e32 v37, v150, v37
	v_mul_f32_e32 v27, v27, v40
	v_mul_f32_e32 v27, v27, v37
	v_mul_f32_e32 v40, 0xbfb8aa3b, v23
	v_exp_f32_e32 v40, v40
	v_cvt_pk_bf16_f32 v27, v27, s0
	v_add_f32_e32 v40, 1.0, v40
	v_rcp_f32_e32 v40, v40
	v_lshlrev_b32_e32 v37, 16, v168
	v_sub_f32_e32 v37, v37, v36
	v_mul_f32_e32 v37, v37, v18
	v_mul_f32_e32 v37, v149, v37
	v_mul_f32_e32 v23, v23, v40
	v_mul_f32_e32 v23, v23, v37
	v_cvt_pk_bf16_f32 v23, v23, s0
	v_lshlrev_b32_e32 v37, 16, v169
	v_sub_f32_e32 v36, v37, v36
	v_mul_f32_e32 v18, v36, v18
	v_mul_f32_e32 v36, 0xbfb8aa3b, v19
	v_exp_f32_e32 v36, v36
	v_mul_f32_e32 v18, v148, v18
	v_add_f32_e32 v36, 1.0, v36
	v_rcp_f32_e32 v36, v36
	s_nop 0
	v_mul_f32_e32 v19, v19, v36
	s_nop 0
	v_mul_f32_e32 v18, v19, v18
	v_cvt_pk_bf16_f32 v50, v18, s0
	v_pk_add_f32 v[18:19], v[206:207], v[208:209]
	s_nop 0
	v_pk_add_f32 v[18:19], v[18:19], v[202:203]
	v_mul_f32_e32 v35, 0xbfb8aa3b, v32
	v_pk_add_f32 v[18:19], v[18:19], v[204:205]
	v_exp_f32_e32 v35, v35
	v_pk_mul_f32 v[18:19], v[18:19], s[18:19] op_sel_hi:[1,0]
	v_add_f32_e32 v35, 1.0, v35
	v_fma_f32 v19, -v18, v18, v19
	v_max_f32_e32 v19, 0, v19
	v_add_f32_e32 v19, 0x3727c5ac, v19
	v_cmp_gt_f32_e32 vcc, s25, v19
	v_mul_f32_e32 v34, 0x4b800000, v19
	v_rcp_f32_e32 v35, v35
	v_cndmask_b32_e32 v19, v19, v34, vcc
	v_rsq_f32_e32 v19, v19
	v_mul_f32_e32 v32, v32, v35
	v_mul_f32_e32 v35, 0xbfb8aa3b, v28
	v_mul_f32_e32 v34, 0x45800000, v19
	v_cndmask_b32_e32 v34, v19, v34, vcc
	v_exp_f32_e32 v35, v35
	v_lshlrev_b32_e32 v19, 16, v170
	v_sub_f32_e32 v19, v19, v18
	v_mul_f32_e32 v19, v19, v34
	v_mul_f32_e32 v19, v151, v19
	v_mul_f32_e32 v19, v32, v19
	v_add_f32_e32 v35, 1.0, v35
	v_rcp_f32_e32 v35, v35
	v_cvt_pk_bf16_f32 v19, v19, s0
	v_mul_f32_e32 v28, v28, v35
	v_mul_f32_e32 v35, 0xbfb8aa3b, v24
	v_exp_f32_e32 v35, v35
	v_lshlrev_b32_e32 v32, 16, v171
	v_sub_f32_e32 v32, v32, v18
	v_mul_f32_e32 v32, v32, v34
	v_mul_f32_e32 v32, v150, v32
	v_mul_f32_e32 v28, v28, v32
	v_add_f32_e32 v35, 1.0, v35
	v_rcp_f32_e32 v35, v35
	v_cvt_pk_bf16_f32 v28, v28, s0
	v_mul_f32_e32 v24, v24, v35
	v_lshlrev_b32_e32 v32, 16, v172
	v_sub_f32_e32 v32, v32, v18
	v_mul_f32_e32 v32, v32, v34
	v_mul_f32_e32 v32, v149, v32
	v_mul_f32_e32 v24, v24, v32
	v_cvt_pk_bf16_f32 v24, v24, s0
	v_lshlrev_b32_e32 v32, 16, v173
	v_sub_f32_e32 v18, v32, v18
	v_mul_f32_e32 v32, 0xbfb8aa3b, v20
	v_exp_f32_e32 v32, v32
	v_mul_f32_e32 v18, v18, v34
	v_mul_f32_e32 v18, v148, v18
	v_add_f32_e32 v32, 1.0, v32
	v_rcp_f32_e32 v32, v32
	s_nop 0
	v_mul_f32_e32 v20, v20, v32
	v_mul_f32_e32 v18, v20, v18
	s_nop 0
	s_nop 0
	v_cvt_pk_bf16_f32 v18, v18, s0
	global_store_short v[44:45], v0, off
	global_store_short v[44:45], v26, off offset:32
	global_store_short v[44:45], v22, off offset:256
	global_store_short v[44:45], v30, off offset:288
	global_store_short v[46:47], v31, off
; __device__ __forceinline__ float bf2f(u16 b) { return __uint_as_float(((unsigned)b) << 16); }
; __device__ __forceinline__ float silu_f(float g) { return g * __builtin_amdgcn_rcpf(1.f + __builtin_amdgcn_exp2f(-g * LOG2E)); }
; template <int EPI>
; __device__ __forceinline__ void epilogue(const Params& p, int pass, int layer, int pm, int pn,
;                                          f32x4 (&acc)[2][2][4][2], const float* xin, float* xout) {
;     ...
;         int tb = t0 + ai * 128 + wr * 64 + m * 16 + fq * 4;
;         asm volatile("" : "+v"(tb));
;         float4 s01[4], s23[4];
;         u16 yv[4][2][2];
; #pragma unroll
;         for (int j = 0; j < 4; ++j) {
;           const float4* sp = (const float4*)(stat + ((long)(tb + j) * 8 + h) * 8);
;           s01[j] = sp[0]; s23[j] = sp[1];
; #pragma unroll
;           for (int bj = 0; bj < 2; ++bj)
; #pragma unroll
;             for (int n = 0; n < 2; ++n)
;               yv[j][bj][n] = Y[(long)(tb + j) * YS + pn * 256 + bj * 128 + wc * 32 + n * 16 + fr];
;         }
; #pragma unroll
;         for (int j = 0; j < 4; ++j) {
;           float s1 = s01[j].x + s01[j].z + s23[j].x + s23[j].z, s2 = s01[j].y + s01[j].w + s23[j].y + s23[j].w;
;           float mu = s1 * (1.f / 512.f);
;           float var = s2 * (1.f / 512.f) - mu * mu;
;           float rstd = rsqrtf(fmaxf(var, 0.f) + 1e-5f);
; #pragma unroll
;           for (int bj = 0; bj < 2; ++bj)
; #pragma unroll
;             for (int n = 0; n < 2; ++n) {
;               float g = acc[ai][bj][m][n][j];
;               float yn = (bf2f(yv[j][bj][n]) - mu) * rstd * gn[bj][n];
;               Y[(long)(tb + j) * YS + pn * 256 + bj * 128 + wc * 32 + n * 16 + fr] = f2bf(silu_f(g) * yn);
	global_store_short v[46:47], v27, off offset:32
	global_store_short v[46:47], v23, off offset:256
	global_store_short v[46:47], v50, off offset:288
	global_store_short v[48:49], v19, off
	global_store_short v[48:49], v28, off offset:32
	global_store_short v[48:49], v24, off offset:256
	global_store_short v[48:49], v18, off offset:288
	v_add_u32_e32 v22, 0xb0, v152
	v_pk_add_f32 v[18:19], v[214:215], v[216:217]
	s_nop 0
	v_pk_add_f32 v[18:19], v[18:19], v[210:211]
	s_nop 0
	v_pk_add_f32 v[18:19], v[18:19], v[212:213]
	s_nop 0
	v_pk_mul_f32 v[18:19], v[18:19], s[18:19] op_sel_hi:[1,0]
	s_nop 0
	v_fma_f32 v0, -v18, v18, v19
	v_max_f32_e32 v0, 0, v0
	v_add_f32_e32 v0, 0x3727c5ac, v0
	v_cmp_gt_f32_e32 vcc, s25, v0
	v_mul_f32_e32 v19, 0x4b800000, v0
	s_nop 0
	v_cndmask_b32_e32 v0, v0, v19, vcc
	v_rsq_f32_e32 v0, v0
	s_nop 0
	v_mul_f32_e32 v19, 0x45800000, v0
	v_cndmask_b32_e32 v0, v0, v19, vcc
	v_lshlrev_b32_e32 v19, 16, v174
	v_mul_f32_e32 v20, 0xbfb8aa3b, v33
	v_exp_f32_e32 v20, v20
	v_sub_f32_e32 v19, v19, v18
	v_mul_f32_e32 v19, v19, v0
	v_mul_f32_e32 v19, v151, v19
	v_add_f32_e32 v20, 1.0, v20
	v_rcp_f32_e32 v20, v20
	s_nop 0
	v_mul_f32_e32 v20, v33, v20
	v_mul_f32_e32 v19, v20, v19
	v_mul_f32_e32 v20, 0xbfb8aa3b, v29
	v_exp_f32_e32 v20, v20
	v_cvt_pk_bf16_f32 v19, v19, s0
	global_store_short v[42:43], v19, off
	v_lshlrev_b32_e32 v19, 16, v175
	v_add_f32_e32 v20, 1.0, v20
	v_rcp_f32_e32 v20, v20
	v_sub_f32_e32 v19, v19, v18
	v_mul_f32_e32 v19, v19, v0
	v_mul_f32_e32 v19, v150, v19
	v_mul_f32_e32 v20, v29, v20
	v_mul_f32_e32 v19, v20, v19
	v_mul_f32_e32 v20, 0xbfb8aa3b, v25
	v_exp_f32_e32 v20, v20
	v_cvt_pk_bf16_f32 v19, v19, s0
	global_store_short v[42:43], v19, off offset:32
	v_lshlrev_b32_e32 v19, 16, v176
	v_add_f32_e32 v20, 1.0, v20
	v_rcp_f32_e32 v20, v20
	v_sub_f32_e32 v19, v19, v18
	v_mul_f32_e32 v19, v19, v0
	v_mul_f32_e32 v19, v149, v19
	v_mul_f32_e32 v20, v25, v20
	v_mul_f32_e32 v19, v20, v19
	v_cvt_pk_bf16_f32 v19, v19, s0
	global_store_short v[42:43], v19, off offset:256
	v_lshlrev_b32_e32 v19, 16, v177
	v_sub_f32_e32 v18, v19, v18
	v_mul_f32_e32 v0, v18, v0
	v_mul_f32_e32 v18, 0xbfb8aa3b, v21
	v_exp_f32_e32 v18, v18
	v_mul_f32_e32 v0, v148, v0
	v_add_f32_e32 v18, 1.0, v18
	v_rcp_f32_e32 v18, v18
	s_nop 0
	v_mul_f32_e32 v18, v21, v18
	v_mul_f32_e32 v0, v18, v0
	v_cvt_pk_bf16_f32 v0, v0, s0
	global_store_short v[42:43], v0, off offset:288
	s_nop 0
	v_ashrrev_i32_e32 v23, 31, v22
	v_lshlrev_b64 v[18:19], 8, v[22:23]
	v_lshl_add_u64 v[24:25], s[16:17], 0, v[18:19]
	global_load_dwordx4 v[34:37], v[24:25], off offset:16
	global_load_dwordx4 v[38:41], v[24:25], off
	v_mad_i64_i32 v[28:29], s[14:15], v22, s24, v[138:139]
	global_load_ushort v178, v[28:29], off
	global_load_ushort v179, v[28:29], off offset:32
	global_load_ushort v180, v[28:29], off offset:256
	global_load_ushort v181, v[28:29], off offset:288
	v_add_u32_e32 v18, 1, v22
	v_ashrrev_i32_e32 v19, 31, v18
	v_lshlrev_b64 v[20:21], 8, v[18:19]
	v_lshl_add_u64 v[20:21], s[16:17], 0, v[20:21]
	global_load_dwordx4 v[194:197], v[20:21], off offset:16
	global_load_dwordx4 v[198:201], v[20:21], off
	v_mad_i64_i32 v[30:31], s[14:15], v18, s24, v[138:139]
	global_load_ushort v182, v[30:31], off
	global_load_ushort v183, v[30:31], off offset:32
	global_load_ushort v184, v[30:31], off offset:256
	global_load_ushort v185, v[30:31], off offset:288
	v_add_u32_e32 v26, 2, v22
	v_ashrrev_i32_e32 v27, 31, v26
	v_lshlrev_b64 v[18:19], 8, v[26:27]
	v_lshl_add_u64 v[18:19], s[16:17], 0, v[18:19]
	global_load_dwordx4 v[202:205], v[18:19], off offset:16
	global_load_dwordx4 v[206:209], v[18:19], off
	v_mad_i64_i32 v[32:33], s[14:15], v26, s24, v[138:139]
	global_load_ushort v186, v[32:33], off
	global_load_ushort v187, v[32:33], off offset:32
	global_load_ushort v188, v[32:33], off offset:256
	global_load_ushort v189, v[32:33], off offset:288
	v_add_u32_e32 v26, 3, v22
	v_ashrrev_i32_e32 v27, 31, v26
	v_lshlrev_b64 v[22:23], 8, v[26:27]
	v_lshl_add_u64 v[22:23], s[16:17], 0, v[22:23]
	global_load_dwordx4 v[210:213], v[22:23], off offset:16
	global_load_dwordx4 v[214:217], v[22:23], off
	v_mad_i64_i32 v[26:27], s[14:15], v26, s24, v[138:139]
	global_load_ushort v190, v[26:27], off
	global_load_ushort v191, v[26:27], off offset:32
	global_load_ushort v192, v[26:27], off offset:256
	global_load_ushort v193, v[26:27], off offset:288
	s_mov_b32 s14, s6
	s_waitcnt vmcnt(0)
; __device__ __forceinline__ float bf2f(u16 b) { return __uint_as_float(((unsigned)b) << 16); }
; __device__ __forceinline__ float silu_f(float g) { return g * __builtin_amdgcn_rcpf(1.f + __builtin_amdgcn_exp2f(-g * LOG2E)); }
; template <int EPI>
; __device__ __forceinline__ void epilogue(const Params& p, int pass, int layer, int pm, int pn,
;                                          f32x4 (&acc)[2][2][4][2], const float* xin, float* xout) {
;     ...
; #pragma unroll
;         for (int j = 0; j < 4; ++j) {
;           const float4* sp = (const float4*)(stat + ((long)(tb + j) * 8 + h) * 8);
;           s01[j] = sp[0]; s23[j] = sp[1];
; #pragma unroll
;           for (int bj = 0; bj < 2; ++bj)
; #pragma unroll
;             for (int n = 0; n < 2; ++n)
;               yv[j][bj][n] = Y[(long)(tb + j) * YS + pn * 256 + bj * 128 + wc * 32 + n * 16 + fr];
;         }
; #pragma unroll
;         for (int j = 0; j < 4; ++j) {
;           float s1 = s01[j].x + s01[j].z + s23[j].x + s23[j].z, s2 = s01[j].y + s01[j].w + s23[j].y + s23[j].w;
;           float mu = s1 * (1.f / 512.f);
;           float var = s2 * (1.f / 512.f) - mu * mu;
;           float rstd = rsqrtf(fmaxf(var, 0.f) + 1e-5f);
; #pragma unroll
;           for (int bj = 0; bj < 2; ++bj)
; #pragma unroll
;             for (int n = 0; n < 2; ++n) {
;               float g = acc[ai][bj][m][n][j];
;               float yn = (bf2f(yv[j][bj][n]) - mu) * rstd * gn[bj][n];
;               Y[(long)(tb + j) * YS + pn * 256 + bj * 128 + wc * 32 + n * 16 + fr] = f2bf(silu_f(g) * yn);
	v_pk_add_f32 v[24:25], v[38:39], v[40:41]
	s_nop 0
	v_pk_add_f32 v[24:25], v[24:25], v[34:35]
	v_mul_f32_e32 v34, 0xbfb8aa3b, v14
	v_pk_add_f32 v[24:25], v[24:25], v[36:37]
	v_exp_f32_e32 v34, v34
	v_pk_mul_f32 v[24:25], v[24:25], s[18:19] op_sel_hi:[1,0]
	v_add_f32_e32 v34, 1.0, v34
	v_fma_f32 v0, -v24, v24, v25
	v_max_f32_e32 v0, 0, v0
	v_add_f32_e32 v0, 0x3727c5ac, v0
	v_cmp_gt_f32_e32 vcc, s25, v0
	v_mul_f32_e32 v25, 0x4b800000, v0
	v_rcp_f32_e32 v34, v34
	v_cndmask_b32_e32 v0, v0, v25, vcc
	v_rsq_f32_e32 v0, v0
	v_mul_f32_e32 v14, v14, v34
	v_mul_f32_e32 v34, 0xbfb8aa3b, v10
	v_mul_f32_e32 v25, 0x45800000, v0
	v_cndmask_b32_e32 v25, v0, v25, vcc
	v_exp_f32_e32 v34, v34
	v_lshlrev_b32_e32 v0, 16, v178
	v_sub_f32_e32 v0, v0, v24
	v_mul_f32_e32 v0, v0, v25
	v_mul_f32_e32 v0, v151, v0
	v_mul_f32_e32 v0, v14, v0
	v_add_f32_e32 v34, 1.0, v34
	v_rcp_f32_e32 v34, v34
	v_cvt_pk_bf16_f32 v0, v0, s0
	v_mul_f32_e32 v10, v10, v34
	v_mul_f32_e32 v34, 0xbfb8aa3b, v6
	v_exp_f32_e32 v34, v34
	v_lshlrev_b32_e32 v14, 16, v179
	v_sub_f32_e32 v14, v14, v24
	v_mul_f32_e32 v14, v14, v25
	v_mul_f32_e32 v14, v150, v14
	v_mul_f32_e32 v10, v10, v14
	v_add_f32_e32 v34, 1.0, v34
	v_rcp_f32_e32 v34, v34
	v_cvt_pk_bf16_f32 v10, v10, s0
	v_mul_f32_e32 v6, v6, v34
	v_lshlrev_b32_e32 v14, 16, v180
	v_sub_f32_e32 v14, v14, v24
	v_mul_f32_e32 v14, v14, v25
	v_mul_f32_e32 v14, v149, v14
	v_mul_f32_e32 v6, v6, v14
	v_cvt_pk_bf16_f32 v6, v6, s0
	v_lshlrev_b32_e32 v14, 16, v181
	v_sub_f32_e32 v14, v14, v24
	v_mul_f32_e32 v24, 0xbfb8aa3b, v2
	v_exp_f32_e32 v24, v24
	v_pk_add_f32 v[20:21], v[198:199], v[200:201]
	v_mul_f32_e32 v14, v14, v25
	v_pk_add_f32 v[20:21], v[20:21], v[194:195]
	v_add_f32_e32 v24, 1.0, v24
	v_rcp_f32_e32 v24, v24
	v_mul_f32_e32 v14, v148, v14
	v_pk_add_f32 v[20:21], v[20:21], v[196:197]
	v_mul_f32_e32 v2, v2, v24
	v_mul_f32_e32 v2, v2, v14
	v_pk_mul_f32 v[20:21], v[20:21], s[18:19] op_sel_hi:[1,0]
	v_cvt_pk_bf16_f32 v14, v2, s0
	v_fma_f32 v2, -v20, v20, v21
	v_max_f32_e32 v2, 0, v2
	v_add_f32_e32 v2, 0x3727c5ac, v2
	v_cmp_gt_f32_e32 vcc, s25, v2
	v_mul_f32_e32 v21, 0x4b800000, v2
	v_mul_f32_e32 v24, 0xbfb8aa3b, v15
	v_cndmask_b32_e32 v2, v2, v21, vcc
	v_rsq_f32_e32 v2, v2
	v_exp_f32_e32 v24, v24
	v_mul_f32_e32 v21, 0x45800000, v2
	v_cndmask_b32_e32 v2, v2, v21, vcc
	v_add_f32_e32 v24, 1.0, v24
	v_rcp_f32_e32 v24, v24
	v_lshlrev_b32_e32 v21, 16, v182
	v_sub_f32_e32 v21, v21, v20
	v_mul_f32_e32 v21, v21, v2
	v_mul_f32_e32 v21, v151, v21
	v_mul_f32_e32 v15, v15, v24
	v_mul_f32_e32 v15, v15, v21
	v_mul_f32_e32 v24, 0xbfb8aa3b, v11
	v_exp_f32_e32 v24, v24
	v_cvt_pk_bf16_f32 v15, v15, s0
	v_add_f32_e32 v24, 1.0, v24
	v_rcp_f32_e32 v24, v24
	v_lshlrev_b32_e32 v21, 16, v183
	v_sub_f32_e32 v21, v21, v20
	v_mul_f32_e32 v21, v21, v2
	v_mul_f32_e32 v21, v150, v21
	v_mul_f32_e32 v11, v11, v24
	v_mul_f32_e32 v11, v11, v21
	v_mul_f32_e32 v24, 0xbfb8aa3b, v7
	v_exp_f32_e32 v24, v24
	v_cvt_pk_bf16_f32 v11, v11, s0
	v_add_f32_e32 v24, 1.0, v24
	v_rcp_f32_e32 v24, v24
	v_lshlrev_b32_e32 v21, 16, v184
	v_sub_f32_e32 v21, v21, v20
	v_mul_f32_e32 v21, v21, v2
	v_mul_f32_e32 v21, v149, v21
	v_mul_f32_e32 v7, v7, v24
	v_mul_f32_e32 v7, v7, v21
	v_cvt_pk_bf16_f32 v7, v7, s0
	v_lshlrev_b32_e32 v21, 16, v185
	v_sub_f32_e32 v20, v21, v20
	v_mul_f32_e32 v2, v20, v2
	v_mul_f32_e32 v20, 0xbfb8aa3b, v3
	v_exp_f32_e32 v20, v20
	v_mul_f32_e32 v2, v148, v2
	v_add_f32_e32 v20, 1.0, v20
	v_rcp_f32_e32 v20, v20
	s_nop 0
	v_mul_f32_e32 v3, v3, v20
	s_nop 0
	v_mul_f32_e32 v2, v3, v2
	v_cvt_pk_bf16_f32 v34, v2, s0
	v_pk_add_f32 v[2:3], v[206:207], v[208:209]
	s_nop 0
	v_pk_add_f32 v[2:3], v[2:3], v[202:203]
	v_mul_f32_e32 v19, 0xbfb8aa3b, v16
	v_pk_add_f32 v[2:3], v[2:3], v[204:205]
	v_exp_f32_e32 v19, v19
	v_pk_mul_f32 v[2:3], v[2:3], s[18:19] op_sel_hi:[1,0]
	v_add_f32_e32 v19, 1.0, v19
	v_fma_f32 v3, -v2, v2, v3
	v_max_f32_e32 v3, 0, v3
	v_add_f32_e32 v3, 0x3727c5ac, v3
; #define MEMBAR asm volatile("" ::: "memory")
; __device__ __forceinline__ float bf2f(u16 b) { return __uint_as_float(((unsigned)b) << 16); }
; __device__ __forceinline__ float silu_f(float g) { return g * __builtin_amdgcn_rcpf(1.f + __builtin_amdgcn_exp2f(-g * LOG2E)); }
; template <int EPI>
; __device__ __forceinline__ void epilogue(const Params& p, int pass, int layer, int pm, int pn,
;                                          f32x4 (&acc)[2][2][4][2], const float* xin, float* xout) {
;     ...
; #pragma unroll
;         for (int j = 0; j < 4; ++j) {
;           const float4* sp = (const float4*)(stat + ((long)(tb + j) * 8 + h) * 8);
;           s01[j] = sp[0]; s23[j] = sp[1];
; #pragma unroll
;           for (int bj = 0; bj < 2; ++bj)
; #pragma unroll
;             for (int n = 0; n < 2; ++n)
;               yv[j][bj][n] = Y[(long)(tb + j) * YS + pn * 256 + bj * 128 + wc * 32 + n * 16 + fr];
;         }
; #pragma unroll
;         for (int j = 0; j < 4; ++j) {
;           float s1 = s01[j].x + s01[j].z + s23[j].x + s23[j].z, s2 = s01[j].y + s01[j].w + s23[j].y + s23[j].w;
;           float mu = s1 * (1.f / 512.f);
;           float var = s2 * (1.f / 512.f) - mu * mu;
;           float rstd = rsqrtf(fmaxf(var, 0.f) + 1e-5f);
; #pragma unroll
;           for (int bj = 0; bj < 2; ++bj)
; #pragma unroll
;             for (int n = 0; n < 2; ++n) {
;               float g = acc[ai][bj][m][n][j];
;               float yn = (bf2f(yv[j][bj][n]) - mu) * rstd * gn[bj][n];
;               Y[(long)(tb + j) * YS + pn * 256 + bj * 128 + wc * 32 + n * 16 + fr] = f2bf(silu_f(g) * yn);
;             }
;         }
;         MEMBAR;
	v_cmp_gt_f32_e32 vcc, s25, v3
	v_mul_f32_e32 v18, 0x4b800000, v3
	v_rcp_f32_e32 v19, v19
	v_cndmask_b32_e32 v3, v3, v18, vcc
	v_rsq_f32_e32 v3, v3
	v_mul_f32_e32 v16, v16, v19
	v_mul_f32_e32 v19, 0xbfb8aa3b, v12
	v_mul_f32_e32 v18, 0x45800000, v3
	v_cndmask_b32_e32 v18, v3, v18, vcc
	v_exp_f32_e32 v19, v19
	v_lshlrev_b32_e32 v3, 16, v186
	v_sub_f32_e32 v3, v3, v2
	v_mul_f32_e32 v3, v3, v18
	v_mul_f32_e32 v3, v151, v3
	v_mul_f32_e32 v3, v16, v3
	v_add_f32_e32 v19, 1.0, v19
	v_rcp_f32_e32 v19, v19
	v_cvt_pk_bf16_f32 v3, v3, s0
	v_mul_f32_e32 v12, v12, v19
	v_mul_f32_e32 v19, 0xbfb8aa3b, v8
	v_exp_f32_e32 v19, v19
	v_lshlrev_b32_e32 v16, 16, v187
	v_sub_f32_e32 v16, v16, v2
	v_mul_f32_e32 v16, v16, v18
	v_mul_f32_e32 v16, v150, v16
	v_mul_f32_e32 v12, v12, v16
	v_add_f32_e32 v19, 1.0, v19
	v_rcp_f32_e32 v19, v19
	v_cvt_pk_bf16_f32 v12, v12, s0
	v_mul_f32_e32 v8, v8, v19
	v_lshlrev_b32_e32 v16, 16, v188
	v_sub_f32_e32 v16, v16, v2
	v_mul_f32_e32 v16, v16, v18
	v_mul_f32_e32 v16, v149, v16
	v_mul_f32_e32 v8, v8, v16
	v_cvt_pk_bf16_f32 v8, v8, s0
	v_lshlrev_b32_e32 v16, 16, v189
	v_sub_f32_e32 v2, v16, v2
	v_mul_f32_e32 v16, 0xbfb8aa3b, v4
	v_exp_f32_e32 v16, v16
	v_mul_f32_e32 v2, v2, v18
	v_mul_f32_e32 v2, v148, v2
	v_add_f32_e32 v16, 1.0, v16
	v_rcp_f32_e32 v16, v16
	s_nop 0
	v_mul_f32_e32 v4, v4, v16
	v_mul_f32_e32 v2, v4, v2
	s_nop 0
	s_nop 0
	v_cvt_pk_bf16_f32 v2, v2, s0
	global_store_short v[28:29], v0, off
	global_store_short v[28:29], v10, off offset:32
	global_store_short v[28:29], v6, off offset:256
	global_store_short v[28:29], v14, off offset:288
	global_store_short v[30:31], v15, off
	global_store_short v[30:31], v11, off offset:32
	global_store_short v[30:31], v7, off offset:256
	global_store_short v[30:31], v34, off offset:288
	global_store_short v[32:33], v3, off
	global_store_short v[32:33], v12, off offset:32
	global_store_short v[32:33], v8, off offset:256
	global_store_short v[32:33], v2, off offset:288
	v_pk_add_f32 v[2:3], v[214:215], v[216:217]
	s_nop 0
	v_pk_add_f32 v[2:3], v[2:3], v[210:211]
	s_nop 0
	v_pk_add_f32 v[2:3], v[2:3], v[212:213]
	s_nop 0
	v_pk_mul_f32 v[2:3], v[2:3], s[18:19] op_sel_hi:[1,0]
	s_nop 0
	v_fma_f32 v0, -v2, v2, v3
	v_max_f32_e32 v0, 0, v0
	v_add_f32_e32 v0, 0x3727c5ac, v0
	v_cmp_gt_f32_e32 vcc, s25, v0
	v_mul_f32_e32 v3, 0x4b800000, v0
	s_nop 0
	v_cndmask_b32_e32 v0, v0, v3, vcc
	v_rsq_f32_e32 v0, v0
	s_nop 0
	v_mul_f32_e32 v3, 0x45800000, v0
	v_cndmask_b32_e32 v0, v0, v3, vcc
	v_lshlrev_b32_e32 v3, 16, v190
	v_mul_f32_e32 v4, 0xbfb8aa3b, v17
	v_exp_f32_e32 v4, v4
	v_sub_f32_e32 v3, v3, v2
	v_mul_f32_e32 v3, v3, v0
	v_mul_f32_e32 v3, v151, v3
	v_add_f32_e32 v4, 1.0, v4
	v_rcp_f32_e32 v4, v4
	s_and_b64 vcc, exec, s[4:5]
	v_mul_f32_e32 v4, v17, v4
	v_mul_f32_e32 v3, v4, v3
	v_mul_f32_e32 v4, 0xbfb8aa3b, v13
	v_exp_f32_e32 v4, v4
	v_cvt_pk_bf16_f32 v3, v3, s0
	global_store_short v[26:27], v3, off
	v_lshlrev_b32_e32 v3, 16, v191
	v_add_f32_e32 v4, 1.0, v4
	v_rcp_f32_e32 v4, v4
	v_sub_f32_e32 v3, v3, v2
	v_mul_f32_e32 v3, v3, v0
	v_mul_f32_e32 v3, v150, v3
	v_mul_f32_e32 v4, v13, v4
	v_mul_f32_e32 v3, v4, v3
	v_mul_f32_e32 v4, 0xbfb8aa3b, v9
	v_exp_f32_e32 v4, v4
	v_cvt_pk_bf16_f32 v3, v3, s0
	global_store_short v[26:27], v3, off offset:32
	v_lshlrev_b32_e32 v3, 16, v192
	v_add_f32_e32 v4, 1.0, v4
	v_rcp_f32_e32 v4, v4
	v_sub_f32_e32 v3, v3, v2
	v_mul_f32_e32 v3, v3, v0
	v_mul_f32_e32 v3, v149, v3
	v_mul_f32_e32 v4, v9, v4
	v_mul_f32_e32 v3, v4, v3
	v_cvt_pk_bf16_f32 v3, v3, s0
	global_store_short v[26:27], v3, off offset:256
	v_lshlrev_b32_e32 v3, 16, v193
	v_sub_f32_e32 v2, v3, v2
	v_mul_f32_e32 v0, v2, v0
	v_mul_f32_e32 v2, 0xbfb8aa3b, v5
	v_exp_f32_e32 v2, v2
	v_mul_f32_e32 v0, v148, v0
	v_add_f32_e32 v2, 1.0, v2
	v_rcp_f32_e32 v2, v2
	s_nop 0
	v_mul_f32_e32 v2, v5, v2
	v_mul_f32_e32 v0, v2, v0
	v_cvt_pk_bf16_f32 v0, v0, s0
	global_store_short v[26:27], v0, off offset:288
	s_cbranch_vccnz .LBB0_66

; #define SB0 __builtin_amdgcn_sched_barrier(0)
; __device__ __forceinline__ void phase_spatial(const Params& p) {
;     ...
;       const char* vbase = (const char*)(VT1 + ((long)chunk * 6144 + g * 768 + csub * 256) * 128);
;       const char* ubase = (const char*)(U + (long)t0 * 6144 + g * 768 + csub * 256);
; #pragma unroll
;       for (int mb = 0; mb < 2; ++mb)
; #pragma unroll
;         for (int ks = 0; ks < 4; ++ks)
;           va[mb][ks] = *(const bf16x8*)(vbase + (mb * 16 * 128 + ks * 32) * 2 + (unsigned)(((wid * 32 + fr) * 128 + fq * 8) * 2));
; #pragma unroll
;       for (int mb = 0; mb < 2; ++mb) {
;         int c0 = cbase + mb * 16 + fq * 4;
;         lg[mb] = *(const float4*)(p.sgu_ln_g + c0);
;         lbv[mb] = *(const float4*)(p.sgu_ln_b + c0);
; #pragma unroll
;         for (int nb = 0; nb < 8; ++nb)
;           uu[mb][nb] = *(const uint2*)(ubase + (nb * 16 * 6144 + mb * 16) * 2 + (unsigned)((fr * 6144 + wid * 32 + fq * 4) * 2));
;       }
;       SB0;
;       f32x4 acc[2][8];
; #pragma unroll
;       for (int a = 0; a < 2; ++a)
; #pragma unroll
;         for (int b = 0; b < 8; ++b) acc[a][b] = f32x4{0.f, 0.f, 0.f, 0.f};
; #pragma unroll
;       for (int ks = 0; ks < 4; ++ks)
; #pragma unroll
;         for (int nb = 0; nb < 8; ++nb) {
;           bf16x8 b = *(const bf16x8*)(Wl + (nb * 16 + fr) * 136 + ks * 32 + fq * 8);
; #pragma unroll
;           for (int mb = 0; mb < 2; ++mb) acc[mb][nb] = mfma16(va[mb][ks], b, acc[mb][nb]);
;         }
.LBB0_232:
	global_load_dword v220, v[86:87], off
	global_load_dword v221, v[86:87], off offset:64
	global_load_dword v222, v[86:87], off offset:128
	global_load_dword v223, v[86:87], off offset:192
	global_load_dword v224, v[86:87], off offset:256
	global_load_dword v225, v[86:87], off offset:320
	global_load_dword v226, v[86:87], off offset:384
	global_load_dword v227, v[86:87], off offset:448
	global_load_dword v228, v[86:87], off
	global_load_dword v229, v[86:87], off offset:64
	global_load_dword v230, v[86:87], off offset:128
	global_load_dword v231, v[86:87], off offset:192
	global_load_dword v232, v[86:87], off offset:256
	global_load_dword v233, v[86:87], off offset:320
	global_load_dword v234, v[86:87], off offset:384
	global_load_dword v235, v[86:87], off offset:448
	v_lshl_add_u64 v[2:3], s[96:97], 0, v[90:91]
	v_add_co_u32_e32 v4, vcc, 0x14800000, v2
	s_nop 1
	v_addc_co_u32_e32 v5, vcc, 0, v3, vcc
	v_add_co_u32_e32 v2, vcc, 0x14801000, v2
	global_load_dwordx4 v[30:33], v[4:5], off
	global_load_dwordx4 v[18:21], v[4:5], off offset:64
	global_load_dwordx4 v[10:13], v[4:5], off offset:128
	global_load_dwordx4 v[6:9], v[4:5], off offset:192
	v_addc_co_u32_e32 v3, vcc, 0, v3, vcc
	v_lshl_add_u64 v[4:5], s[96:97], 0, v[88:89]
	v_add_co_u32_e32 v38, vcc, s3, v4
	global_load_dwordx4 v[34:37], v[2:3], off
	global_load_dwordx4 v[22:25], v[2:3], off offset:64
	global_load_dwordx4 v[14:17], v[2:3], off offset:128
	global_load_dwordx4 v[66:69], v[2:3], off offset:192
	v_addc_co_u32_e32 v39, vcc, 0, v5, vcc
	v_add_co_u32_e32 v40, vcc, s10, v4
	v_add_u32_e32 v2, s2, v137
	s_nop 0
	v_addc_co_u32_e32 v41, vcc, 0, v5, vcc
	v_add_co_u32_e32 v46, vcc, s11, v4
	v_ashrrev_i32_e32 v3, 31, v2
	s_nop 0
	v_addc_co_u32_e32 v47, vcc, 0, v5, vcc
	v_add_co_u32_e32 v48, vcc, s12, v4
	v_lshlrev_b64 v[2:3], 2, v[2:3]
	s_nop 0
	v_addc_co_u32_e32 v49, vcc, 0, v5, vcc
	v_add_co_u32_e32 v50, vcc, s13, v4
	v_lshl_add_u64 v[26:27], s[22:23], 0, v[2:3]
	s_nop 0
	v_addc_co_u32_e32 v51, vcc, 0, v5, vcc
	v_add_co_u32_e32 v52, vcc, s14, v4
	v_lshl_add_u64 v[28:29], s[24:25], 0, v[2:3]
	s_nop 0
	v_addc_co_u32_e32 v53, vcc, 0, v5, vcc
	v_add_co_u32_e32 v54, vcc, s15, v4
	s_nop 1
	v_addc_co_u32_e32 v55, vcc, 0, v5, vcc
	v_add_co_u32_e32 v56, vcc, s16, v4
	s_nop 1
	v_addc_co_u32_e32 v57, vcc, 0, v5, vcc
	global_load_dwordx4 v[42:45], v[26:27], off
	global_load_dwordx4 v[2:5], v[26:27], off offset:64
	global_load_dwordx4 v[62:65], v[28:29], off
	s_nop 0
	global_load_dwordx4 v[26:29], v[28:29], off offset:64
	s_nop 0
	global_load_dwordx2 v[134:135], v[38:39], off
	global_load_dwordx2 v[132:133], v[40:41], off
	global_load_dwordx2 v[106:107], v[40:41], off offset:32
	global_load_dwordx2 v[108:109], v[38:39], off offset:32
	global_load_dwordx2 v[130:131], v[46:47], off
	global_load_dwordx2 v[124:125], v[48:49], off
	global_load_dwordx2 v[102:103], v[48:49], off offset:32
	global_load_dwordx2 v[104:105], v[46:47], off offset:32
	global_load_dwordx2 v[120:121], v[50:51], off
	global_load_dwordx2 v[118:119], v[52:53], off
	global_load_dwordx2 v[98:99], v[52:53], off offset:32
	global_load_dwordx2 v[100:101], v[50:51], off offset:32
	global_load_dwordx2 v[116:117], v[54:55], off
	global_load_dwordx2 v[114:115], v[56:57], off
	global_load_dwordx2 v[94:95], v[56:57], off offset:32
	global_load_dwordx2 v[96:97], v[54:55], off offset:32
	ds_read_b128 v[38:41], v0
	ds_read_b128 v[50:53], v0 offset:4352
	ds_read_b128 v[58:61], v0 offset:8704
	ds_read_b128 v[74:77], v0 offset:13056
	ds_read_b128 v[82:85], v0 offset:17408
	ds_read_b128 v[126:129], v0 offset:21760
	ds_read_b128 v[142:145], v0 offset:26112
	ds_read_b128 v[150:153], v0 offset:30464
	s_waitcnt vmcnt(27) lgkmcnt(7)
	v_mfma_f32_16x16x32_bf16 v[46:49], v[30:33], v[38:41], 0
	s_waitcnt vmcnt(23)
	v_mfma_f32_16x16x32_bf16 v[38:41], v[34:37], v[38:41], 0
	s_waitcnt lgkmcnt(6)
	v_mfma_f32_16x16x32_bf16 v[54:57], v[30:33], v[50:53], 0
	v_mfma_f32_16x16x32_bf16 v[50:53], v[34:37], v[50:53], 0
	s_waitcnt lgkmcnt(5)
	v_mfma_f32_16x16x32_bf16 v[70:73], v[30:33], v[58:61], 0
	v_mfma_f32_16x16x32_bf16 v[58:61], v[34:37], v[58:61], 0
	s_waitcnt lgkmcnt(4)
	v_mfma_f32_16x16x32_bf16 v[78:81], v[30:33], v[74:77], 0
	v_mfma_f32_16x16x32_bf16 v[74:77], v[34:37], v[74:77], 0
	s_waitcnt lgkmcnt(3)
	v_mfma_f32_16x16x32_bf16 v[110:113], v[30:33], v[82:85], 0
	v_mfma_f32_16x16x32_bf16 v[82:85], v[34:37], v[82:85], 0
	s_waitcnt lgkmcnt(2)
	v_mfma_f32_16x16x32_bf16 v[138:141], v[30:33], v[126:129], 0
	v_mfma_f32_16x16x32_bf16 v[126:129], v[34:37], v[126:129], 0
	s_waitcnt lgkmcnt(1)
	v_mfma_f32_16x16x32_bf16 v[146:149], v[30:33], v[142:145], 0
	v_mfma_f32_16x16x32_bf16 v[142:145], v[34:37], v[142:145], 0
	s_waitcnt lgkmcnt(0)
	v_mfma_f32_16x16x32_bf16 v[30:33], v[30:33], v[150:153], 0
	v_mfma_f32_16x16x32_bf16 v[34:37], v[34:37], v[150:153], 0
	ds_read_b128 v[150:153], v0 offset:64
	s_waitcnt lgkmcnt(0)
	v_mfma_f32_16x16x32_bf16 v[46:49], v[18:21], v[150:153], v[46:49]
	s_waitcnt vmcnt(22)
	v_mfma_f32_16x16x32_bf16 v[38:41], v[22:25], v[150:153], v[38:41]
	ds_read_b128 v[150:153], v0 offset:4416
	s_waitcnt lgkmcnt(0)
	v_mfma_f32_16x16x32_bf16 v[54:57], v[18:21], v[150:153], v[54:57]
	v_mfma_f32_16x16x32_bf16 v[50:53], v[22:25], v[150:153], v[50:53]
	ds_read_b128 v[150:153], v0 offset:8768
	s_waitcnt lgkmcnt(0)
	v_mfma_f32_16x16x32_bf16 v[70:73], v[18:21], v[150:153], v[70:73]
	v_mfma_f32_16x16x32_bf16 v[58:61], v[22:25], v[150:153], v[58:61]
	ds_read_b128 v[150:153], v0 offset:13120
	s_waitcnt lgkmcnt(0)
	v_mfma_f32_16x16x32_bf16 v[78:81], v[18:21], v[150:153], v[78:81]
	v_mfma_f32_16x16x32_bf16 v[74:77], v[22:25], v[150:153], v[74:77]
	ds_read_b128 v[150:153], v0 offset:17472
	s_waitcnt lgkmcnt(0)
; __device__ __forceinline__ float bf2f(u16 b) { return __uint_as_float(((unsigned)b) << 16); }
; #define SB0 __builtin_amdgcn_sched_barrier(0)
; __device__ __forceinline__ void phase_spatial(const Params& p) {
;     ...
; #pragma unroll
;       for (int ks = 0; ks < 4; ++ks)
; #pragma unroll
;         for (int nb = 0; nb < 8; ++nb) {
;           bf16x8 b = *(const bf16x8*)(Wl + (nb * 16 + fr) * 136 + ks * 32 + fq * 8);
; #pragma unroll
;           for (int mb = 0; mb < 2; ++mb) acc[mb][nb] = mfma16(va[mb][ks], b, acc[mb][nb]);
;         }
;       SB0;
; #pragma unroll
;       for (int mb = 0; mb < 2; ++mb)
; #pragma unroll
;         for (int nb = 0; nb < 8; ++nb) {
;           int i = nb * 16 + fr;
;           float bsi = p.sgu_b_s[g * 128 + i];
;           float s0i = s0[i], s1i = s1[i];
;           f32x4 a = acc[mb][nb];
;           float m0 = lg[mb].x * (a[0] - s1i) + lbv[mb].x * s0i + bsi;
;           float m1 = lg[mb].y * (a[1] - s1i) + lbv[mb].y * s0i + bsi;
;           float m2 = lg[mb].z * (a[2] - s1i) + lbv[mb].z * s0i + bsi;
;           float m3 = lg[mb].w * (a[3] - s1i) + lbv[mb].w * s0i + bsi;
;           uint2 u2 = uu[mb][nb];
;           float u0 = bf2f((u16)(u2.x & 0xffff)), u1 = bf2f((u16)(u2.x >> 16));
;           float u2f = bf2f((u16)(u2.y & 0xffff)), u3 = bf2f((u16)(u2.y >> 16));
;           *(uint2*)(ubase + (nb * 16 * 6144 + mb * 16) * 2 + (unsigned)((fr * 6144 + wid * 32 + fq * 4) * 2)) =
;               make_uint2(pack2(u0 * m0, u1 * m1), pack2(u2f * m2, u3 * m3));
	v_mfma_f32_16x16x32_bf16 v[110:113], v[18:21], v[150:153], v[110:113]
	v_mfma_f32_16x16x32_bf16 v[82:85], v[22:25], v[150:153], v[82:85]
	ds_read_b128 v[150:153], v0 offset:21824
	s_waitcnt lgkmcnt(0)
	v_mfma_f32_16x16x32_bf16 v[138:141], v[18:21], v[150:153], v[138:141]
	v_mfma_f32_16x16x32_bf16 v[126:129], v[22:25], v[150:153], v[126:129]
	ds_read_b128 v[150:153], v0 offset:26176
	s_waitcnt lgkmcnt(0)
	v_mfma_f32_16x16x32_bf16 v[146:149], v[18:21], v[150:153], v[146:149]
	v_mfma_f32_16x16x32_bf16 v[142:145], v[22:25], v[150:153], v[142:145]
	ds_read_b128 v[150:153], v0 offset:30528
	s_waitcnt lgkmcnt(0)
	v_mfma_f32_16x16x32_bf16 v[18:21], v[18:21], v[150:153], v[30:33]
	s_nop 2
	ds_read_b128 v[30:33], v0 offset:128
	v_mfma_f32_16x16x32_bf16 v[22:25], v[22:25], v[150:153], v[34:37]
	s_waitcnt lgkmcnt(0)
	v_mfma_f32_16x16x32_bf16 v[34:37], v[10:13], v[30:33], v[46:49]
	s_waitcnt vmcnt(21)
	v_mfma_f32_16x16x32_bf16 v[30:33], v[14:17], v[30:33], v[38:41]
	s_nop 2
	ds_read_b128 v[38:41], v0 offset:4480
	s_waitcnt lgkmcnt(0)
	v_mfma_f32_16x16x32_bf16 v[46:49], v[10:13], v[38:41], v[54:57]
	v_mfma_f32_16x16x32_bf16 v[50:53], v[14:17], v[38:41], v[50:53]
	ds_read_b128 v[38:41], v0 offset:8832
	s_waitcnt lgkmcnt(0)
	v_mfma_f32_16x16x32_bf16 v[54:57], v[10:13], v[38:41], v[70:73]
	v_mfma_f32_16x16x32_bf16 v[58:61], v[14:17], v[38:41], v[58:61]
	ds_read_b128 v[38:41], v0 offset:13184
	s_waitcnt lgkmcnt(0)
	v_mfma_f32_16x16x32_bf16 v[70:73], v[10:13], v[38:41], v[78:81]
	v_mfma_f32_16x16x32_bf16 v[150:153], v[14:17], v[38:41], v[74:77]
	ds_read_b128 v[38:41], v0 offset:17536
	s_waitcnt lgkmcnt(0)
	v_mfma_f32_16x16x32_bf16 v[110:113], v[10:13], v[38:41], v[110:113]
	v_mfma_f32_16x16x32_bf16 v[154:157], v[14:17], v[38:41], v[82:85]
	ds_read_b128 v[38:41], v0 offset:21888
	s_waitcnt lgkmcnt(0)
	v_mfma_f32_16x16x32_bf16 v[138:141], v[10:13], v[38:41], v[138:141]
	v_mfma_f32_16x16x32_bf16 v[126:129], v[14:17], v[38:41], v[126:129]
	ds_read_b128 v[38:41], v0 offset:26240
	s_waitcnt lgkmcnt(0)
	v_mfma_f32_16x16x32_bf16 v[146:149], v[10:13], v[38:41], v[146:149]
	v_mfma_f32_16x16x32_bf16 v[142:145], v[14:17], v[38:41], v[142:145]
	ds_read_b128 v[38:41], v0 offset:30592
	s_waitcnt lgkmcnt(0)
	v_mfma_f32_16x16x32_bf16 v[158:161], v[10:13], v[38:41], v[18:21]
	ds_read_b128 v[10:13], v0 offset:192
	v_mfma_f32_16x16x32_bf16 v[162:165], v[14:17], v[38:41], v[22:25]
	s_waitcnt lgkmcnt(0)
	v_mfma_f32_16x16x32_bf16 v[82:85], v[6:9], v[10:13], v[34:37]
	s_waitcnt vmcnt(20)
	v_mfma_f32_16x16x32_bf16 v[38:41], v[66:69], v[10:13], v[30:33]
	ds_read_b128 v[10:13], v0 offset:4544
	s_waitcnt lgkmcnt(0)
	v_mfma_f32_16x16x32_bf16 v[78:81], v[6:9], v[10:13], v[46:49]
	v_mfma_f32_16x16x32_bf16 v[34:37], v[66:69], v[10:13], v[50:53]
	ds_read_b128 v[10:13], v0 offset:8896
	s_waitcnt lgkmcnt(0)
	v_mfma_f32_16x16x32_bf16 v[74:77], v[6:9], v[10:13], v[54:57]
	v_mfma_f32_16x16x32_bf16 v[30:33], v[66:69], v[10:13], v[58:61]
	ds_read_b128 v[10:13], v0 offset:13248
	s_waitcnt lgkmcnt(0)
	v_mfma_f32_16x16x32_bf16 v[70:73], v[6:9], v[10:13], v[70:73]
	v_mfma_f32_16x16x32_bf16 v[22:25], v[66:69], v[10:13], v[150:153]
	ds_read_b128 v[10:13], v0 offset:17600
	s_waitcnt lgkmcnt(0)
	v_mfma_f32_16x16x32_bf16 v[58:61], v[6:9], v[10:13], v[110:113]
	s_nop 2
	ds_read_b128 v[110:113], v0 offset:30656
	v_mfma_f32_16x16x32_bf16 v[18:21], v[66:69], v[10:13], v[154:157]
	ds_read_b128 v[10:13], v0 offset:21952
	s_waitcnt lgkmcnt(0)
	v_mfma_f32_16x16x32_bf16 v[54:57], v[6:9], v[10:13], v[138:141]
	v_mfma_f32_16x16x32_bf16 v[14:17], v[66:69], v[10:13], v[126:129]
	ds_read_b128 v[10:13], v0 offset:26304
	s_waitcnt lgkmcnt(0)
	v_mfma_f32_16x16x32_bf16 v[50:53], v[6:9], v[10:13], v[146:149]
	v_mfma_f32_16x16x32_bf16 v[10:13], v[66:69], v[10:13], v[142:145]
	v_mfma_f32_16x16x32_bf16 v[46:49], v[6:9], v[110:113], v[158:161]
	v_mfma_f32_16x16x32_bf16 v[6:9], v[66:69], v[110:113], v[162:165]
	v_add_u32_e32 v138, 0x8c00, v136
	ds_read2_b32 v[110:111], v138 offset1:16
	ds_read2_b32 v[112:113], v138 offset0:128 offset1:144
	s_waitcnt vmcnt(17)
	v_mov_b32_e32 v126, v62
	v_mov_b32_e32 v127, v42
	v_mov_b32_e32 v128, v64
	s_waitcnt lgkmcnt(1)
	v_mov_b32_e32 v66, v110
	s_waitcnt lgkmcnt(0)
	v_sub_f32_e32 v67, v82, v112
	v_pk_mul_f32 v[66:67], v[126:127], v[66:67]
	v_mov_b32_e32 v129, v44
	v_add_f32_e32 v42, v66, v67
	v_sub_f32_e32 v67, v83, v112
	v_mov_b32_e32 v66, v110
	v_lshl_add_u64 v[122:123], s[96:97], 0, v[92:93]
	v_add_co_u32_e32 v82, vcc, s3, v122
	v_sub_f32_e32 v39, v39, v112
	s_nop 0
	v_addc_co_u32_e32 v83, vcc, 0, v123, vcc
	s_addk_i32 s2, 0x100
	s_mov_b64 s[4:5], 0x10000
	v_lshl_add_u64 v[88:89], v[88:89], 0, s[18:19]
	v_lshl_add_u64 v[90:91], v[90:91], 0, s[4:5]
	v_lshl_add_u64 v[92:93], v[92:93], 0, s[18:19]
	s_cmpk_eq_i32 s2, 0x300
	s_waitcnt vmcnt(0)
; __device__ __forceinline__ float bf2f(u16 b) { return __uint_as_float(((unsigned)b) << 16); }
; __device__ __forceinline__ void phase_spatial(const Params& p) {
;     ...
;       for (int mb = 0; mb < 2; ++mb)
; #pragma unroll
;         for (int nb = 0; nb < 8; ++nb) {
;           int i = nb * 16 + fr;
;           float bsi = p.sgu_b_s[g * 128 + i];
;           float s0i = s0[i], s1i = s1[i];
;           f32x4 a = acc[mb][nb];
;           float m0 = lg[mb].x * (a[0] - s1i) + lbv[mb].x * s0i + bsi;
;           float m1 = lg[mb].y * (a[1] - s1i) + lbv[mb].y * s0i + bsi;
;           float m2 = lg[mb].z * (a[2] - s1i) + lbv[mb].z * s0i + bsi;
;           float m3 = lg[mb].w * (a[3] - s1i) + lbv[mb].w * s0i + bsi;
;           uint2 u2 = uu[mb][nb];
;           float u0 = bf2f((u16)(u2.x & 0xffff)), u1 = bf2f((u16)(u2.x >> 16));
;           float u2f = bf2f((u16)(u2.y & 0xffff)), u3 = bf2f((u16)(u2.y >> 16));
;           *(uint2*)(ubase + (nb * 16 * 6144 + mb * 16) * 2 + (unsigned)((fr * 6144 + wid * 32 + fq * 4) * 2)) =
;               make_uint2(pack2(u0 * m0, u1 * m1), pack2(u2f * m2, u3 * m3));
	v_add_f32_e32 v69, v220, v42
	v_mov_b32_e32 v42, v63
	v_pk_mul_f32 v[62:63], v[42:43], v[66:67]
	v_lshlrev_b32_e32 v67, 16, v135
	v_add_f32_e32 v62, v62, v63
	v_add_f32_e32 v66, v220, v62
	v_sub_f32_e32 v63, v84, v112
	v_mov_b32_e32 v62, v110
	v_pk_mul_f32 v[62:63], v[128:129], v[62:63]
	s_nop 0
	v_add_f32_e32 v44, v62, v63
	v_add_f32_e32 v64, v220, v44
	v_sub_f32_e32 v63, v85, v112
	v_mov_b32_e32 v44, v65
	v_mov_b32_e32 v62, v110
	v_pk_mul_f32 v[62:63], v[44:45], v[62:63]
	v_and_b32_e32 v65, 0xffff0000, v134
	v_add_f32_e32 v62, v62, v63
	v_add_f32_e32 v63, v220, v62
	v_lshlrev_b32_e32 v62, 16, v134
	v_and_b32_e32 v68, 0xffff0000, v135
	v_mul_f32_e32 v62, v69, v62
	v_mul_f32_e32 v65, v66, v65
	v_mul_f32_e32 v64, v64, v67
	v_mul_f32_e32 v63, v63, v68
	v_cvt_pk_bf16_f32 v62, v62, v65
	v_cvt_pk_bf16_f32 v63, v64, v63
	global_store_dwordx2 v[82:83], v[62:63], off
	v_sub_f32_e32 v63, v78, v113
	v_mov_b32_e32 v62, v111
	v_pk_mul_f32 v[62:63], v[126:127], v[62:63]
	v_lshlrev_b32_e32 v68, 16, v133
	v_add_f32_e32 v62, v62, v63
	v_sub_f32_e32 v63, v79, v113
	v_and_b32_e32 v69, 0xffff0000, v133
	v_add_co_u32_e32 v78, vcc, s10, v122
	v_add_f32_e32 v65, v221, v62
	v_mov_b32_e32 v62, v111
	v_pk_mul_f32 v[62:63], v[42:43], v[62:63]
	v_addc_co_u32_e32 v79, vcc, 0, v123, vcc
	v_add_f32_e32 v62, v62, v63
	v_add_f32_e32 v66, v221, v62
	v_sub_f32_e32 v63, v80, v113
	v_mov_b32_e32 v62, v111
	v_pk_mul_f32 v[62:63], v[128:129], v[62:63]
	s_nop 0
	v_add_f32_e32 v62, v62, v63
	v_add_f32_e32 v67, v221, v62
	v_sub_f32_e32 v63, v81, v113
	v_mov_b32_e32 v62, v111
	v_pk_mul_f32 v[62:63], v[44:45], v[62:63]
	s_nop 0
	v_add_f32_e32 v62, v62, v63
	v_add_f32_e32 v63, v221, v62
	v_lshlrev_b32_e32 v62, 16, v132
	v_and_b32_e32 v64, 0xffff0000, v132
	v_mul_f32_e32 v62, v65, v62
	v_mul_f32_e32 v64, v66, v64
	v_cvt_pk_bf16_f32 v62, v62, v64
	v_mul_f32_e32 v64, v67, v68
	v_mul_f32_e32 v63, v63, v69
	v_cvt_pk_bf16_f32 v63, v64, v63
	global_store_dwordx2 v[78:79], v[62:63], off
	ds_read2_b32 v[66:67], v138 offset0:32 offset1:48
	ds_read2_b32 v[68:69], v138 offset0:160 offset1:176
	s_waitcnt lgkmcnt(1)
	v_mov_b32_e32 v62, v66
	s_waitcnt lgkmcnt(0)
	v_sub_f32_e32 v63, v74, v68
	v_pk_mul_f32 v[62:63], v[126:127], v[62:63]
	v_sub_f32_e32 v23, v23, v69
	v_add_f32_e32 v62, v62, v63
	v_sub_f32_e32 v63, v75, v68
	v_add_f32_e32 v65, v222, v62
	v_mov_b32_e32 v62, v66
	v_pk_mul_f32 v[62:63], v[42:43], v[62:63]
	s_nop 0
	v_add_f32_e32 v62, v62, v63
	v_add_f32_e32 v74, v222, v62
	v_sub_f32_e32 v63, v76, v68
	v_mov_b32_e32 v62, v66
	v_pk_mul_f32 v[62:63], v[128:129], v[62:63]
	v_lshlrev_b32_e32 v76, 16, v131
	v_add_f32_e32 v62, v62, v63
	v_add_f32_e32 v75, v222, v62
	v_sub_f32_e32 v63, v77, v68
	v_mov_b32_e32 v62, v66
	v_pk_mul_f32 v[62:63], v[44:45], v[62:63]
	v_and_b32_e32 v77, 0xffff0000, v131
	v_add_f32_e32 v62, v62, v63
	v_add_f32_e32 v63, v222, v62
	v_lshlrev_b32_e32 v62, 16, v130
	v_and_b32_e32 v64, 0xffff0000, v130
	v_mul_f32_e32 v62, v65, v62
	v_mul_f32_e32 v64, v74, v64
	v_cvt_pk_bf16_f32 v62, v62, v64
	v_mul_f32_e32 v64, v75, v76
	v_mul_f32_e32 v63, v63, v77
	v_add_co_u32_e32 v74, vcc, s11, v122
	v_cvt_pk_bf16_f32 v63, v64, v63
	s_nop 0
	v_addc_co_u32_e32 v75, vcc, 0, v123, vcc
	global_store_dwordx2 v[74:75], v[62:63], off
	v_sub_f32_e32 v63, v70, v69
	v_mov_b32_e32 v62, v67
	v_pk_mul_f32 v[62:63], v[126:127], v[62:63]
	v_and_b32_e32 v77, 0xffff0000, v121
	v_add_f32_e32 v62, v62, v63
	v_sub_f32_e32 v63, v71, v69
	v_add_f32_e32 v65, v223, v62
	v_mov_b32_e32 v62, v67
	v_pk_mul_f32 v[62:63], v[42:43], v[62:63]
	s_nop 0
	v_add_f32_e32 v62, v62, v63
	v_add_f32_e32 v70, v223, v62
	v_sub_f32_e32 v63, v72, v69
	v_mov_b32_e32 v62, v67
	v_pk_mul_f32 v[62:63], v[128:129], v[62:63]
	v_lshlrev_b32_e32 v72, 16, v125
	v_add_f32_e32 v62, v62, v63
	v_add_f32_e32 v71, v223, v62
	v_sub_f32_e32 v63, v73, v69
	v_mov_b32_e32 v62, v67
	v_pk_mul_f32 v[62:63], v[44:45], v[62:63]
	v_and_b32_e32 v73, 0xffff0000, v125
	v_add_f32_e32 v62, v62, v63
	v_add_f32_e32 v63, v223, v62
	v_lshlrev_b32_e32 v62, 16, v124
	v_and_b32_e32 v64, 0xffff0000, v124
	v_mul_f32_e32 v62, v65, v62
	v_mul_f32_e32 v64, v70, v64
	v_cvt_pk_bf16_f32 v62, v62, v64
	v_mul_f32_e32 v64, v71, v72
	v_mul_f32_e32 v63, v63, v73
	v_add_co_u32_e32 v70, vcc, s12, v122
	v_cvt_pk_bf16_f32 v63, v64, v63
	s_nop 0
	v_addc_co_u32_e32 v71, vcc, 0, v123, vcc
	global_store_dwordx2 v[70:71], v[62:63], off
	ds_read2_b32 v[62:63], v138 offset0:64 offset1:80
	ds_read2_b32 v[64:65], v138 offset0:192 offset1:208
	s_waitcnt lgkmcnt(1)
	v_mov_b32_e32 v72, v62
	s_waitcnt lgkmcnt(0)
; __device__ __forceinline__ float bf2f(u16 b) { return __uint_as_float(((unsigned)b) << 16); }
; __device__ __forceinline__ void phase_spatial(const Params& p) {
;     ...
;       for (int mb = 0; mb < 2; ++mb)
; #pragma unroll
;         for (int nb = 0; nb < 8; ++nb) {
;           int i = nb * 16 + fr;
;           float bsi = p.sgu_b_s[g * 128 + i];
;           float s0i = s0[i], s1i = s1[i];
;           f32x4 a = acc[mb][nb];
;           float m0 = lg[mb].x * (a[0] - s1i) + lbv[mb].x * s0i + bsi;
;           float m1 = lg[mb].y * (a[1] - s1i) + lbv[mb].y * s0i + bsi;
;           float m2 = lg[mb].z * (a[2] - s1i) + lbv[mb].z * s0i + bsi;
;           float m3 = lg[mb].w * (a[3] - s1i) + lbv[mb].w * s0i + bsi;
;           uint2 u2 = uu[mb][nb];
;           float u0 = bf2f((u16)(u2.x & 0xffff)), u1 = bf2f((u16)(u2.x >> 16));
;           float u2f = bf2f((u16)(u2.y & 0xffff)), u3 = bf2f((u16)(u2.y >> 16));
;           *(uint2*)(ubase + (nb * 16 * 6144 + mb * 16) * 2 + (unsigned)((fr * 6144 + wid * 32 + fq * 4) * 2)) =
;               make_uint2(pack2(u0 * m0, u1 * m1), pack2(u2f * m2, u3 * m3));
	v_sub_f32_e32 v73, v58, v64
	v_pk_mul_f32 v[72:73], v[126:127], v[72:73]
	v_sub_f32_e32 v59, v59, v64
	v_add_f32_e32 v58, v72, v73
	v_sub_f32_e32 v55, v55, v65
	v_sub_f32_e32 v19, v19, v64
	v_sub_f32_e32 v15, v15, v65
	v_add_f32_e32 v72, v224, v58
	v_mov_b32_e32 v58, v62
	v_pk_mul_f32 v[58:59], v[42:43], v[58:59]
	s_nop 0
	v_add_f32_e32 v58, v58, v59
	v_add_f32_e32 v73, v224, v58
	v_sub_f32_e32 v59, v60, v64
	v_mov_b32_e32 v58, v62
	v_pk_mul_f32 v[58:59], v[128:129], v[58:59]
	s_nop 0
	v_add_f32_e32 v58, v58, v59
	v_add_f32_e32 v60, v224, v58
	v_sub_f32_e32 v59, v61, v64
	v_mov_b32_e32 v58, v62
	v_pk_mul_f32 v[58:59], v[44:45], v[58:59]
	v_and_b32_e32 v61, 0xffff0000, v120
	v_add_f32_e32 v58, v58, v59
	v_add_f32_e32 v59, v224, v58
	v_lshlrev_b32_e32 v76, 16, v121
	v_lshlrev_b32_e32 v58, 16, v120
	v_mul_f32_e32 v60, v60, v76
	v_mul_f32_e32 v59, v59, v77
	v_mul_f32_e32 v58, v72, v58
	v_mul_f32_e32 v61, v73, v61
	v_cvt_pk_bf16_f32 v59, v60, v59
	v_add_co_u32_e32 v60, vcc, s13, v122
	v_cvt_pk_bf16_f32 v58, v58, v61
	s_nop 0
	v_addc_co_u32_e32 v61, vcc, 0, v123, vcc
	global_store_dwordx2 v[60:61], v[58:59], off
	v_sub_f32_e32 v59, v54, v65
	v_mov_b32_e32 v58, v63
	v_pk_mul_f32 v[58:59], v[126:127], v[58:59]
	v_and_b32_e32 v73, 0xffff0000, v119
	v_add_f32_e32 v54, v58, v59
	v_add_f32_e32 v58, v225, v54
	v_mov_b32_e32 v54, v63
	v_pk_mul_f32 v[54:55], v[42:43], v[54:55]
	s_nop 0
	v_add_f32_e32 v54, v54, v55
	v_add_f32_e32 v59, v225, v54
	v_sub_f32_e32 v55, v56, v65
	v_mov_b32_e32 v54, v63
	v_pk_mul_f32 v[54:55], v[128:129], v[54:55]
	s_nop 0
	v_add_f32_e32 v54, v54, v55
	v_add_f32_e32 v56, v225, v54
	v_sub_f32_e32 v55, v57, v65
	v_mov_b32_e32 v54, v63
	v_pk_mul_f32 v[54:55], v[44:45], v[54:55]
	v_and_b32_e32 v57, 0xffff0000, v118
	v_add_f32_e32 v54, v54, v55
	v_add_f32_e32 v55, v225, v54
	v_lshlrev_b32_e32 v54, 16, v118
	v_lshlrev_b32_e32 v72, 16, v119
	v_mul_f32_e32 v54, v58, v54
	v_mul_f32_e32 v57, v59, v57
	v_mul_f32_e32 v56, v56, v72
	v_mul_f32_e32 v55, v55, v73
	v_add_co_u32_e32 v58, vcc, s14, v122
	v_cvt_pk_bf16_f32 v54, v54, v57
	v_cvt_pk_bf16_f32 v55, v56, v55
	v_addc_co_u32_e32 v59, vcc, 0, v123, vcc
	global_store_dwordx2 v[58:59], v[54:55], off
	ds_read2_b32 v[54:55], v138 offset0:96 offset1:112
	ds_read2_b32 v[56:57], v138 offset0:224 offset1:240
	s_waitcnt lgkmcnt(1)
	v_mov_b32_e32 v72, v54
	s_waitcnt lgkmcnt(0)
	v_sub_f32_e32 v73, v50, v56
	v_pk_mul_f32 v[72:73], v[126:127], v[72:73]
	v_sub_f32_e32 v51, v51, v56
	v_add_f32_e32 v50, v72, v73
	v_sub_f32_e32 v47, v47, v57
	v_sub_f32_e32 v11, v11, v56
	v_sub_f32_e32 v7, v7, v57
	v_add_f32_e32 v72, v226, v50
	v_mov_b32_e32 v50, v54
	v_pk_mul_f32 v[50:51], v[42:43], v[50:51]
	s_nop 0
	v_add_f32_e32 v50, v50, v51
	v_add_f32_e32 v73, v226, v50
	v_sub_f32_e32 v51, v52, v56
	v_mov_b32_e32 v50, v54
	v_pk_mul_f32 v[50:51], v[128:129], v[50:51]
	v_and_b32_e32 v52, 0xffff0000, v116
	v_add_f32_e32 v50, v50, v51
	v_add_f32_e32 v77, v226, v50
	v_sub_f32_e32 v51, v53, v56
	v_mov_b32_e32 v50, v54
	v_pk_mul_f32 v[50:51], v[44:45], v[50:51]
	v_lshlrev_b32_e32 v53, 16, v117
	v_add_f32_e32 v50, v50, v51
	v_lshlrev_b32_e32 v51, 16, v116
	v_add_f32_e32 v50, v226, v50
	v_and_b32_e32 v76, 0xffff0000, v117
	v_mul_f32_e32 v51, v72, v51
	v_mul_f32_e32 v52, v73, v52
	v_cvt_pk_bf16_f32 v52, v51, v52
	v_mul_f32_e32 v51, v77, v53
	v_mul_f32_e32 v50, v50, v76
	v_cvt_pk_bf16_f32 v53, v51, v50
	v_add_co_u32_e32 v50, vcc, s15, v122
	s_nop 1
	v_addc_co_u32_e32 v51, vcc, 0, v123, vcc
	global_store_dwordx2 v[50:51], v[52:53], off
	v_sub_f32_e32 v53, v46, v57
	v_mov_b32_e32 v52, v55
	v_pk_mul_f32 v[52:53], v[126:127], v[52:53]
	s_nop 0
	v_add_f32_e32 v46, v52, v53
	v_add_f32_e32 v52, v227, v46
	v_mov_b32_e32 v46, v55
	v_pk_mul_f32 v[42:43], v[42:43], v[46:47]
	s_nop 0
	v_add_f32_e32 v42, v42, v43
	v_add_f32_e32 v46, v227, v42
	v_sub_f32_e32 v43, v48, v57
	v_mov_b32_e32 v42, v55
	v_pk_mul_f32 v[42:43], v[128:129], v[42:43]
	v_and_b32_e32 v48, 0xffff0000, v115
	v_add_f32_e32 v42, v42, v43
	v_add_f32_e32 v47, v227, v42
	v_sub_f32_e32 v43, v49, v57
	v_mov_b32_e32 v42, v55
	v_pk_mul_f32 v[42:43], v[44:45], v[42:43]
	v_and_b32_e32 v44, 0xffff0000, v114
	v_add_f32_e32 v42, v42, v43
	v_lshlrev_b32_e32 v43, 16, v114
	v_add_f32_e32 v42, v227, v42
	v_lshlrev_b32_e32 v45, 16, v115
	v_mul_f32_e32 v43, v52, v43
	v_mul_f32_e32 v44, v46, v44
	v_cvt_pk_bf16_f32 v44, v43, v44
	v_mul_f32_e32 v43, v47, v45
	v_mul_f32_e32 v42, v42, v48
	v_cvt_pk_bf16_f32 v45, v43, v42
	v_add_co_u32_e32 v42, vcc, s16, v122
	v_sub_f32_e32 v47, v38, v112
	s_nop 0
	v_addc_co_u32_e32 v43, vcc, 0, v123, vcc
	global_store_dwordx2 v[42:43], v[44:45], off
	v_mov_b32_e32 v44, v26
	v_mov_b32_e32 v45, v2
	v_mov_b32_e32 v46, v110
	v_pk_mul_f32 v[46:47], v[44:45], v[46:47]
	v_mov_b32_e32 v38, v110
	v_add_f32_e32 v2, v46, v47
	v_add_f32_e32 v46, v2, v228
	v_mov_b32_e32 v2, v27
	v_pk_mul_f32 v[26:27], v[2:3], v[38:39]
	v_sub_f32_e32 v39, v40, v112
	v_add_f32_e32 v26, v26, v27
	v_add_f32_e32 v47, v26, v228
	v_mov_b32_e32 v26, v28
	v_mov_b32_e32 v27, v4
	v_pk_mul_f32 v[38:39], v[26:27], v[38:39]
	s_nop 0
	v_add_f32_e32 v4, v38, v39
	v_add_f32_e32 v40, v4, v228
	v_sub_f32_e32 v39, v41, v112
	v_mov_b32_e32 v4, v29
	v_mov_b32_e32 v38, v110
	v_pk_mul_f32 v[28:29], v[4:5], v[38:39]
	v_and_b32_e32 v38, 0xffff0000, v108
	v_add_f32_e32 v28, v28, v29
	v_add_f32_e32 v29, v28, v228
	v_lshlrev_b32_e32 v28, 16, v108
	v_lshlrev_b32_e32 v39, 16, v109
	v_and_b32_e32 v41, 0xffff0000, v109
	v_mul_f32_e32 v28, v46, v28
	v_mul_f32_e32 v38, v47, v38
	v_cvt_pk_bf16_f32 v28, v28, v38
	v_mul_f32_e32 v38, v40, v39
	v_mul_f32_e32 v29, v29, v41
	v_cvt_pk_bf16_f32 v29, v38, v29
; __device__ __forceinline__ float bf2f(u16 b) { return __uint_as_float(((unsigned)b) << 16); }
; __device__ __forceinline__ void phase_spatial(const Params& p) {
;     ...
;     for (int csub = 0; csub < 3; ++csub) {
;     ...
;       for (int mb = 0; mb < 2; ++mb)
; #pragma unroll
;         for (int nb = 0; nb < 8; ++nb) {
;           int i = nb * 16 + fr;
;           float bsi = p.sgu_b_s[g * 128 + i];
;           float s0i = s0[i], s1i = s1[i];
;           f32x4 a = acc[mb][nb];
;           float m0 = lg[mb].x * (a[0] - s1i) + lbv[mb].x * s0i + bsi;
;           float m1 = lg[mb].y * (a[1] - s1i) + lbv[mb].y * s0i + bsi;
;           float m2 = lg[mb].z * (a[2] - s1i) + lbv[mb].z * s0i + bsi;
;           float m3 = lg[mb].w * (a[3] - s1i) + lbv[mb].w * s0i + bsi;
;           uint2 u2 = uu[mb][nb];
;           float u0 = bf2f((u16)(u2.x & 0xffff)), u1 = bf2f((u16)(u2.x >> 16));
;           float u2f = bf2f((u16)(u2.y & 0xffff)), u3 = bf2f((u16)(u2.y >> 16));
;           *(uint2*)(ubase + (nb * 16 * 6144 + mb * 16) * 2 + (unsigned)((fr * 6144 + wid * 32 + fq * 4) * 2)) =
;               make_uint2(pack2(u0 * m0, u1 * m1), pack2(u2f * m2, u3 * m3));
	global_store_dwordx2 v[82:83], v[28:29], off offset:32
	v_sub_f32_e32 v29, v34, v113
	v_mov_b32_e32 v28, v111
	v_pk_mul_f32 v[28:29], v[44:45], v[28:29]
	v_and_b32_e32 v39, 0xffff0000, v107
	v_add_f32_e32 v28, v28, v29
	v_sub_f32_e32 v29, v35, v113
	v_add_f32_e32 v34, v28, v229
	v_mov_b32_e32 v28, v111
	v_pk_mul_f32 v[28:29], v[2:3], v[28:29]
	s_nop 0
	v_add_f32_e32 v28, v28, v29
	v_add_f32_e32 v35, v28, v229
	v_sub_f32_e32 v29, v36, v113
	v_mov_b32_e32 v28, v111
	v_pk_mul_f32 v[28:29], v[26:27], v[28:29]
	s_nop 0
	v_add_f32_e32 v28, v28, v29
	v_add_f32_e32 v36, v28, v229
	v_sub_f32_e32 v29, v37, v113
	v_mov_b32_e32 v28, v111
	v_pk_mul_f32 v[28:29], v[4:5], v[28:29]
	v_and_b32_e32 v37, 0xffff0000, v106
	v_add_f32_e32 v28, v28, v29
	v_add_f32_e32 v29, v28, v229
	v_lshlrev_b32_e32 v28, 16, v106
	v_lshlrev_b32_e32 v38, 16, v107
	v_mul_f32_e32 v28, v34, v28
	v_mul_f32_e32 v34, v35, v37
	v_cvt_pk_bf16_f32 v28, v28, v34
	v_mul_f32_e32 v34, v36, v38
	v_mul_f32_e32 v29, v29, v39
	v_cvt_pk_bf16_f32 v29, v34, v29
	global_store_dwordx2 v[78:79], v[28:29], off offset:32
	v_sub_f32_e32 v29, v30, v68
	v_mov_b32_e32 v28, v66
	v_pk_mul_f32 v[28:29], v[44:45], v[28:29]
	v_and_b32_e32 v35, 0xffff0000, v105
	v_add_f32_e32 v28, v28, v29
	v_sub_f32_e32 v29, v31, v68
	v_add_f32_e32 v30, v28, v230
	v_mov_b32_e32 v28, v66
	v_pk_mul_f32 v[28:29], v[2:3], v[28:29]
	s_nop 0
	v_add_f32_e32 v28, v28, v29
	v_add_f32_e32 v31, v28, v230
	v_sub_f32_e32 v29, v32, v68
	v_mov_b32_e32 v28, v66
	v_pk_mul_f32 v[28:29], v[26:27], v[28:29]
	s_nop 0
	v_add_f32_e32 v28, v28, v29
	v_add_f32_e32 v32, v28, v230
	v_sub_f32_e32 v29, v33, v68
	v_mov_b32_e32 v28, v66
	v_pk_mul_f32 v[28:29], v[4:5], v[28:29]
	v_and_b32_e32 v33, 0xffff0000, v104
	v_add_f32_e32 v28, v28, v29
	v_add_f32_e32 v29, v28, v230
	v_lshlrev_b32_e32 v28, 16, v104
	v_lshlrev_b32_e32 v34, 16, v105
	v_mul_f32_e32 v28, v30, v28
	v_mul_f32_e32 v30, v31, v33
	v_cvt_pk_bf16_f32 v28, v28, v30
	v_mul_f32_e32 v30, v32, v34
	v_mul_f32_e32 v29, v29, v35
	v_cvt_pk_bf16_f32 v29, v30, v29
	global_store_dwordx2 v[74:75], v[28:29], off offset:32
	v_sub_f32_e32 v29, v22, v69
	v_mov_b32_e32 v28, v67
	v_pk_mul_f32 v[28:29], v[44:45], v[28:29]
	v_and_b32_e32 v31, 0xffff0000, v103
	v_add_f32_e32 v22, v28, v29
	v_add_f32_e32 v28, v22, v231
	v_mov_b32_e32 v22, v67
	v_pk_mul_f32 v[22:23], v[2:3], v[22:23]
	s_nop 0
	v_add_f32_e32 v22, v22, v23
	v_add_f32_e32 v29, v22, v231
	v_sub_f32_e32 v23, v24, v69
	v_mov_b32_e32 v22, v67
	v_pk_mul_f32 v[22:23], v[26:27], v[22:23]
	s_nop 0
	v_add_f32_e32 v22, v22, v23
	v_add_f32_e32 v24, v22, v231
	v_sub_f32_e32 v23, v25, v69
	v_mov_b32_e32 v22, v67
	v_pk_mul_f32 v[22:23], v[4:5], v[22:23]
	v_and_b32_e32 v25, 0xffff0000, v102
	v_add_f32_e32 v22, v22, v23
	v_add_f32_e32 v23, v22, v231
	v_lshlrev_b32_e32 v22, 16, v102
	v_lshlrev_b32_e32 v30, 16, v103
	v_mul_f32_e32 v22, v28, v22
	v_mul_f32_e32 v25, v29, v25
	v_mul_f32_e32 v24, v24, v30
	v_mul_f32_e32 v23, v23, v31
	v_cvt_pk_bf16_f32 v22, v22, v25
	v_cvt_pk_bf16_f32 v23, v24, v23
	global_store_dwordx2 v[70:71], v[22:23], off offset:32
	v_sub_f32_e32 v23, v18, v64
	v_mov_b32_e32 v22, v62
	v_pk_mul_f32 v[22:23], v[44:45], v[22:23]
	v_and_b32_e32 v25, 0xffff0000, v101
	v_add_f32_e32 v18, v22, v23
	v_add_f32_e32 v22, v18, v232
	v_mov_b32_e32 v18, v62
	v_pk_mul_f32 v[18:19], v[2:3], v[18:19]
	s_nop 0
	v_add_f32_e32 v18, v18, v19
	v_add_f32_e32 v23, v18, v232
	v_sub_f32_e32 v19, v20, v64
	v_mov_b32_e32 v18, v62
	v_pk_mul_f32 v[18:19], v[26:27], v[18:19]
	s_nop 0
	v_add_f32_e32 v18, v18, v19
	v_add_f32_e32 v20, v18, v232
	v_sub_f32_e32 v19, v21, v64
	v_mov_b32_e32 v18, v62
	v_pk_mul_f32 v[18:19], v[4:5], v[18:19]
	v_and_b32_e32 v21, 0xffff0000, v100
	v_add_f32_e32 v18, v18, v19
	v_add_f32_e32 v19, v18, v232
	v_lshlrev_b32_e32 v18, 16, v100
	v_lshlrev_b32_e32 v24, 16, v101
	v_mul_f32_e32 v18, v22, v18
	v_mul_f32_e32 v21, v23, v21
	v_mul_f32_e32 v20, v20, v24
	v_mul_f32_e32 v19, v19, v25
	v_cvt_pk_bf16_f32 v18, v18, v21
	v_cvt_pk_bf16_f32 v19, v20, v19
	global_store_dwordx2 v[60:61], v[18:19], off offset:32
	v_sub_f32_e32 v19, v14, v65
	v_mov_b32_e32 v18, v63
	v_pk_mul_f32 v[18:19], v[44:45], v[18:19]
	v_and_b32_e32 v21, 0xffff0000, v99
	v_add_f32_e32 v14, v18, v19
	v_add_f32_e32 v18, v14, v233
	v_mov_b32_e32 v14, v63
	v_pk_mul_f32 v[14:15], v[2:3], v[14:15]
	s_nop 0
	v_add_f32_e32 v14, v14, v15
	v_add_f32_e32 v19, v14, v233
	v_sub_f32_e32 v15, v16, v65
	v_mov_b32_e32 v14, v63
	v_pk_mul_f32 v[14:15], v[26:27], v[14:15]
	s_nop 0
	v_add_f32_e32 v14, v14, v15
	v_add_f32_e32 v16, v14, v233
	v_sub_f32_e32 v15, v17, v65
	v_mov_b32_e32 v14, v63
	v_pk_mul_f32 v[14:15], v[4:5], v[14:15]
	v_and_b32_e32 v17, 0xffff0000, v98
	v_add_f32_e32 v14, v14, v15
	v_add_f32_e32 v15, v14, v233
	v_lshlrev_b32_e32 v14, 16, v98
	v_lshlrev_b32_e32 v20, 16, v99
	v_mul_f32_e32 v14, v18, v14
	v_mul_f32_e32 v17, v19, v17
	v_mul_f32_e32 v16, v16, v20
	v_mul_f32_e32 v15, v15, v21
	v_cvt_pk_bf16_f32 v14, v14, v17
	v_cvt_pk_bf16_f32 v15, v16, v15
	global_store_dwordx2 v[58:59], v[14:15], off offset:32
	v_sub_f32_e32 v15, v10, v56
	v_mov_b32_e32 v14, v54
	v_pk_mul_f32 v[14:15], v[44:45], v[14:15]
	v_and_b32_e32 v17, 0xffff0000, v97
	v_add_f32_e32 v10, v14, v15
	v_add_f32_e32 v14, v10, v234
	v_mov_b32_e32 v10, v54
	v_pk_mul_f32 v[10:11], v[2:3], v[10:11]
	s_nop 0
	v_add_f32_e32 v10, v10, v11
	v_add_f32_e32 v15, v10, v234
	v_sub_f32_e32 v11, v12, v56
	v_mov_b32_e32 v10, v54
	v_pk_mul_f32 v[10:11], v[26:27], v[10:11]
	s_nop 0
	v_add_f32_e32 v10, v10, v11
	v_add_f32_e32 v12, v10, v234
	v_sub_f32_e32 v11, v13, v56
	v_mov_b32_e32 v10, v54
	v_pk_mul_f32 v[10:11], v[4:5], v[10:11]
	v_and_b32_e32 v13, 0xffff0000, v96
	v_add_f32_e32 v10, v10, v11
	v_add_f32_e32 v11, v10, v234
	v_lshlrev_b32_e32 v10, 16, v96
	v_lshlrev_b32_e32 v16, 16, v97
	v_mul_f32_e32 v10, v14, v10
	v_mul_f32_e32 v13, v15, v13
	v_mul_f32_e32 v12, v12, v16
	v_mul_f32_e32 v11, v11, v17
	v_cvt_pk_bf16_f32 v10, v10, v13
	v_cvt_pk_bf16_f32 v11, v12, v11
	global_store_dwordx2 v[50:51], v[10:11], off offset:32
	v_sub_f32_e32 v11, v6, v57
	v_mov_b32_e32 v10, v55
	v_pk_mul_f32 v[10:11], v[44:45], v[10:11]
	s_nop 0
	v_add_f32_e32 v6, v10, v11
	v_add_f32_e32 v10, v6, v235
	v_mov_b32_e32 v6, v55
	v_pk_mul_f32 v[2:3], v[2:3], v[6:7]
	s_nop 0
	v_add_f32_e32 v2, v2, v3
	v_add_f32_e32 v6, v2, v235
	v_sub_f32_e32 v3, v8, v57
	v_mov_b32_e32 v2, v55
	v_pk_mul_f32 v[2:3], v[26:27], v[2:3]
	v_and_b32_e32 v8, 0xffff0000, v95
	v_add_f32_e32 v2, v2, v3
	v_add_f32_e32 v7, v2, v235
	v_sub_f32_e32 v3, v9, v57
	v_mov_b32_e32 v2, v55
	v_pk_mul_f32 v[2:3], v[4:5], v[2:3]
	v_and_b32_e32 v4, 0xffff0000, v94
	v_add_f32_e32 v2, v2, v3
	v_add_f32_e32 v3, v2, v235
	v_lshlrev_b32_e32 v2, 16, v94
	v_lshlrev_b32_e32 v5, 16, v95
	v_mul_f32_e32 v2, v10, v2
	v_mul_f32_e32 v4, v6, v4
	v_cvt_pk_bf16_f32 v2, v2, v4
	v_mul_f32_e32 v4, v7, v5
	v_mul_f32_e32 v3, v3, v8
	v_cvt_pk_bf16_f32 v3, v4, v3
	global_store_dwordx2 v[42:43], v[2:3], off offset:32
	s_cbranch_scc0 .LBB0_232
; __device__ __forceinline__ void phase_spatial(const Params& p) {
;     ...
;   for (int item = blockIdx.x; item < 1024; item += gridDim.x) {
;     int tid = get_tid(p.wid), wid = tid >> 6, lane = tid & 63, fr = lane & 15, fq = lane >> 4;
;     int g = item & 7, chunk = item >> 3, t0 = chunk * 128;
;     ...
;     __syncthreads();
	v_readlane_b32 s2, v253, 30
	s_add_i32 s7, s7, s2
	s_add_i32 s6, s6, s2
	s_cmpk_gt_i32 s7, 0x3ff
	s_barrier
	s_cbranch_scc0 .LBB0_227
	s_branch .LBB0_235
